# de-serialised RESID GEMM epilogue (FFN_DOWN, SSD_OUT, DA_O, RK_O): 32 residual loads in flight, counted vmcnt, then stores; no per-row exec masks
# speedup vs baseline: 1.0505x; 1.0289x over previous
;     ...
;   const int lrow = tid >> 3, lkc = (tid & 7) * 8;
;   const bf16* Ag = jb.A + (size_t)max(m0 + lrow, 0) * jb.lda + lkc;
;   const bf16* Ag1 = jb.A + (ptrdiff_t)(m0 + lrow) * jb.lda + lkc;
;   const bf16* Bg = jb.Bt + (size_t)(n0 + lrow) * jb.K + lkc;
;   const size_t astep = (size_t)32 * jb.lda, bstep = (size_t)32 * jb.K;
;   if (kt1 < 0) kt1 = jb.K >> 6;
;   const int nk = kt1 - kt0;
;   Ag += (size_t)kt0 * 64; Ag1 += (size_t)kt0 * 64; Bg += (size_t)kt0 * 64;
;   u32x4 ra0[4], rb0[4], ra1[4], rb1[4];
;     ...
;   bf16* As1 = As + 2 * 128 * 72;
;   bf16* Bs1 = As1 + 128 * 72;
;   G_LOAD(ra0, rb0, 0);
;   if (nk > 1) G_LOAD(ra1, rb1, 1);
;   G_STORE(ra0, rb0, As, Bs);
;   __syncthreads();
;   for (int kt = 0; kt < nk; kt += 2) {
;     if (kt + 2 < nk) G_LOAD(ra0, rb0, kt + 2);
;     if (kt + 1 < nk) G_STORE(ra1, rb1, As1, Bs1);
;     G_COMPUTE(As, Bs);
;     __syncthreads();
;     if (kt + 1 < nk) {
;       if (kt + 3 < nk) G_LOAD(ra1, rb1, kt + 3);
;       if (kt + 2 < nk) G_STORE(ra0, rb0, As, Bs);
;       G_COMPUTE(As1, Bs1);
;       __syncthreads();
;     }
;   }
.LBB0_20:
	s_ashr_i32 s2, s4, 31
	s_lshr_b32 s2, s2, 25
	s_add_i32 s2, s4, s2
	s_and_b32 s3, s2, 0xffffff80
	s_sub_i32 s3, s4, s3
	s_ashr_i32 s5, s3, 31
	s_lshr_b32 s5, s5, 28
	s_add_i32 s5, s3, s5
	s_and_b32 s14, s5, 0x1fffff0
	s_sub_i32 s3, s3, s14
	s_lshl_b32 s2, s2, 4
	s_and_b32 s2, s2, 0xfffff800
	s_lshl_b32 s3, s3, 7
	v_mov_b32_e32 v84, v208
	s_add_i32 s3, s3, s2
	s_lshl_b32 s2, s5, 3
	v_ashrrev_i32_e32 v82, 3, v84
	v_add_u32_e32 v0, s3, v82
	v_max_i32_e32 v96, 0, v0
	v_lshlrev_b32_e32 v1, 4, v84
	v_lshlrev_b64 v[2:3], 11, v[96:97]
	v_and_b32_e32 v96, 0x70, v1
	v_ashrrev_i32_e32 v1, 31, v0
	v_lshlrev_b64 v[0:1], 11, v[0:1]
	s_and_b32 s2, s2, 0xffffff80
	v_lshl_add_u64 v[0:1], s[8:9], 0, v[0:1]
	v_lshl_add_u64 v[28:29], v[0:1], 0, v[96:97]
	v_add_u32_e32 v0, s2, v82
	v_ashrrev_i32_e32 v1, 31, v0
	v_lshlrev_b64 v[0:1], 11, v[0:1]
	v_lshl_add_u64 v[0:1], s[12:13], 0, v[0:1]
	v_add_co_u32_e32 v70, vcc, s63, v28
	v_lshl_add_u64 v[68:69], v[0:1], 0, v[96:97]
	s_nop 0
	v_addc_co_u32_e32 v71, vcc, 0, v29, vcc
	v_add_co_u32_e32 v72, vcc, s63, v68
	v_lshl_add_u64 v[2:3], s[8:9], 0, v[2:3]
	s_nop 0
	v_addc_co_u32_e32 v73, vcc, 0, v69, vcc
	v_add_co_u32_e32 v74, vcc, s64, v28
	v_lshl_add_u64 v[66:67], v[2:3], 0, v[96:97]
	s_nop 0
	v_addc_co_u32_e32 v75, vcc, 0, v29, vcc
	v_add_co_u32_e32 v76, vcc, s64, v68
	global_load_dwordx4 v[0:3], v[66:67], off
	global_load_dwordx4 v[4:7], v[68:69], off
	v_addc_co_u32_e32 v77, vcc, 0, v69, vcc
	v_add_co_u32_e32 v78, vcc, s65, v68
	global_load_dwordx4 v[8:11], v[70:71], off
	s_nop 0
	v_addc_co_u32_e32 v79, vcc, 0, v69, vcc
	v_add_co_u32_e32 v80, vcc, s65, v28
	global_load_dwordx4 v[12:15], v[72:73], off
	s_nop 0
	v_addc_co_u32_e32 v81, vcc, 0, v29, vcc
	global_load_dwordx4 v[16:19], v[74:75], off
	global_load_dwordx4 v[20:23], v[76:77], off
	global_load_dwordx4 v[24:27], v[78:79], off
	global_load_dwordx4 v[28:31], v[80:81], off
	global_load_dwordx4 v[32:35], v[66:67], off offset:128
	global_load_dwordx4 v[36:39], v[68:69], off offset:128
	global_load_dwordx4 v[40:43], v[70:71], off offset:128
	global_load_dwordx4 v[44:47], v[72:73], off offset:128
	global_load_dwordx4 v[48:51], v[74:75], off offset:128
	global_load_dwordx4 v[52:55], v[76:77], off offset:128
	global_load_dwordx4 v[56:59], v[80:81], off offset:128
	global_load_dwordx4 v[60:63], v[78:79], off offset:128
	v_ashrrev_i32_e32 v64, 1, v84
	v_lshrrev_b32_e32 v65, 1, v84
	v_and_b32_e32 v85, 0xffffffc0, v64
	v_and_b32_e32 v88, 16, v65
	v_and_or_b32 v64, v84, 31, v85
	v_mad_u64_u32 v[82:83], s[14:15], v82, s91, v[96:97]
	v_mad_u64_u32 v[64:65], s[14:15], v64, s91, v[88:89]
	v_add_u32_e32 v86, 0xd800, v82
	v_and_b32_e32 v65, 0x5f, v84
	v_mad_u32_u24 v83, v65, s91, v88
	s_mov_b32 s14, 23
	s_waitcnt vmcnt(14)
	ds_write_b128 v82, v[4:7] offset:18432
	ds_write_b128 v82, v[0:3]
	s_waitcnt vmcnt(12)
	ds_write_b128 v82, v[12:15] offset:23040
	s_waitcnt vmcnt(10)
	ds_write_b128 v82, v[20:23] offset:27648
	s_waitcnt vmcnt(9)
	ds_write_b128 v82, v[24:27] offset:32256
	ds_write_b128 v82, v[8:11] offset:4608
	ds_write_b128 v82, v[16:19] offset:9216
	s_waitcnt vmcnt(8)
	ds_write_b128 v82, v[28:31] offset:13824
	s_waitcnt lgkmcnt(0)
	s_barrier
	s_waitcnt vmcnt(7)
	ds_write_b128 v82, v[32:35] offset:36864
	s_waitcnt vmcnt(6)
	ds_write_b128 v82, v[36:39] offset:55296
	s_waitcnt vmcnt(5)
	ds_write_b128 v82, v[40:43] offset:41472
	s_waitcnt vmcnt(4)
	ds_write_b128 v82, v[44:47] offset:59904
	s_waitcnt vmcnt(3)
	ds_write_b128 v82, v[48:51] offset:46080
	s_waitcnt vmcnt(2)
	ds_write_b128 v82, v[52:55] offset:64512
	s_waitcnt vmcnt(1)
	ds_write_b128 v82, v[56:59] offset:50688
	s_waitcnt vmcnt(0)
	ds_write_b128 v86, v[60:63] offset:13824
	ds_read_b128 v[0:3], v64
	ds_read_b128 v[4:7], v83 offset:18432
	ds_read_b128 v[88:91], v64 offset:32
	ds_read_b128 v[92:95], v83 offset:18464
	ds_read_b128 v[8:11], v83 offset:23040
	ds_read_b128 v[98:101], v83 offset:23072
	global_load_dwordx4 v[138:141], v[66:67], off offset:256
	global_load_dwordx4 v[142:145], v[68:69], off offset:256
	global_load_dwordx4 v[146:149], v[70:71], off offset:256
	global_load_dwordx4 v[150:153], v[72:73], off offset:256
	global_load_dwordx4 v[154:157], v[74:75], off offset:256
	global_load_dwordx4 v[158:161], v[76:77], off offset:256
	global_load_dwordx4 v[162:165], v[80:81], off offset:256
	global_load_dwordx4 v[166:169], v[78:79], off offset:256
	s_waitcnt lgkmcnt(4)
	v_mfma_f32_32x32x16_bf16 v[48:63], v[0:3], v[4:7], 0
	s_waitcnt lgkmcnt(1)
	v_mfma_f32_32x32x16_bf16 v[32:47], v[0:3], v[8:11], 0
	ds_read_b128 v[0:3], v64 offset:4608
	ds_read_b128 v[102:105], v64 offset:4640
	s_waitcnt lgkmcnt(1)
	v_mfma_f32_32x32x16_bf16 v[16:31], v[0:3], v[4:7], 0
	v_mfma_f32_32x32x16_bf16 v[0:15], v[0:3], v[8:11], 0
	v_mfma_f32_32x32x16_bf16 v[48:63], v[88:91], v[92:95], v[48:63]
	v_mfma_f32_32x32x16_bf16 v[32:47], v[88:91], v[98:101], v[32:47]
	s_waitcnt lgkmcnt(0)
	v_mfma_f32_32x32x16_bf16 v[16:31], v[102:105], v[92:95], v[16:31]
	v_mfma_f32_32x32x16_bf16 v[0:15], v[102:105], v[98:101], v[0:15]
	ds_read_b128 v[88:91], v64 offset:64
	ds_read_b128 v[92:95], v83 offset:18496
	ds_read_b128 v[98:101], v64 offset:96
	ds_read_b128 v[102:105], v83 offset:18528
	ds_read_b128 v[106:109], v83 offset:23104
	ds_read_b128 v[110:113], v83 offset:23136
	s_waitcnt lgkmcnt(4)
	v_mfma_f32_32x32x16_bf16 v[48:63], v[88:91], v[92:95], v[48:63]
	s_waitcnt lgkmcnt(1)
	v_mfma_f32_32x32x16_bf16 v[32:47], v[88:91], v[106:109], v[32:47]
	ds_read_b128 v[88:91], v64 offset:4672
	ds_read_b128 v[114:117], v64 offset:4704
	s_waitcnt lgkmcnt(1)
	v_mfma_f32_32x32x16_bf16 v[16:31], v[88:91], v[92:95], v[16:31]
	v_mfma_f32_32x32x16_bf16 v[0:15], v[88:91], v[106:109], v[0:15]
	v_mfma_f32_32x32x16_bf16 v[48:63], v[98:101], v[102:105], v[48:63]
	v_mfma_f32_32x32x16_bf16 v[32:47], v[98:101], v[110:113], v[32:47]
	s_waitcnt lgkmcnt(0)
	v_mfma_f32_32x32x16_bf16 v[16:31], v[114:117], v[102:105], v[16:31]
	s_barrier
;     ...
;   for (int kt = 0; kt < nk; kt += 2) {
;     if (kt + 2 < nk) G_LOAD(ra0, rb0, kt + 2);
;     if (kt + 1 < nk) G_STORE(ra1, rb1, As1, Bs1);
;     G_COMPUTE(As, Bs);
;     __syncthreads();
;     if (kt + 1 < nk) {
;       if (kt + 3 < nk) G_LOAD(ra1, rb1, kt + 3);
;       if (kt + 2 < nk) G_STORE(ra0, rb0, As, Bs);
;       G_COMPUTE(As1, Bs1);
;       __syncthreads();
;     }
;   }
	s_waitcnt vmcnt(7)
	ds_write_b128 v82, v[138:141]
	s_waitcnt vmcnt(6)
	ds_write_b128 v82, v[142:145] offset:18432
	s_waitcnt vmcnt(5)
	ds_write_b128 v82, v[146:149] offset:4608
	s_waitcnt vmcnt(4)
	ds_write_b128 v82, v[150:153] offset:23040
	s_waitcnt vmcnt(3)
	ds_write_b128 v82, v[154:157] offset:9216
	s_waitcnt vmcnt(2)
	ds_write_b128 v82, v[158:161] offset:27648
	s_waitcnt vmcnt(1)
	ds_write_b128 v82, v[162:165] offset:13824
	s_waitcnt vmcnt(0)
	ds_write_b128 v82, v[166:169] offset:32256
	v_mfma_f32_32x32x16_bf16 v[0:15], v[114:117], v[110:113], v[0:15]
	ds_read_b128 v[88:91], v64 offset:36864
	ds_read_b128 v[92:95], v83 offset:55296
	ds_read_b128 v[98:101], v64 offset:36896
	ds_read_b128 v[102:105], v83 offset:55328
	ds_read_b128 v[106:109], v83 offset:59904
	ds_read_b128 v[110:113], v83 offset:59936
	global_load_dwordx4 v[138:141], v[66:67], off offset:384
	global_load_dwordx4 v[142:145], v[68:69], off offset:384
	global_load_dwordx4 v[146:149], v[70:71], off offset:384
	global_load_dwordx4 v[150:153], v[72:73], off offset:384
	global_load_dwordx4 v[154:157], v[74:75], off offset:384
	global_load_dwordx4 v[158:161], v[76:77], off offset:384
	global_load_dwordx4 v[162:165], v[80:81], off offset:384
	global_load_dwordx4 v[166:169], v[78:79], off offset:384
	s_waitcnt lgkmcnt(4)
	v_mfma_f32_32x32x16_bf16 v[48:63], v[88:91], v[92:95], v[48:63]
	s_waitcnt lgkmcnt(1)
	v_mfma_f32_32x32x16_bf16 v[32:47], v[88:91], v[106:109], v[32:47]
	ds_read_b128 v[88:91], v64 offset:41472
	ds_read_b128 v[114:117], v64 offset:41504
	s_waitcnt lgkmcnt(1)
	v_mfma_f32_32x32x16_bf16 v[16:31], v[88:91], v[92:95], v[16:31]
	v_mfma_f32_32x32x16_bf16 v[0:15], v[88:91], v[106:109], v[0:15]
	v_mfma_f32_32x32x16_bf16 v[48:63], v[98:101], v[102:105], v[48:63]
	v_mfma_f32_32x32x16_bf16 v[32:47], v[98:101], v[110:113], v[32:47]
	s_waitcnt lgkmcnt(0)
	v_mfma_f32_32x32x16_bf16 v[16:31], v[114:117], v[102:105], v[16:31]
	ds_read_b128 v[88:91], v64 offset:36928
	ds_read_b128 v[92:95], v83 offset:55360
	ds_read_b128 v[98:101], v64 offset:36960
	ds_read_b128 v[102:105], v83 offset:55392
	v_mfma_f32_32x32x16_bf16 v[0:15], v[114:117], v[110:113], v[0:15]
	ds_read_b128 v[106:109], v83 offset:59968
	ds_read_b128 v[110:113], v83 offset:60000
	s_waitcnt lgkmcnt(4)
	v_mfma_f32_32x32x16_bf16 v[48:63], v[88:91], v[92:95], v[48:63]
	s_waitcnt lgkmcnt(1)
	v_mfma_f32_32x32x16_bf16 v[32:47], v[88:91], v[106:109], v[32:47]
	ds_read_b128 v[88:91], v64 offset:41536
	ds_read_b128 v[114:117], v64 offset:41568
	s_waitcnt lgkmcnt(1)
	v_mfma_f32_32x32x16_bf16 v[16:31], v[88:91], v[92:95], v[16:31]
	v_mfma_f32_32x32x16_bf16 v[0:15], v[88:91], v[106:109], v[0:15]
	v_mfma_f32_32x32x16_bf16 v[48:63], v[98:101], v[102:105], v[48:63]
	v_mfma_f32_32x32x16_bf16 v[32:47], v[98:101], v[110:113], v[32:47]
	s_waitcnt lgkmcnt(0)
	v_mfma_f32_32x32x16_bf16 v[16:31], v[114:117], v[102:105], v[16:31]
	s_barrier
	s_waitcnt vmcnt(7)
	ds_write_b128 v82, v[138:141] offset:36864
	s_waitcnt vmcnt(6)
	ds_write_b128 v82, v[142:145] offset:55296
	s_waitcnt vmcnt(5)
	ds_write_b128 v82, v[146:149] offset:41472
	s_waitcnt vmcnt(4)
	ds_write_b128 v82, v[150:153] offset:59904
	s_waitcnt vmcnt(3)
	ds_write_b128 v82, v[154:157] offset:46080
	s_waitcnt vmcnt(2)
	ds_write_b128 v82, v[158:161] offset:64512
	s_waitcnt vmcnt(1)
	ds_write_b128 v82, v[162:165] offset:50688
	s_waitcnt vmcnt(0)
	ds_write_b128 v86, v[166:169] offset:13824
	v_mfma_f32_32x32x16_bf16 v[0:15], v[114:117], v[110:113], v[0:15]
	ds_read_b128 v[88:91], v64
	ds_read_b128 v[92:95], v83 offset:18432
	ds_read_b128 v[98:101], v64 offset:32
	ds_read_b128 v[102:105], v83 offset:18464
	ds_read_b128 v[106:109], v83 offset:23040
	ds_read_b128 v[110:113], v83 offset:23072
	global_load_dwordx4 v[138:141], v[66:67], off offset:512
	global_load_dwordx4 v[142:145], v[68:69], off offset:512
	global_load_dwordx4 v[146:149], v[70:71], off offset:512
	global_load_dwordx4 v[150:153], v[72:73], off offset:512
	global_load_dwordx4 v[154:157], v[74:75], off offset:512
	global_load_dwordx4 v[158:161], v[76:77], off offset:512
	global_load_dwordx4 v[162:165], v[80:81], off offset:512
	global_load_dwordx4 v[166:169], v[78:79], off offset:512
	s_waitcnt lgkmcnt(4)
	v_mfma_f32_32x32x16_bf16 v[48:63], v[88:91], v[92:95], v[48:63]
	s_waitcnt lgkmcnt(1)
	v_mfma_f32_32x32x16_bf16 v[32:47], v[88:91], v[106:109], v[32:47]
	ds_read_b128 v[88:91], v64 offset:4608
	ds_read_b128 v[114:117], v64 offset:4640
	s_waitcnt lgkmcnt(1)
	v_mfma_f32_32x32x16_bf16 v[16:31], v[88:91], v[92:95], v[16:31]
	v_mfma_f32_32x32x16_bf16 v[0:15], v[88:91], v[106:109], v[0:15]
	v_mfma_f32_32x32x16_bf16 v[48:63], v[98:101], v[102:105], v[48:63]
	v_mfma_f32_32x32x16_bf16 v[32:47], v[98:101], v[110:113], v[32:47]
	s_waitcnt lgkmcnt(0)
	v_mfma_f32_32x32x16_bf16 v[16:31], v[114:117], v[102:105], v[16:31]
	ds_read_b128 v[88:91], v64 offset:64
	ds_read_b128 v[92:95], v83 offset:18496
	ds_read_b128 v[98:101], v64 offset:96
	ds_read_b128 v[102:105], v83 offset:18528
	v_mfma_f32_32x32x16_bf16 v[0:15], v[114:117], v[110:113], v[0:15]
	ds_read_b128 v[106:109], v83 offset:23104
	ds_read_b128 v[110:113], v83 offset:23136
	s_waitcnt lgkmcnt(4)
	v_mfma_f32_32x32x16_bf16 v[48:63], v[88:91], v[92:95], v[48:63]
	s_waitcnt lgkmcnt(1)
	v_mfma_f32_32x32x16_bf16 v[32:47], v[88:91], v[106:109], v[32:47]
	ds_read_b128 v[88:91], v64 offset:4672
	ds_read_b128 v[114:117], v64 offset:4704
	s_waitcnt lgkmcnt(1)
	v_mfma_f32_32x32x16_bf16 v[16:31], v[88:91], v[92:95], v[16:31]
	v_mfma_f32_32x32x16_bf16 v[0:15], v[88:91], v[106:109], v[0:15]
	v_mfma_f32_32x32x16_bf16 v[48:63], v[98:101], v[102:105], v[48:63]
	v_mfma_f32_32x32x16_bf16 v[32:47], v[98:101], v[110:113], v[32:47]
	s_waitcnt lgkmcnt(0)
	v_mfma_f32_32x32x16_bf16 v[16:31], v[114:117], v[102:105], v[16:31]
	s_barrier
;     ...
;   for (int kt = 0; kt < nk; kt += 2) {
;     if (kt + 2 < nk) G_LOAD(ra0, rb0, kt + 2);
;     if (kt + 1 < nk) G_STORE(ra1, rb1, As1, Bs1);
;     G_COMPUTE(As, Bs);
;     __syncthreads();
;     if (kt + 1 < nk) {
;       if (kt + 3 < nk) G_LOAD(ra1, rb1, kt + 3);
;       if (kt + 2 < nk) G_STORE(ra0, rb0, As, Bs);
;       G_COMPUTE(As1, Bs1);
;       __syncthreads();
;     }
;   }
	s_waitcnt vmcnt(7)
	ds_write_b128 v82, v[138:141]
	s_waitcnt vmcnt(6)
	ds_write_b128 v82, v[142:145] offset:18432
	s_waitcnt vmcnt(5)
	ds_write_b128 v82, v[146:149] offset:4608
	s_waitcnt vmcnt(4)
	ds_write_b128 v82, v[150:153] offset:23040
	s_waitcnt vmcnt(3)
	ds_write_b128 v82, v[154:157] offset:9216
	s_waitcnt vmcnt(2)
	ds_write_b128 v82, v[158:161] offset:27648
	s_waitcnt vmcnt(1)
	ds_write_b128 v82, v[162:165] offset:13824
	s_waitcnt vmcnt(0)
	ds_write_b128 v82, v[166:169] offset:32256
	v_mfma_f32_32x32x16_bf16 v[0:15], v[114:117], v[110:113], v[0:15]
	ds_read_b128 v[88:91], v64 offset:36864
	ds_read_b128 v[92:95], v83 offset:55296
	ds_read_b128 v[98:101], v64 offset:36896
	ds_read_b128 v[102:105], v83 offset:55328
	ds_read_b128 v[106:109], v83 offset:59904
	ds_read_b128 v[110:113], v83 offset:59936
	global_load_dwordx4 v[138:141], v[66:67], off offset:640
	global_load_dwordx4 v[142:145], v[68:69], off offset:640
	global_load_dwordx4 v[146:149], v[70:71], off offset:640
	global_load_dwordx4 v[150:153], v[72:73], off offset:640
	global_load_dwordx4 v[154:157], v[74:75], off offset:640
	global_load_dwordx4 v[158:161], v[76:77], off offset:640
	global_load_dwordx4 v[162:165], v[80:81], off offset:640
	global_load_dwordx4 v[166:169], v[78:79], off offset:640
	s_waitcnt lgkmcnt(4)
	v_mfma_f32_32x32x16_bf16 v[48:63], v[88:91], v[92:95], v[48:63]
	s_waitcnt lgkmcnt(1)
	v_mfma_f32_32x32x16_bf16 v[32:47], v[88:91], v[106:109], v[32:47]
	ds_read_b128 v[88:91], v64 offset:41472
	ds_read_b128 v[114:117], v64 offset:41504
	s_waitcnt lgkmcnt(1)
	v_mfma_f32_32x32x16_bf16 v[16:31], v[88:91], v[92:95], v[16:31]
	v_mfma_f32_32x32x16_bf16 v[0:15], v[88:91], v[106:109], v[0:15]
	v_mfma_f32_32x32x16_bf16 v[48:63], v[98:101], v[102:105], v[48:63]
	v_mfma_f32_32x32x16_bf16 v[32:47], v[98:101], v[110:113], v[32:47]
	s_waitcnt lgkmcnt(0)
	v_mfma_f32_32x32x16_bf16 v[16:31], v[114:117], v[102:105], v[16:31]
	ds_read_b128 v[88:91], v64 offset:36928
	ds_read_b128 v[92:95], v83 offset:55360
	ds_read_b128 v[98:101], v64 offset:36960
	ds_read_b128 v[102:105], v83 offset:55392
	v_mfma_f32_32x32x16_bf16 v[0:15], v[114:117], v[110:113], v[0:15]
	ds_read_b128 v[106:109], v83 offset:59968
	ds_read_b128 v[110:113], v83 offset:60000
	s_waitcnt lgkmcnt(4)
	v_mfma_f32_32x32x16_bf16 v[48:63], v[88:91], v[92:95], v[48:63]
	s_waitcnt lgkmcnt(1)
	v_mfma_f32_32x32x16_bf16 v[32:47], v[88:91], v[106:109], v[32:47]
	ds_read_b128 v[88:91], v64 offset:41536
	ds_read_b128 v[114:117], v64 offset:41568
	s_waitcnt lgkmcnt(1)
	v_mfma_f32_32x32x16_bf16 v[16:31], v[88:91], v[92:95], v[16:31]
	v_mfma_f32_32x32x16_bf16 v[0:15], v[88:91], v[106:109], v[0:15]
	v_mfma_f32_32x32x16_bf16 v[48:63], v[98:101], v[102:105], v[48:63]
	v_mfma_f32_32x32x16_bf16 v[32:47], v[98:101], v[110:113], v[32:47]
	s_waitcnt lgkmcnt(0)
	v_mfma_f32_32x32x16_bf16 v[16:31], v[114:117], v[102:105], v[16:31]
	s_barrier
	s_waitcnt vmcnt(7)
	ds_write_b128 v82, v[138:141] offset:36864
	s_waitcnt vmcnt(6)
	ds_write_b128 v82, v[142:145] offset:55296
	s_waitcnt vmcnt(5)
	ds_write_b128 v82, v[146:149] offset:41472
	s_waitcnt vmcnt(4)
	ds_write_b128 v82, v[150:153] offset:59904
	s_waitcnt vmcnt(3)
	ds_write_b128 v82, v[154:157] offset:46080
	s_waitcnt vmcnt(2)
	ds_write_b128 v82, v[158:161] offset:64512
	s_waitcnt vmcnt(1)
	ds_write_b128 v82, v[162:165] offset:50688
	s_waitcnt vmcnt(0)
	ds_write_b128 v86, v[166:169] offset:13824
	v_mfma_f32_32x32x16_bf16 v[0:15], v[114:117], v[110:113], v[0:15]
	ds_read_b128 v[88:91], v64
	ds_read_b128 v[92:95], v83 offset:18432
	ds_read_b128 v[98:101], v64 offset:32
	ds_read_b128 v[102:105], v83 offset:18464
	ds_read_b128 v[106:109], v83 offset:23040
	ds_read_b128 v[110:113], v83 offset:23072
	global_load_dwordx4 v[138:141], v[66:67], off offset:768
	global_load_dwordx4 v[142:145], v[68:69], off offset:768
	global_load_dwordx4 v[146:149], v[70:71], off offset:768
	global_load_dwordx4 v[150:153], v[72:73], off offset:768
	global_load_dwordx4 v[154:157], v[74:75], off offset:768
	global_load_dwordx4 v[158:161], v[76:77], off offset:768
	global_load_dwordx4 v[162:165], v[80:81], off offset:768
	global_load_dwordx4 v[166:169], v[78:79], off offset:768
	s_waitcnt lgkmcnt(4)
	v_mfma_f32_32x32x16_bf16 v[48:63], v[88:91], v[92:95], v[48:63]
	s_waitcnt lgkmcnt(1)
	v_mfma_f32_32x32x16_bf16 v[32:47], v[88:91], v[106:109], v[32:47]
	ds_read_b128 v[88:91], v64 offset:4608
	ds_read_b128 v[114:117], v64 offset:4640
	s_waitcnt lgkmcnt(1)
	v_mfma_f32_32x32x16_bf16 v[16:31], v[88:91], v[92:95], v[16:31]
	v_mfma_f32_32x32x16_bf16 v[0:15], v[88:91], v[106:109], v[0:15]
	v_mfma_f32_32x32x16_bf16 v[48:63], v[98:101], v[102:105], v[48:63]
	v_mfma_f32_32x32x16_bf16 v[32:47], v[98:101], v[110:113], v[32:47]
	s_waitcnt lgkmcnt(0)
	v_mfma_f32_32x32x16_bf16 v[16:31], v[114:117], v[102:105], v[16:31]
	ds_read_b128 v[88:91], v64 offset:64
	ds_read_b128 v[92:95], v83 offset:18496
	ds_read_b128 v[98:101], v64 offset:96
	ds_read_b128 v[102:105], v83 offset:18528
	v_mfma_f32_32x32x16_bf16 v[0:15], v[114:117], v[110:113], v[0:15]
	ds_read_b128 v[106:109], v83 offset:23104
	ds_read_b128 v[110:113], v83 offset:23136
	s_waitcnt lgkmcnt(4)
	v_mfma_f32_32x32x16_bf16 v[48:63], v[88:91], v[92:95], v[48:63]
	s_waitcnt lgkmcnt(1)
	v_mfma_f32_32x32x16_bf16 v[32:47], v[88:91], v[106:109], v[32:47]
	ds_read_b128 v[88:91], v64 offset:4672
	ds_read_b128 v[114:117], v64 offset:4704
	s_waitcnt lgkmcnt(1)
	v_mfma_f32_32x32x16_bf16 v[16:31], v[88:91], v[92:95], v[16:31]
	v_mfma_f32_32x32x16_bf16 v[0:15], v[88:91], v[106:109], v[0:15]
	v_mfma_f32_32x32x16_bf16 v[48:63], v[98:101], v[102:105], v[48:63]
	v_mfma_f32_32x32x16_bf16 v[32:47], v[98:101], v[110:113], v[32:47]
	s_waitcnt lgkmcnt(0)
	v_mfma_f32_32x32x16_bf16 v[16:31], v[114:117], v[102:105], v[16:31]
	s_barrier
;     ...
;   for (int kt = 0; kt < nk; kt += 2) {
;     if (kt + 2 < nk) G_LOAD(ra0, rb0, kt + 2);
;     if (kt + 1 < nk) G_STORE(ra1, rb1, As1, Bs1);
;     G_COMPUTE(As, Bs);
;     __syncthreads();
;     if (kt + 1 < nk) {
;       if (kt + 3 < nk) G_LOAD(ra1, rb1, kt + 3);
;       if (kt + 2 < nk) G_STORE(ra0, rb0, As, Bs);
;       G_COMPUTE(As1, Bs1);
;       __syncthreads();
;     }
;   }
	s_waitcnt vmcnt(7)
	ds_write_b128 v82, v[138:141]
	s_waitcnt vmcnt(6)
	ds_write_b128 v82, v[142:145] offset:18432
	s_waitcnt vmcnt(5)
	ds_write_b128 v82, v[146:149] offset:4608
	s_waitcnt vmcnt(4)
	ds_write_b128 v82, v[150:153] offset:23040
	s_waitcnt vmcnt(3)
	ds_write_b128 v82, v[154:157] offset:9216
	s_waitcnt vmcnt(2)
	ds_write_b128 v82, v[158:161] offset:27648
	s_waitcnt vmcnt(1)
	ds_write_b128 v82, v[162:165] offset:13824
	s_waitcnt vmcnt(0)
	ds_write_b128 v82, v[166:169] offset:32256
	v_mfma_f32_32x32x16_bf16 v[0:15], v[114:117], v[110:113], v[0:15]
	ds_read_b128 v[88:91], v64 offset:36864
	ds_read_b128 v[92:95], v83 offset:55296
	ds_read_b128 v[98:101], v64 offset:36896
	ds_read_b128 v[102:105], v83 offset:55328
	ds_read_b128 v[106:109], v83 offset:59904
	ds_read_b128 v[110:113], v83 offset:59936
	global_load_dwordx4 v[138:141], v[66:67], off offset:896
	global_load_dwordx4 v[142:145], v[68:69], off offset:896
	global_load_dwordx4 v[146:149], v[70:71], off offset:896
	global_load_dwordx4 v[150:153], v[72:73], off offset:896
	global_load_dwordx4 v[154:157], v[74:75], off offset:896
	global_load_dwordx4 v[158:161], v[76:77], off offset:896
	global_load_dwordx4 v[162:165], v[80:81], off offset:896
	global_load_dwordx4 v[166:169], v[78:79], off offset:896
	s_waitcnt lgkmcnt(4)
	v_mfma_f32_32x32x16_bf16 v[48:63], v[88:91], v[92:95], v[48:63]
	s_waitcnt lgkmcnt(1)
	v_mfma_f32_32x32x16_bf16 v[32:47], v[88:91], v[106:109], v[32:47]
	ds_read_b128 v[88:91], v64 offset:41472
	ds_read_b128 v[114:117], v64 offset:41504
	s_waitcnt lgkmcnt(1)
	v_mfma_f32_32x32x16_bf16 v[16:31], v[88:91], v[92:95], v[16:31]
	v_mfma_f32_32x32x16_bf16 v[0:15], v[88:91], v[106:109], v[0:15]
	v_mfma_f32_32x32x16_bf16 v[48:63], v[98:101], v[102:105], v[48:63]
	v_mfma_f32_32x32x16_bf16 v[32:47], v[98:101], v[110:113], v[32:47]
	s_waitcnt lgkmcnt(0)
	v_mfma_f32_32x32x16_bf16 v[16:31], v[114:117], v[102:105], v[16:31]
	ds_read_b128 v[88:91], v64 offset:36928
	ds_read_b128 v[92:95], v83 offset:55360
	ds_read_b128 v[98:101], v64 offset:36960
	ds_read_b128 v[102:105], v83 offset:55392
	v_mfma_f32_32x32x16_bf16 v[0:15], v[114:117], v[110:113], v[0:15]
	ds_read_b128 v[106:109], v83 offset:59968
	ds_read_b128 v[110:113], v83 offset:60000
	s_waitcnt lgkmcnt(4)
	v_mfma_f32_32x32x16_bf16 v[48:63], v[88:91], v[92:95], v[48:63]
	s_waitcnt lgkmcnt(1)
	v_mfma_f32_32x32x16_bf16 v[32:47], v[88:91], v[106:109], v[32:47]
	ds_read_b128 v[88:91], v64 offset:41536
	ds_read_b128 v[114:117], v64 offset:41568
	s_waitcnt lgkmcnt(1)
	v_mfma_f32_32x32x16_bf16 v[16:31], v[88:91], v[92:95], v[16:31]
	v_mfma_f32_32x32x16_bf16 v[0:15], v[88:91], v[106:109], v[0:15]
	v_mfma_f32_32x32x16_bf16 v[48:63], v[98:101], v[102:105], v[48:63]
	v_mfma_f32_32x32x16_bf16 v[32:47], v[98:101], v[110:113], v[32:47]
	s_waitcnt lgkmcnt(0)
	v_mfma_f32_32x32x16_bf16 v[16:31], v[114:117], v[102:105], v[16:31]
	s_barrier
	s_waitcnt vmcnt(7)
	ds_write_b128 v82, v[138:141] offset:36864
	s_waitcnt vmcnt(6)
	ds_write_b128 v82, v[142:145] offset:55296
	s_waitcnt vmcnt(5)
	ds_write_b128 v82, v[146:149] offset:41472
	s_waitcnt vmcnt(4)
	ds_write_b128 v82, v[150:153] offset:59904
	s_waitcnt vmcnt(3)
	ds_write_b128 v82, v[154:157] offset:46080
	s_waitcnt vmcnt(2)
	ds_write_b128 v82, v[158:161] offset:64512
	s_waitcnt vmcnt(1)
	ds_write_b128 v82, v[162:165] offset:50688
	s_waitcnt vmcnt(0)
	ds_write_b128 v86, v[166:169] offset:13824
	v_mfma_f32_32x32x16_bf16 v[0:15], v[114:117], v[110:113], v[0:15]
	ds_read_b128 v[88:91], v64
	ds_read_b128 v[92:95], v83 offset:18432
	ds_read_b128 v[98:101], v64 offset:32
	ds_read_b128 v[102:105], v83 offset:18464
	ds_read_b128 v[106:109], v83 offset:23040
	ds_read_b128 v[110:113], v83 offset:23072
	global_load_dwordx4 v[138:141], v[66:67], off offset:1024
	global_load_dwordx4 v[142:145], v[68:69], off offset:1024
	global_load_dwordx4 v[146:149], v[70:71], off offset:1024
	global_load_dwordx4 v[150:153], v[72:73], off offset:1024
	global_load_dwordx4 v[154:157], v[74:75], off offset:1024
	global_load_dwordx4 v[158:161], v[76:77], off offset:1024
	global_load_dwordx4 v[162:165], v[80:81], off offset:1024
	global_load_dwordx4 v[166:169], v[78:79], off offset:1024
	s_waitcnt lgkmcnt(4)
	v_mfma_f32_32x32x16_bf16 v[48:63], v[88:91], v[92:95], v[48:63]
	s_waitcnt lgkmcnt(1)
	v_mfma_f32_32x32x16_bf16 v[32:47], v[88:91], v[106:109], v[32:47]
	ds_read_b128 v[88:91], v64 offset:4608
	ds_read_b128 v[114:117], v64 offset:4640
	s_waitcnt lgkmcnt(1)
	v_mfma_f32_32x32x16_bf16 v[16:31], v[88:91], v[92:95], v[16:31]
	v_mfma_f32_32x32x16_bf16 v[0:15], v[88:91], v[106:109], v[0:15]
	v_mfma_f32_32x32x16_bf16 v[48:63], v[98:101], v[102:105], v[48:63]
	v_mfma_f32_32x32x16_bf16 v[32:47], v[98:101], v[110:113], v[32:47]
	s_waitcnt lgkmcnt(0)
	v_mfma_f32_32x32x16_bf16 v[16:31], v[114:117], v[102:105], v[16:31]
	ds_read_b128 v[88:91], v64 offset:64
	ds_read_b128 v[92:95], v83 offset:18496
	ds_read_b128 v[98:101], v64 offset:96
	ds_read_b128 v[102:105], v83 offset:18528
	v_mfma_f32_32x32x16_bf16 v[0:15], v[114:117], v[110:113], v[0:15]
	ds_read_b128 v[106:109], v83 offset:23104
	ds_read_b128 v[110:113], v83 offset:23136
	s_waitcnt lgkmcnt(4)
	v_mfma_f32_32x32x16_bf16 v[48:63], v[88:91], v[92:95], v[48:63]
	s_waitcnt lgkmcnt(1)
	v_mfma_f32_32x32x16_bf16 v[32:47], v[88:91], v[106:109], v[32:47]
	ds_read_b128 v[88:91], v64 offset:4672
	ds_read_b128 v[114:117], v64 offset:4704
	s_waitcnt lgkmcnt(1)
	v_mfma_f32_32x32x16_bf16 v[16:31], v[88:91], v[92:95], v[16:31]
	v_mfma_f32_32x32x16_bf16 v[0:15], v[88:91], v[106:109], v[0:15]
	v_mfma_f32_32x32x16_bf16 v[48:63], v[98:101], v[102:105], v[48:63]
	v_mfma_f32_32x32x16_bf16 v[32:47], v[98:101], v[110:113], v[32:47]
	s_waitcnt lgkmcnt(0)
	v_mfma_f32_32x32x16_bf16 v[16:31], v[114:117], v[102:105], v[16:31]
	s_barrier
;     ...
;   for (int kt = 0; kt < nk; kt += 2) {
;     if (kt + 2 < nk) G_LOAD(ra0, rb0, kt + 2);
;     if (kt + 1 < nk) G_STORE(ra1, rb1, As1, Bs1);
;     G_COMPUTE(As, Bs);
;     __syncthreads();
;     if (kt + 1 < nk) {
;       if (kt + 3 < nk) G_LOAD(ra1, rb1, kt + 3);
;       if (kt + 2 < nk) G_STORE(ra0, rb0, As, Bs);
;       G_COMPUTE(As1, Bs1);
;       __syncthreads();
;     }
;   }
	s_waitcnt vmcnt(7)
	ds_write_b128 v82, v[138:141]
	s_waitcnt vmcnt(6)
	ds_write_b128 v82, v[142:145] offset:18432
	s_waitcnt vmcnt(5)
	ds_write_b128 v82, v[146:149] offset:4608
	s_waitcnt vmcnt(4)
	ds_write_b128 v82, v[150:153] offset:23040
	s_waitcnt vmcnt(3)
	ds_write_b128 v82, v[154:157] offset:9216
	s_waitcnt vmcnt(2)
	ds_write_b128 v82, v[158:161] offset:27648
	s_waitcnt vmcnt(1)
	ds_write_b128 v82, v[162:165] offset:13824
	s_waitcnt vmcnt(0)
	ds_write_b128 v82, v[166:169] offset:32256
	v_mfma_f32_32x32x16_bf16 v[0:15], v[114:117], v[110:113], v[0:15]
	ds_read_b128 v[88:91], v64 offset:36864
	ds_read_b128 v[92:95], v83 offset:55296
	ds_read_b128 v[98:101], v64 offset:36896
	ds_read_b128 v[102:105], v83 offset:55328
	ds_read_b128 v[106:109], v83 offset:59904
	ds_read_b128 v[110:113], v83 offset:59936
	global_load_dwordx4 v[138:141], v[66:67], off offset:1152
	global_load_dwordx4 v[142:145], v[68:69], off offset:1152
	global_load_dwordx4 v[146:149], v[70:71], off offset:1152
	global_load_dwordx4 v[150:153], v[72:73], off offset:1152
	global_load_dwordx4 v[154:157], v[74:75], off offset:1152
	global_load_dwordx4 v[158:161], v[76:77], off offset:1152
	global_load_dwordx4 v[162:165], v[80:81], off offset:1152
	global_load_dwordx4 v[166:169], v[78:79], off offset:1152
	s_waitcnt lgkmcnt(4)
	v_mfma_f32_32x32x16_bf16 v[48:63], v[88:91], v[92:95], v[48:63]
	s_waitcnt lgkmcnt(1)
	v_mfma_f32_32x32x16_bf16 v[32:47], v[88:91], v[106:109], v[32:47]
	ds_read_b128 v[88:91], v64 offset:41472
	ds_read_b128 v[114:117], v64 offset:41504
	s_waitcnt lgkmcnt(1)
	v_mfma_f32_32x32x16_bf16 v[16:31], v[88:91], v[92:95], v[16:31]
	v_mfma_f32_32x32x16_bf16 v[0:15], v[88:91], v[106:109], v[0:15]
	v_mfma_f32_32x32x16_bf16 v[48:63], v[98:101], v[102:105], v[48:63]
	v_mfma_f32_32x32x16_bf16 v[32:47], v[98:101], v[110:113], v[32:47]
	s_waitcnt lgkmcnt(0)
	v_mfma_f32_32x32x16_bf16 v[16:31], v[114:117], v[102:105], v[16:31]
	ds_read_b128 v[88:91], v64 offset:36928
	ds_read_b128 v[92:95], v83 offset:55360
	ds_read_b128 v[98:101], v64 offset:36960
	ds_read_b128 v[102:105], v83 offset:55392
	v_mfma_f32_32x32x16_bf16 v[0:15], v[114:117], v[110:113], v[0:15]
	ds_read_b128 v[106:109], v83 offset:59968
	ds_read_b128 v[110:113], v83 offset:60000
	s_waitcnt lgkmcnt(4)
	v_mfma_f32_32x32x16_bf16 v[48:63], v[88:91], v[92:95], v[48:63]
	s_waitcnt lgkmcnt(1)
	v_mfma_f32_32x32x16_bf16 v[32:47], v[88:91], v[106:109], v[32:47]
	ds_read_b128 v[88:91], v64 offset:41536
	ds_read_b128 v[114:117], v64 offset:41568
	s_waitcnt lgkmcnt(1)
	v_mfma_f32_32x32x16_bf16 v[16:31], v[88:91], v[92:95], v[16:31]
	v_mfma_f32_32x32x16_bf16 v[0:15], v[88:91], v[106:109], v[0:15]
	v_mfma_f32_32x32x16_bf16 v[48:63], v[98:101], v[102:105], v[48:63]
	v_mfma_f32_32x32x16_bf16 v[32:47], v[98:101], v[110:113], v[32:47]
	s_waitcnt lgkmcnt(0)
	v_mfma_f32_32x32x16_bf16 v[16:31], v[114:117], v[102:105], v[16:31]
	s_barrier
	s_waitcnt vmcnt(7)
	ds_write_b128 v82, v[138:141] offset:36864
	s_waitcnt vmcnt(6)
	ds_write_b128 v82, v[142:145] offset:55296
	s_waitcnt vmcnt(5)
	ds_write_b128 v82, v[146:149] offset:41472
	s_waitcnt vmcnt(4)
	ds_write_b128 v82, v[150:153] offset:59904
	s_waitcnt vmcnt(3)
	ds_write_b128 v82, v[154:157] offset:46080
	s_waitcnt vmcnt(2)
	ds_write_b128 v82, v[158:161] offset:64512
	s_waitcnt vmcnt(1)
	ds_write_b128 v82, v[162:165] offset:50688
	s_waitcnt vmcnt(0)
	ds_write_b128 v86, v[166:169] offset:13824
	v_mfma_f32_32x32x16_bf16 v[0:15], v[114:117], v[110:113], v[0:15]
	ds_read_b128 v[88:91], v64
	ds_read_b128 v[92:95], v83 offset:18432
	ds_read_b128 v[98:101], v64 offset:32
	ds_read_b128 v[102:105], v83 offset:18464
	ds_read_b128 v[106:109], v83 offset:23040
	ds_read_b128 v[110:113], v83 offset:23072
	global_load_dwordx4 v[138:141], v[66:67], off offset:1280
	global_load_dwordx4 v[142:145], v[68:69], off offset:1280
	global_load_dwordx4 v[146:149], v[70:71], off offset:1280
	global_load_dwordx4 v[150:153], v[72:73], off offset:1280
	global_load_dwordx4 v[154:157], v[74:75], off offset:1280
	global_load_dwordx4 v[158:161], v[76:77], off offset:1280
	global_load_dwordx4 v[162:165], v[80:81], off offset:1280
	global_load_dwordx4 v[166:169], v[78:79], off offset:1280
	s_waitcnt lgkmcnt(4)
	v_mfma_f32_32x32x16_bf16 v[48:63], v[88:91], v[92:95], v[48:63]
	s_waitcnt lgkmcnt(1)
	v_mfma_f32_32x32x16_bf16 v[32:47], v[88:91], v[106:109], v[32:47]
	ds_read_b128 v[88:91], v64 offset:4608
	ds_read_b128 v[114:117], v64 offset:4640
	s_waitcnt lgkmcnt(1)
	v_mfma_f32_32x32x16_bf16 v[16:31], v[88:91], v[92:95], v[16:31]
	v_mfma_f32_32x32x16_bf16 v[0:15], v[88:91], v[106:109], v[0:15]
	v_mfma_f32_32x32x16_bf16 v[48:63], v[98:101], v[102:105], v[48:63]
	v_mfma_f32_32x32x16_bf16 v[32:47], v[98:101], v[110:113], v[32:47]
	s_waitcnt lgkmcnt(0)
	v_mfma_f32_32x32x16_bf16 v[16:31], v[114:117], v[102:105], v[16:31]
	ds_read_b128 v[88:91], v64 offset:64
	ds_read_b128 v[92:95], v83 offset:18496
	ds_read_b128 v[98:101], v64 offset:96
	ds_read_b128 v[102:105], v83 offset:18528
	v_mfma_f32_32x32x16_bf16 v[0:15], v[114:117], v[110:113], v[0:15]
	ds_read_b128 v[106:109], v83 offset:23104
	ds_read_b128 v[110:113], v83 offset:23136
	s_waitcnt lgkmcnt(4)
	v_mfma_f32_32x32x16_bf16 v[48:63], v[88:91], v[92:95], v[48:63]
	s_waitcnt lgkmcnt(1)
	v_mfma_f32_32x32x16_bf16 v[32:47], v[88:91], v[106:109], v[32:47]
	ds_read_b128 v[88:91], v64 offset:4672
	ds_read_b128 v[114:117], v64 offset:4704
	s_waitcnt lgkmcnt(1)
	v_mfma_f32_32x32x16_bf16 v[16:31], v[88:91], v[92:95], v[16:31]
	v_mfma_f32_32x32x16_bf16 v[0:15], v[88:91], v[106:109], v[0:15]
	v_mfma_f32_32x32x16_bf16 v[48:63], v[98:101], v[102:105], v[48:63]
	v_mfma_f32_32x32x16_bf16 v[32:47], v[98:101], v[110:113], v[32:47]
	s_waitcnt lgkmcnt(0)
	v_mfma_f32_32x32x16_bf16 v[16:31], v[114:117], v[102:105], v[16:31]
	s_barrier
;     ...
;   for (int kt = 0; kt < nk; kt += 2) {
;     if (kt + 2 < nk) G_LOAD(ra0, rb0, kt + 2);
;     if (kt + 1 < nk) G_STORE(ra1, rb1, As1, Bs1);
;     G_COMPUTE(As, Bs);
;     __syncthreads();
;     if (kt + 1 < nk) {
;       if (kt + 3 < nk) G_LOAD(ra1, rb1, kt + 3);
;       if (kt + 2 < nk) G_STORE(ra0, rb0, As, Bs);
;       G_COMPUTE(As1, Bs1);
;       __syncthreads();
;     }
;   }
	s_waitcnt vmcnt(7)
	ds_write_b128 v82, v[138:141]
	s_waitcnt vmcnt(6)
	ds_write_b128 v82, v[142:145] offset:18432
	s_waitcnt vmcnt(5)
	ds_write_b128 v82, v[146:149] offset:4608
	s_waitcnt vmcnt(4)
	ds_write_b128 v82, v[150:153] offset:23040
	s_waitcnt vmcnt(3)
	ds_write_b128 v82, v[154:157] offset:9216
	s_waitcnt vmcnt(2)
	ds_write_b128 v82, v[158:161] offset:27648
	s_waitcnt vmcnt(1)
	ds_write_b128 v82, v[162:165] offset:13824
	s_waitcnt vmcnt(0)
	ds_write_b128 v82, v[166:169] offset:32256
	v_mfma_f32_32x32x16_bf16 v[0:15], v[114:117], v[110:113], v[0:15]
	ds_read_b128 v[88:91], v64 offset:36864
	ds_read_b128 v[92:95], v83 offset:55296
	ds_read_b128 v[98:101], v64 offset:36896
	ds_read_b128 v[102:105], v83 offset:55328
	ds_read_b128 v[106:109], v83 offset:59904
	ds_read_b128 v[110:113], v83 offset:59936
	global_load_dwordx4 v[138:141], v[66:67], off offset:1408
	global_load_dwordx4 v[142:145], v[68:69], off offset:1408
	global_load_dwordx4 v[146:149], v[70:71], off offset:1408
	global_load_dwordx4 v[150:153], v[72:73], off offset:1408
	global_load_dwordx4 v[154:157], v[74:75], off offset:1408
	global_load_dwordx4 v[158:161], v[76:77], off offset:1408
	global_load_dwordx4 v[162:165], v[80:81], off offset:1408
	global_load_dwordx4 v[166:169], v[78:79], off offset:1408
	s_waitcnt lgkmcnt(4)
	v_mfma_f32_32x32x16_bf16 v[48:63], v[88:91], v[92:95], v[48:63]
	s_waitcnt lgkmcnt(1)
	v_mfma_f32_32x32x16_bf16 v[32:47], v[88:91], v[106:109], v[32:47]
	ds_read_b128 v[88:91], v64 offset:41472
	ds_read_b128 v[114:117], v64 offset:41504
	s_waitcnt lgkmcnt(1)
	v_mfma_f32_32x32x16_bf16 v[16:31], v[88:91], v[92:95], v[16:31]
	v_mfma_f32_32x32x16_bf16 v[0:15], v[88:91], v[106:109], v[0:15]
	v_mfma_f32_32x32x16_bf16 v[48:63], v[98:101], v[102:105], v[48:63]
	v_mfma_f32_32x32x16_bf16 v[32:47], v[98:101], v[110:113], v[32:47]
	s_waitcnt lgkmcnt(0)
	v_mfma_f32_32x32x16_bf16 v[16:31], v[114:117], v[102:105], v[16:31]
	ds_read_b128 v[88:91], v64 offset:36928
	ds_read_b128 v[92:95], v83 offset:55360
	ds_read_b128 v[98:101], v64 offset:36960
	ds_read_b128 v[102:105], v83 offset:55392
	v_mfma_f32_32x32x16_bf16 v[0:15], v[114:117], v[110:113], v[0:15]
	ds_read_b128 v[106:109], v83 offset:59968
	ds_read_b128 v[110:113], v83 offset:60000
	s_waitcnt lgkmcnt(4)
	v_mfma_f32_32x32x16_bf16 v[48:63], v[88:91], v[92:95], v[48:63]
	s_waitcnt lgkmcnt(1)
	v_mfma_f32_32x32x16_bf16 v[32:47], v[88:91], v[106:109], v[32:47]
	ds_read_b128 v[88:91], v64 offset:41536
	ds_read_b128 v[114:117], v64 offset:41568
	s_waitcnt lgkmcnt(1)
	v_mfma_f32_32x32x16_bf16 v[16:31], v[88:91], v[92:95], v[16:31]
	v_mfma_f32_32x32x16_bf16 v[0:15], v[88:91], v[106:109], v[0:15]
	v_mfma_f32_32x32x16_bf16 v[48:63], v[98:101], v[102:105], v[48:63]
	v_mfma_f32_32x32x16_bf16 v[32:47], v[98:101], v[110:113], v[32:47]
	s_waitcnt lgkmcnt(0)
	v_mfma_f32_32x32x16_bf16 v[16:31], v[114:117], v[102:105], v[16:31]
	s_barrier
	s_waitcnt vmcnt(7)
	ds_write_b128 v82, v[138:141] offset:36864
	s_waitcnt vmcnt(6)
	ds_write_b128 v82, v[142:145] offset:55296
	s_waitcnt vmcnt(5)
	ds_write_b128 v82, v[146:149] offset:41472
	s_waitcnt vmcnt(4)
	ds_write_b128 v82, v[150:153] offset:59904
	s_waitcnt vmcnt(3)
	ds_write_b128 v82, v[154:157] offset:46080
	s_waitcnt vmcnt(2)
	ds_write_b128 v82, v[158:161] offset:64512
	s_waitcnt vmcnt(1)
	ds_write_b128 v82, v[162:165] offset:50688
	s_waitcnt vmcnt(0)
	ds_write_b128 v86, v[166:169] offset:13824
	v_mfma_f32_32x32x16_bf16 v[0:15], v[114:117], v[110:113], v[0:15]
	ds_read_b128 v[88:91], v64
	ds_read_b128 v[92:95], v83 offset:18432
	ds_read_b128 v[98:101], v64 offset:32
	ds_read_b128 v[102:105], v83 offset:18464
	ds_read_b128 v[106:109], v83 offset:23040
	ds_read_b128 v[110:113], v83 offset:23072
	global_load_dwordx4 v[138:141], v[66:67], off offset:1536
	global_load_dwordx4 v[142:145], v[68:69], off offset:1536
	global_load_dwordx4 v[146:149], v[70:71], off offset:1536
	global_load_dwordx4 v[150:153], v[72:73], off offset:1536
	global_load_dwordx4 v[154:157], v[74:75], off offset:1536
	global_load_dwordx4 v[158:161], v[76:77], off offset:1536
	global_load_dwordx4 v[162:165], v[80:81], off offset:1536
	global_load_dwordx4 v[166:169], v[78:79], off offset:1536
	s_waitcnt lgkmcnt(4)
	v_mfma_f32_32x32x16_bf16 v[48:63], v[88:91], v[92:95], v[48:63]
	s_waitcnt lgkmcnt(1)
	v_mfma_f32_32x32x16_bf16 v[32:47], v[88:91], v[106:109], v[32:47]
	ds_read_b128 v[88:91], v64 offset:4608
	ds_read_b128 v[114:117], v64 offset:4640
	s_waitcnt lgkmcnt(1)
	v_mfma_f32_32x32x16_bf16 v[16:31], v[88:91], v[92:95], v[16:31]
	v_mfma_f32_32x32x16_bf16 v[0:15], v[88:91], v[106:109], v[0:15]
	v_mfma_f32_32x32x16_bf16 v[48:63], v[98:101], v[102:105], v[48:63]
	v_mfma_f32_32x32x16_bf16 v[32:47], v[98:101], v[110:113], v[32:47]
	s_waitcnt lgkmcnt(0)
	v_mfma_f32_32x32x16_bf16 v[16:31], v[114:117], v[102:105], v[16:31]
	ds_read_b128 v[88:91], v64 offset:64
	ds_read_b128 v[92:95], v83 offset:18496
	ds_read_b128 v[98:101], v64 offset:96
	ds_read_b128 v[102:105], v83 offset:18528
	v_mfma_f32_32x32x16_bf16 v[0:15], v[114:117], v[110:113], v[0:15]
	ds_read_b128 v[106:109], v83 offset:23104
	ds_read_b128 v[110:113], v83 offset:23136
	s_waitcnt lgkmcnt(4)
	v_mfma_f32_32x32x16_bf16 v[48:63], v[88:91], v[92:95], v[48:63]
	s_waitcnt lgkmcnt(1)
	v_mfma_f32_32x32x16_bf16 v[32:47], v[88:91], v[106:109], v[32:47]
	ds_read_b128 v[88:91], v64 offset:4672
	ds_read_b128 v[114:117], v64 offset:4704
	s_waitcnt lgkmcnt(1)
	v_mfma_f32_32x32x16_bf16 v[16:31], v[88:91], v[92:95], v[16:31]
	v_mfma_f32_32x32x16_bf16 v[0:15], v[88:91], v[106:109], v[0:15]
	v_mfma_f32_32x32x16_bf16 v[48:63], v[98:101], v[102:105], v[48:63]
	v_mfma_f32_32x32x16_bf16 v[32:47], v[98:101], v[110:113], v[32:47]
	s_waitcnt lgkmcnt(0)
	v_mfma_f32_32x32x16_bf16 v[16:31], v[114:117], v[102:105], v[16:31]
	s_barrier
;     ...
;   for (int kt = 0; kt < nk; kt += 2) {
;     if (kt + 2 < nk) G_LOAD(ra0, rb0, kt + 2);
;     if (kt + 1 < nk) G_STORE(ra1, rb1, As1, Bs1);
;     G_COMPUTE(As, Bs);
;     __syncthreads();
;     if (kt + 1 < nk) {
;       if (kt + 3 < nk) G_LOAD(ra1, rb1, kt + 3);
;       if (kt + 2 < nk) G_STORE(ra0, rb0, As, Bs);
;       G_COMPUTE(As1, Bs1);
;       __syncthreads();
;     }
;   }
	s_waitcnt vmcnt(7)
	ds_write_b128 v82, v[138:141]
	s_waitcnt vmcnt(6)
	ds_write_b128 v82, v[142:145] offset:18432
	s_waitcnt vmcnt(5)
	ds_write_b128 v82, v[146:149] offset:4608
	s_waitcnt vmcnt(4)
	ds_write_b128 v82, v[150:153] offset:23040
	s_waitcnt vmcnt(3)
	ds_write_b128 v82, v[154:157] offset:9216
	s_waitcnt vmcnt(2)
	ds_write_b128 v82, v[158:161] offset:27648
	s_waitcnt vmcnt(1)
	ds_write_b128 v82, v[162:165] offset:13824
	s_waitcnt vmcnt(0)
	ds_write_b128 v82, v[166:169] offset:32256
	v_mfma_f32_32x32x16_bf16 v[0:15], v[114:117], v[110:113], v[0:15]
	ds_read_b128 v[88:91], v64 offset:36864
	ds_read_b128 v[92:95], v83 offset:55296
	ds_read_b128 v[98:101], v64 offset:36896
	ds_read_b128 v[102:105], v83 offset:55328
	ds_read_b128 v[106:109], v83 offset:59904
	ds_read_b128 v[110:113], v83 offset:59936
	global_load_dwordx4 v[138:141], v[66:67], off offset:1664
	global_load_dwordx4 v[142:145], v[68:69], off offset:1664
	global_load_dwordx4 v[146:149], v[70:71], off offset:1664
	global_load_dwordx4 v[150:153], v[72:73], off offset:1664
	global_load_dwordx4 v[154:157], v[74:75], off offset:1664
	global_load_dwordx4 v[158:161], v[76:77], off offset:1664
	global_load_dwordx4 v[162:165], v[80:81], off offset:1664
	global_load_dwordx4 v[166:169], v[78:79], off offset:1664
	s_waitcnt lgkmcnt(4)
	v_mfma_f32_32x32x16_bf16 v[48:63], v[88:91], v[92:95], v[48:63]
	s_waitcnt lgkmcnt(1)
	v_mfma_f32_32x32x16_bf16 v[32:47], v[88:91], v[106:109], v[32:47]
	ds_read_b128 v[88:91], v64 offset:41472
	ds_read_b128 v[114:117], v64 offset:41504
	s_waitcnt lgkmcnt(1)
	v_mfma_f32_32x32x16_bf16 v[16:31], v[88:91], v[92:95], v[16:31]
	v_mfma_f32_32x32x16_bf16 v[0:15], v[88:91], v[106:109], v[0:15]
	v_mfma_f32_32x32x16_bf16 v[48:63], v[98:101], v[102:105], v[48:63]
	v_mfma_f32_32x32x16_bf16 v[32:47], v[98:101], v[110:113], v[32:47]
	s_waitcnt lgkmcnt(0)
	v_mfma_f32_32x32x16_bf16 v[16:31], v[114:117], v[102:105], v[16:31]
	ds_read_b128 v[88:91], v64 offset:36928
	ds_read_b128 v[92:95], v83 offset:55360
	ds_read_b128 v[98:101], v64 offset:36960
	ds_read_b128 v[102:105], v83 offset:55392
	v_mfma_f32_32x32x16_bf16 v[0:15], v[114:117], v[110:113], v[0:15]
	ds_read_b128 v[106:109], v83 offset:59968
	ds_read_b128 v[110:113], v83 offset:60000
	s_waitcnt lgkmcnt(4)
	v_mfma_f32_32x32x16_bf16 v[48:63], v[88:91], v[92:95], v[48:63]
	s_waitcnt lgkmcnt(1)
	v_mfma_f32_32x32x16_bf16 v[32:47], v[88:91], v[106:109], v[32:47]
	ds_read_b128 v[88:91], v64 offset:41536
	ds_read_b128 v[114:117], v64 offset:41568
	s_waitcnt lgkmcnt(1)
	v_mfma_f32_32x32x16_bf16 v[16:31], v[88:91], v[92:95], v[16:31]
	v_mfma_f32_32x32x16_bf16 v[0:15], v[88:91], v[106:109], v[0:15]
	v_mfma_f32_32x32x16_bf16 v[48:63], v[98:101], v[102:105], v[48:63]
	v_mfma_f32_32x32x16_bf16 v[32:47], v[98:101], v[110:113], v[32:47]
	s_waitcnt lgkmcnt(0)
	v_mfma_f32_32x32x16_bf16 v[16:31], v[114:117], v[102:105], v[16:31]
	s_barrier
	s_waitcnt vmcnt(7)
	ds_write_b128 v82, v[138:141] offset:36864
	s_waitcnt vmcnt(6)
	ds_write_b128 v82, v[142:145] offset:55296
	s_waitcnt vmcnt(5)
	ds_write_b128 v82, v[146:149] offset:41472
	s_waitcnt vmcnt(4)
	ds_write_b128 v82, v[150:153] offset:59904
	s_waitcnt vmcnt(3)
	ds_write_b128 v82, v[154:157] offset:46080
	s_waitcnt vmcnt(2)
	ds_write_b128 v82, v[158:161] offset:64512
	s_waitcnt vmcnt(1)
	ds_write_b128 v82, v[162:165] offset:50688
	s_waitcnt vmcnt(0)
	ds_write_b128 v86, v[166:169] offset:13824
	v_mfma_f32_32x32x16_bf16 v[0:15], v[114:117], v[110:113], v[0:15]
	ds_read_b128 v[88:91], v64
	ds_read_b128 v[92:95], v83 offset:18432
	ds_read_b128 v[98:101], v64 offset:32
	ds_read_b128 v[102:105], v83 offset:18464
	ds_read_b128 v[106:109], v83 offset:23040
	ds_read_b128 v[110:113], v83 offset:23072
	global_load_dwordx4 v[138:141], v[66:67], off offset:1792
	global_load_dwordx4 v[142:145], v[68:69], off offset:1792
	global_load_dwordx4 v[146:149], v[70:71], off offset:1792
	global_load_dwordx4 v[150:153], v[72:73], off offset:1792
	global_load_dwordx4 v[154:157], v[74:75], off offset:1792
	global_load_dwordx4 v[158:161], v[76:77], off offset:1792
	global_load_dwordx4 v[162:165], v[80:81], off offset:1792
	global_load_dwordx4 v[166:169], v[78:79], off offset:1792
	s_waitcnt lgkmcnt(4)
	v_mfma_f32_32x32x16_bf16 v[48:63], v[88:91], v[92:95], v[48:63]
	s_waitcnt lgkmcnt(1)
	v_mfma_f32_32x32x16_bf16 v[32:47], v[88:91], v[106:109], v[32:47]
	ds_read_b128 v[88:91], v64 offset:4608
	ds_read_b128 v[114:117], v64 offset:4640
	s_waitcnt lgkmcnt(1)
	v_mfma_f32_32x32x16_bf16 v[16:31], v[88:91], v[92:95], v[16:31]
	v_mfma_f32_32x32x16_bf16 v[0:15], v[88:91], v[106:109], v[0:15]
	v_mfma_f32_32x32x16_bf16 v[48:63], v[98:101], v[102:105], v[48:63]
	v_mfma_f32_32x32x16_bf16 v[32:47], v[98:101], v[110:113], v[32:47]
	s_waitcnt lgkmcnt(0)
	v_mfma_f32_32x32x16_bf16 v[16:31], v[114:117], v[102:105], v[16:31]
	ds_read_b128 v[88:91], v64 offset:64
	ds_read_b128 v[92:95], v83 offset:18496
	ds_read_b128 v[98:101], v64 offset:96
	ds_read_b128 v[102:105], v83 offset:18528
	v_mfma_f32_32x32x16_bf16 v[0:15], v[114:117], v[110:113], v[0:15]
	ds_read_b128 v[106:109], v83 offset:23104
	ds_read_b128 v[110:113], v83 offset:23136
	s_waitcnt lgkmcnt(4)
	v_mfma_f32_32x32x16_bf16 v[48:63], v[88:91], v[92:95], v[48:63]
	s_waitcnt lgkmcnt(1)
	v_mfma_f32_32x32x16_bf16 v[32:47], v[88:91], v[106:109], v[32:47]
	ds_read_b128 v[88:91], v64 offset:4672
	ds_read_b128 v[114:117], v64 offset:4704
	s_waitcnt lgkmcnt(1)
	v_mfma_f32_32x32x16_bf16 v[16:31], v[88:91], v[92:95], v[16:31]
	v_mfma_f32_32x32x16_bf16 v[0:15], v[88:91], v[106:109], v[0:15]
	v_mfma_f32_32x32x16_bf16 v[48:63], v[98:101], v[102:105], v[48:63]
	v_mfma_f32_32x32x16_bf16 v[32:47], v[98:101], v[110:113], v[32:47]
	s_waitcnt lgkmcnt(0)
	v_mfma_f32_32x32x16_bf16 v[16:31], v[114:117], v[102:105], v[16:31]
	s_barrier
;     ...
;   for (int kt = 0; kt < nk; kt += 2) {
;     if (kt + 2 < nk) G_LOAD(ra0, rb0, kt + 2);
;     if (kt + 1 < nk) G_STORE(ra1, rb1, As1, Bs1);
;     G_COMPUTE(As, Bs);
;     __syncthreads();
;     if (kt + 1 < nk) {
;       if (kt + 3 < nk) G_LOAD(ra1, rb1, kt + 3);
;       if (kt + 2 < nk) G_STORE(ra0, rb0, As, Bs);
;       G_COMPUTE(As1, Bs1);
;       __syncthreads();
;     }
;   }
	s_waitcnt vmcnt(7)
	ds_write_b128 v82, v[138:141]
	s_waitcnt vmcnt(6)
	ds_write_b128 v82, v[142:145] offset:18432
	s_waitcnt vmcnt(5)
	ds_write_b128 v82, v[146:149] offset:4608
	s_waitcnt vmcnt(4)
	ds_write_b128 v82, v[150:153] offset:23040
	s_waitcnt vmcnt(3)
	ds_write_b128 v82, v[154:157] offset:9216
	s_waitcnt vmcnt(2)
	ds_write_b128 v82, v[158:161] offset:27648
	s_waitcnt vmcnt(1)
	ds_write_b128 v82, v[162:165] offset:13824
	s_waitcnt vmcnt(0)
	ds_write_b128 v82, v[166:169] offset:32256
	v_mfma_f32_32x32x16_bf16 v[0:15], v[114:117], v[110:113], v[0:15]
	ds_read_b128 v[88:91], v64 offset:36864
	ds_read_b128 v[92:95], v83 offset:55296
	ds_read_b128 v[98:101], v64 offset:36896
	ds_read_b128 v[102:105], v83 offset:55328
	ds_read_b128 v[106:109], v83 offset:59904
	ds_read_b128 v[110:113], v83 offset:59936
	global_load_dwordx4 v[138:141], v[66:67], off offset:1920
	global_load_dwordx4 v[142:145], v[68:69], off offset:1920
	global_load_dwordx4 v[146:149], v[70:71], off offset:1920
	global_load_dwordx4 v[150:153], v[72:73], off offset:1920
	global_load_dwordx4 v[154:157], v[74:75], off offset:1920
	global_load_dwordx4 v[158:161], v[76:77], off offset:1920
	global_load_dwordx4 v[162:165], v[80:81], off offset:1920
	global_load_dwordx4 v[166:169], v[78:79], off offset:1920
	s_waitcnt lgkmcnt(4)
	v_mfma_f32_32x32x16_bf16 v[48:63], v[88:91], v[92:95], v[48:63]
	s_waitcnt lgkmcnt(1)
	v_mfma_f32_32x32x16_bf16 v[32:47], v[88:91], v[106:109], v[32:47]
	ds_read_b128 v[88:91], v64 offset:41472
	ds_read_b128 v[114:117], v64 offset:41504
	s_waitcnt lgkmcnt(1)
	v_mfma_f32_32x32x16_bf16 v[16:31], v[88:91], v[92:95], v[16:31]
	v_mfma_f32_32x32x16_bf16 v[0:15], v[88:91], v[106:109], v[0:15]
	v_mfma_f32_32x32x16_bf16 v[48:63], v[98:101], v[102:105], v[48:63]
	v_mfma_f32_32x32x16_bf16 v[32:47], v[98:101], v[110:113], v[32:47]
	s_waitcnt lgkmcnt(0)
	v_mfma_f32_32x32x16_bf16 v[16:31], v[114:117], v[102:105], v[16:31]
	ds_read_b128 v[88:91], v64 offset:36928
	ds_read_b128 v[92:95], v83 offset:55360
	ds_read_b128 v[98:101], v64 offset:36960
	ds_read_b128 v[102:105], v83 offset:55392
	v_mfma_f32_32x32x16_bf16 v[0:15], v[114:117], v[110:113], v[0:15]
	ds_read_b128 v[106:109], v83 offset:59968
	ds_read_b128 v[110:113], v83 offset:60000
	s_waitcnt lgkmcnt(4)
	v_mfma_f32_32x32x16_bf16 v[48:63], v[88:91], v[92:95], v[48:63]
	s_waitcnt lgkmcnt(1)
	v_mfma_f32_32x32x16_bf16 v[32:47], v[88:91], v[106:109], v[32:47]
	ds_read_b128 v[88:91], v64 offset:41536
	ds_read_b128 v[114:117], v64 offset:41568
	s_waitcnt lgkmcnt(1)
	v_mfma_f32_32x32x16_bf16 v[16:31], v[88:91], v[92:95], v[16:31]
	v_mfma_f32_32x32x16_bf16 v[0:15], v[88:91], v[106:109], v[0:15]
	v_mfma_f32_32x32x16_bf16 v[48:63], v[98:101], v[102:105], v[48:63]
	v_mfma_f32_32x32x16_bf16 v[32:47], v[98:101], v[110:113], v[32:47]
	s_nop 0
	s_nop 0
	s_nop 0
	s_nop 0
	s_nop 0
	s_nop 0
	s_nop 0
	s_waitcnt lgkmcnt(0)
	s_barrier
	s_waitcnt vmcnt(7)
	ds_write_b128 v82, v[138:141] offset:36864
	s_waitcnt vmcnt(6)
	ds_write_b128 v82, v[142:145] offset:55296
	s_waitcnt vmcnt(5)
	ds_write_b128 v82, v[146:149] offset:41472
	s_waitcnt vmcnt(4)
	ds_write_b128 v82, v[150:153] offset:59904
	s_waitcnt vmcnt(3)
	ds_write_b128 v82, v[154:157] offset:46080
	s_waitcnt vmcnt(2)
	ds_write_b128 v82, v[158:161] offset:64512
	s_waitcnt vmcnt(1)
	ds_write_b128 v82, v[162:165] offset:50688
	s_waitcnt vmcnt(0)
	ds_write_b128 v86, v[166:169] offset:13824
	v_mfma_f32_32x32x16_bf16 v[16:31], v[114:117], v[102:105], v[16:31]
	ds_read_b128 v[66:69], v64
	ds_read_b128 v[70:73], v83 offset:18432
	ds_read_b128 v[74:77], v64 offset:32
	ds_read_b128 v[78:81], v83 offset:18464
	ds_read_b128 v[86:89], v83 offset:23040
	ds_read_b128 v[90:93], v83 offset:23072
	v_mfma_f32_32x32x16_bf16 v[0:15], v[114:117], v[110:113], v[0:15]
	s_waitcnt lgkmcnt(4)
	v_mfma_f32_32x32x16_bf16 v[48:63], v[66:69], v[70:73], v[48:63]
	s_waitcnt lgkmcnt(1)
	v_mfma_f32_32x32x16_bf16 v[32:47], v[66:69], v[86:89], v[32:47]
	ds_read_b128 v[66:69], v64 offset:4608
	ds_read_b128 v[98:101], v64 offset:4640
	s_waitcnt lgkmcnt(1)
	v_mfma_f32_32x32x16_bf16 v[16:31], v[66:69], v[70:73], v[16:31]
	v_mfma_f32_32x32x16_bf16 v[0:15], v[66:69], v[86:89], v[0:15]
	v_mfma_f32_32x32x16_bf16 v[48:63], v[74:77], v[78:81], v[48:63]
	v_mfma_f32_32x32x16_bf16 v[32:47], v[74:77], v[90:93], v[32:47]
	s_waitcnt lgkmcnt(0)
	v_mfma_f32_32x32x16_bf16 v[16:31], v[98:101], v[78:81], v[16:31]
	ds_read_b128 v[66:69], v64 offset:64
	ds_read_b128 v[70:73], v83 offset:18496
	ds_read_b128 v[74:77], v64 offset:96
	ds_read_b128 v[78:81], v83 offset:18528
	v_mfma_f32_32x32x16_bf16 v[0:15], v[98:101], v[90:93], v[0:15]
	ds_read_b128 v[86:89], v83 offset:23104
	ds_read_b128 v[90:93], v83 offset:23136
	s_waitcnt lgkmcnt(4)
	v_mfma_f32_32x32x16_bf16 v[48:63], v[66:69], v[70:73], v[48:63]
	s_waitcnt lgkmcnt(1)
	v_mfma_f32_32x32x16_bf16 v[32:47], v[66:69], v[86:89], v[32:47]
	ds_read_b128 v[66:69], v64 offset:4672
	ds_read_b128 v[98:101], v64 offset:4704
	s_waitcnt lgkmcnt(0)
	s_barrier
; #define PW(T, off) ((T*)(lndp(p.ws) + (off)))
; DEVI float bf2f(bf16 h) { return __uint_as_float(((unsigned)h) << 16); }
; DEVI int accrow(int r, int lane) { return (r & 3) + 8 * (r >> 2) + 4 * (lane >> 5); }
; template <int EPI>
; DEVI void gemm_epi(const Params& p, const GJob& jb, f32x16 (&acc)[2][2], int rbase, int cbase, int lane) {
;     ...
; #pragma unroll
;   for (int i = 0; i < 2; ++i) {
; #pragma unroll
;     for (int r = 0; r < 16; ++r) {
;       const int row = rbase + i * 32 + accrow(r, lane);
;       if (row < M) {
; #pragma unroll
;         for (int j = 0; j < 2; ++j) {
;           const int col = cbase + j * 32 + (lane & 31);
;           const float v = acc[i][j][r];
;           if (EPI == EPI_SSD_IN) {
;             if (col < 2048) ((bf16*)(ar + S_ZB))[(size_t)row * 2048 + col] = f2bf(v);
;             else if (col < 6144) ((bf16*)(ar + S_XBC))[(size_t)row * 4096 + col - 2048] = f2bf(v);
;             else if (col < 6176) ((float*)(ar + S_DTRAW))[(size_t)row * 32 + col - 6144] = v;
;           } else if (EPI == EPI_RESID) {
;             PW(bf16, W_Z)[(size_t)row * 1024 + col] = f2bf(ALPHA * bf2f(PW(bf16, W_Xb)[(size_t)row * 1024 + col]) + v);
;     ...
;   for (int kt = 0; kt < nk; kt += 2) {
;     if (kt + 2 < nk) G_LOAD(ra0, rb0, kt + 2);
;     if (kt + 1 < nk) G_STORE(ra1, rb1, As1, Bs1);
;     G_COMPUTE(As, Bs);
;     __syncthreads();
;     if (kt + 1 < nk) {
;       if (kt + 3 < nk) G_LOAD(ra1, rb1, kt + 3);
;       if (kt + 2 < nk) G_STORE(ra0, rb0, As, Bs);
;       G_COMPUTE(As1, Bs1);
;       __syncthreads();
;     }
;   }
	v_mfma_f32_32x32x16_bf16 v[16:31], v[66:69], v[70:73], v[16:31]
	v_mfma_f32_32x32x16_bf16 v[48:63], v[74:77], v[78:81], v[48:63]
	v_mfma_f32_32x32x16_bf16 v[32:47], v[74:77], v[90:93], v[32:47]
	v_mfma_f32_32x32x16_bf16 v[0:15], v[66:69], v[86:89], v[0:15]
	v_mfma_f32_32x32x16_bf16 v[16:31], v[98:101], v[78:81], v[16:31]
	ds_read_b128 v[66:69], v64 offset:36864
	ds_read_b128 v[70:73], v83 offset:55296
	ds_read_b128 v[74:77], v83 offset:55328
	ds_read_b128 v[78:81], v64 offset:36896
	ds_read_b128 v[86:89], v83 offset:59904
	s_waitcnt lgkmcnt(3)
	v_mfma_f32_32x32x16_bf16 v[48:63], v[66:69], v[70:73], v[48:63]
	s_waitcnt lgkmcnt(0)
	v_mfma_f32_32x32x16_bf16 v[32:47], v[66:69], v[86:89], v[32:47]
	ds_read_b128 v[66:69], v64 offset:41472
	v_mfma_f32_32x32x16_bf16 v[0:15], v[98:101], v[90:93], v[0:15]
	s_waitcnt lgkmcnt(0)
	v_mfma_f32_32x32x16_bf16 v[16:31], v[66:69], v[70:73], v[16:31]
	ds_read_b128 v[70:73], v64 offset:41504
	v_mfma_f32_32x32x16_bf16 v[0:15], v[66:69], v[86:89], v[0:15]
	ds_read_b128 v[66:69], v83 offset:59936
	v_mfma_f32_32x32x16_bf16 v[48:63], v[78:81], v[74:77], v[48:63]
	s_waitcnt lgkmcnt(0)
	v_mfma_f32_32x32x16_bf16 v[32:47], v[78:81], v[66:69], v[32:47]
	v_mfma_f32_32x32x16_bf16 v[16:31], v[70:73], v[74:77], v[16:31]
	v_mfma_f32_32x32x16_bf16 v[0:15], v[70:73], v[66:69], v[0:15]
	ds_read_b128 v[66:69], v64 offset:36928
	ds_read_b128 v[70:73], v83 offset:55360
	ds_read_b128 v[74:77], v83 offset:59968
	s_waitcnt lgkmcnt(1)
	v_mfma_f32_32x32x16_bf16 v[48:63], v[66:69], v[70:73], v[48:63]
	s_waitcnt lgkmcnt(0)
	v_mfma_f32_32x32x16_bf16 v[32:47], v[66:69], v[74:77], v[32:47]
	ds_read_b128 v[66:69], v64 offset:41536
	s_waitcnt lgkmcnt(0)
	v_mfma_f32_32x32x16_bf16 v[16:31], v[66:69], v[70:73], v[16:31]
	ds_read_b128 v[78:81], v83 offset:60000
	ds_read_b128 v[86:89], v83 offset:55392
	ds_read_b128 v[90:93], v64 offset:41568
	ds_read_b128 v[70:73], v64 offset:36960
	s_waitcnt lgkmcnt(0)
	s_barrier
	s_ashr_i32 s15, s14, 31
	s_lshl_b64 s[14:15], s[14:15], 3
	v_mfma_f32_32x32x16_bf16 v[0:15], v[66:69], v[74:77], v[0:15]
	s_add_u32 s14, s0, s14
	s_addc_u32 s15, s1, s15
	s_load_dwordx2 s[14:15], s[14:15], 0x0
	s_waitcnt lgkmcnt(0)
	s_mov_b32 s14, 26
	s_ashr_i32 s15, s14, 31
	v_mfma_f32_32x32x16_bf16 v[48:63], v[70:73], v[86:89], v[48:63]
	s_lshl_b64 s[14:15], s[14:15], 3
	s_add_u32 s14, s0, s14
	s_addc_u32 s15, s1, s15
	s_load_dwordx2 s[14:15], s[14:15], 0x0
	v_or_b32_e32 v66, s2, v65
	s_waitcnt lgkmcnt(0)
	v_or_b32_e32 v64, 32, v66
	v_mfma_f32_32x32x16_bf16 v[32:47], v[70:73], v[78:81], v[32:47]
	v_lshrrev_b32_e32 v72, 3, v84
	v_add_u32_e32 v70, s3, v85
	v_and_b32_e32 v71, 4, v72
	v_or_b32_e32 v68, v70, v71
	s_mov_b64 s[14:15], s[74:75]
	v_cmp_gt_i32_e32 vcc, s90, v68
	v_ashrrev_i32_e32 v67, 31, v66
	v_mfma_f32_32x32x16_bf16 v[16:31], v[90:93], v[86:89], v[16:31]
	v_ashrrev_i32_e32 v65, 31, v64
	v_mfma_f32_32x32x16_bf16 v[0:15], v[90:93], v[78:81], v[0:15]
	s_add_u32 s94, s74, 0xf724000
	s_addc_u32 s95, s75, 0
	s_add_u32 s96, s74, 0xb5a4000
	s_addc_u32 s97, s75, 0
	v_lshlrev_b32_e32 v115, 1, v66
	v_lshl_add_u32 v116, v68, 11, v115
	v_mov_b32_e32 v98, v116
	v_add_u32_e32 v99, 0x1000, v116
	v_add_u32_e32 v100, 0x4000, v116
	v_add_u32_e32 v101, 0x5000, v116
	v_add_u32_e32 v102, 0x8000, v116
	v_add_u32_e32 v103, 0x9000, v116
	v_add_u32_e32 v104, 0xc000, v116
	v_add_u32_e32 v105, 0xd000, v116
	v_add_u32_e32 v106, 0x10000, v116
	v_add_u32_e32 v107, 0x11000, v116
	v_add_u32_e32 v108, 0x14000, v116
	v_add_u32_e32 v109, 0x15000, v116
	v_add_u32_e32 v110, 0x18000, v116
	v_add_u32_e32 v111, 0x19000, v116
	v_add_u32_e32 v112, 0x1c000, v116
	v_add_u32_e32 v113, 0x1d000, v116
	global_load_ushort v64, v98, s[94:95]
	global_load_ushort v65, v98, s[94:95] offset:64
	global_load_ushort v66, v98, s[94:95] offset:2048
	global_load_ushort v67, v98, s[94:95] offset:2112
	global_load_ushort v68, v99, s[94:95]
	global_load_ushort v69, v99, s[94:95] offset:64
	global_load_ushort v70, v99, s[94:95] offset:2048
	global_load_ushort v71, v99, s[94:95] offset:2112
	global_load_ushort v72, v100, s[94:95]
	global_load_ushort v73, v100, s[94:95] offset:64
	global_load_ushort v74, v100, s[94:95] offset:2048
	global_load_ushort v75, v100, s[94:95] offset:2112
	global_load_ushort v76, v101, s[94:95]
	global_load_ushort v77, v101, s[94:95] offset:64
	global_load_ushort v78, v101, s[94:95] offset:2048
	global_load_ushort v79, v101, s[94:95] offset:2112
	global_load_ushort v80, v102, s[94:95]
	global_load_ushort v81, v102, s[94:95] offset:64
	global_load_ushort v82, v102, s[94:95] offset:2048
	global_load_ushort v83, v102, s[94:95] offset:2112
	global_load_ushort v84, v103, s[94:95]
	global_load_ushort v85, v103, s[94:95] offset:64
	global_load_ushort v86, v103, s[94:95] offset:2048
	global_load_ushort v87, v103, s[94:95] offset:2112
	global_load_ushort v88, v104, s[94:95]
	global_load_ushort v89, v104, s[94:95] offset:64
	global_load_ushort v90, v104, s[94:95] offset:2048
	global_load_ushort v91, v104, s[94:95] offset:2112
	global_load_ushort v92, v105, s[94:95]
	global_load_ushort v93, v105, s[94:95] offset:64
	global_load_ushort v94, v105, s[94:95] offset:2048
	global_load_ushort v95, v105, s[94:95] offset:2112
	s_waitcnt vmcnt(31)
	v_lshlrev_b32_e32 v64, 16, v64
	v_fmamk_f32 v48, v64, 0x3fd744fd, v48
	v_cvt_pk_bf16_f32 v48, v48, s0
	s_waitcnt vmcnt(30)
	v_lshlrev_b32_e32 v65, 16, v65
	v_fmamk_f32 v32, v65, 0x3fd744fd, v32
	v_cvt_pk_bf16_f32 v32, v32, s0
	s_waitcnt vmcnt(29)
	v_lshlrev_b32_e32 v66, 16, v66
	v_fmamk_f32 v49, v66, 0x3fd744fd, v49
	v_cvt_pk_bf16_f32 v49, v49, s0
	s_waitcnt vmcnt(28)
	v_lshlrev_b32_e32 v67, 16, v67
	v_fmamk_f32 v33, v67, 0x3fd744fd, v33
	v_cvt_pk_bf16_f32 v33, v33, s0
	s_waitcnt vmcnt(27)
; #define PW(T, off) ((T*)(lndp(p.ws) + (off)))
; DEVI float bf2f(bf16 h) { return __uint_as_float(((unsigned)h) << 16); }
; DEVI int accrow(int r, int lane) { return (r & 3) + 8 * (r >> 2) + 4 * (lane >> 5); }
; template <int EPI>
; DEVI void gemm_epi(const Params& p, const GJob& jb, f32x16 (&acc)[2][2], int rbase, int cbase, int lane) {
;     ...
; #pragma unroll
;   for (int i = 0; i < 2; ++i) {
; #pragma unroll
;     for (int r = 0; r < 16; ++r) {
;       const int row = rbase + i * 32 + accrow(r, lane);
;       if (row < M) {
; #pragma unroll
;         for (int j = 0; j < 2; ++j) {
;           const int col = cbase + j * 32 + (lane & 31);
;           const float v = acc[i][j][r];
;           if (EPI == EPI_SSD_IN) {
;             if (col < 2048) ((bf16*)(ar + S_ZB))[(size_t)row * 2048 + col] = f2bf(v);
;             else if (col < 6144) ((bf16*)(ar + S_XBC))[(size_t)row * 4096 + col - 2048] = f2bf(v);
;             else if (col < 6176) ((float*)(ar + S_DTRAW))[(size_t)row * 32 + col - 6144] = v;
;           } else if (EPI == EPI_RESID) {
;             PW(bf16, W_Z)[(size_t)row * 1024 + col] = f2bf(ALPHA * bf2f(PW(bf16, W_Xb)[(size_t)row * 1024 + col]) + v);
	v_lshlrev_b32_e32 v68, 16, v68
	v_fmamk_f32 v50, v68, 0x3fd744fd, v50
	v_cvt_pk_bf16_f32 v50, v50, s0
	s_waitcnt vmcnt(26)
	v_lshlrev_b32_e32 v69, 16, v69
	v_fmamk_f32 v34, v69, 0x3fd744fd, v34
	v_cvt_pk_bf16_f32 v34, v34, s0
	s_waitcnt vmcnt(25)
	v_lshlrev_b32_e32 v70, 16, v70
	v_fmamk_f32 v51, v70, 0x3fd744fd, v51
	v_cvt_pk_bf16_f32 v51, v51, s0
	s_waitcnt vmcnt(24)
	v_lshlrev_b32_e32 v71, 16, v71
	v_fmamk_f32 v35, v71, 0x3fd744fd, v35
	v_cvt_pk_bf16_f32 v35, v35, s0
	s_waitcnt vmcnt(23)
	v_lshlrev_b32_e32 v72, 16, v72
	v_fmamk_f32 v52, v72, 0x3fd744fd, v52
	v_cvt_pk_bf16_f32 v52, v52, s0
	s_waitcnt vmcnt(22)
	v_lshlrev_b32_e32 v73, 16, v73
	v_fmamk_f32 v36, v73, 0x3fd744fd, v36
	v_cvt_pk_bf16_f32 v36, v36, s0
	s_waitcnt vmcnt(21)
	v_lshlrev_b32_e32 v74, 16, v74
	v_fmamk_f32 v53, v74, 0x3fd744fd, v53
	v_cvt_pk_bf16_f32 v53, v53, s0
	s_waitcnt vmcnt(20)
	v_lshlrev_b32_e32 v75, 16, v75
	v_fmamk_f32 v37, v75, 0x3fd744fd, v37
	v_cvt_pk_bf16_f32 v37, v37, s0
	s_waitcnt vmcnt(19)
	v_lshlrev_b32_e32 v76, 16, v76
	v_fmamk_f32 v54, v76, 0x3fd744fd, v54
	v_cvt_pk_bf16_f32 v54, v54, s0
	s_waitcnt vmcnt(18)
	v_lshlrev_b32_e32 v77, 16, v77
	v_fmamk_f32 v38, v77, 0x3fd744fd, v38
	v_cvt_pk_bf16_f32 v38, v38, s0
	s_waitcnt vmcnt(17)
	v_lshlrev_b32_e32 v78, 16, v78
	v_fmamk_f32 v55, v78, 0x3fd744fd, v55
	v_cvt_pk_bf16_f32 v55, v55, s0
	s_waitcnt vmcnt(16)
	v_lshlrev_b32_e32 v79, 16, v79
	v_fmamk_f32 v39, v79, 0x3fd744fd, v39
	v_cvt_pk_bf16_f32 v39, v39, s0
	s_waitcnt vmcnt(15)
	v_lshlrev_b32_e32 v80, 16, v80
	v_fmamk_f32 v56, v80, 0x3fd744fd, v56
	v_cvt_pk_bf16_f32 v56, v56, s0
	s_waitcnt vmcnt(14)
	v_lshlrev_b32_e32 v81, 16, v81
	v_fmamk_f32 v40, v81, 0x3fd744fd, v40
	v_cvt_pk_bf16_f32 v40, v40, s0
	s_waitcnt vmcnt(13)
	v_lshlrev_b32_e32 v82, 16, v82
	v_fmamk_f32 v57, v82, 0x3fd744fd, v57
	v_cvt_pk_bf16_f32 v57, v57, s0
	s_waitcnt vmcnt(12)
	v_lshlrev_b32_e32 v83, 16, v83
	v_fmamk_f32 v41, v83, 0x3fd744fd, v41
	v_cvt_pk_bf16_f32 v41, v41, s0
	s_waitcnt vmcnt(11)
	v_lshlrev_b32_e32 v84, 16, v84
	v_fmamk_f32 v58, v84, 0x3fd744fd, v58
	v_cvt_pk_bf16_f32 v58, v58, s0
	s_waitcnt vmcnt(10)
	v_lshlrev_b32_e32 v85, 16, v85
	v_fmamk_f32 v42, v85, 0x3fd744fd, v42
	v_cvt_pk_bf16_f32 v42, v42, s0
	s_waitcnt vmcnt(9)
	v_lshlrev_b32_e32 v86, 16, v86
	v_fmamk_f32 v59, v86, 0x3fd744fd, v59
	v_cvt_pk_bf16_f32 v59, v59, s0
	s_waitcnt vmcnt(8)
	v_lshlrev_b32_e32 v87, 16, v87
	v_fmamk_f32 v43, v87, 0x3fd744fd, v43
	v_cvt_pk_bf16_f32 v43, v43, s0
	s_waitcnt vmcnt(7)
	v_lshlrev_b32_e32 v88, 16, v88
	v_fmamk_f32 v60, v88, 0x3fd744fd, v60
	v_cvt_pk_bf16_f32 v60, v60, s0
	s_waitcnt vmcnt(6)
	v_lshlrev_b32_e32 v89, 16, v89
	v_fmamk_f32 v44, v89, 0x3fd744fd, v44
	v_cvt_pk_bf16_f32 v44, v44, s0
	s_waitcnt vmcnt(5)
	v_lshlrev_b32_e32 v90, 16, v90
	v_fmamk_f32 v61, v90, 0x3fd744fd, v61
	v_cvt_pk_bf16_f32 v61, v61, s0
	s_waitcnt vmcnt(4)
	v_lshlrev_b32_e32 v91, 16, v91
	v_fmamk_f32 v45, v91, 0x3fd744fd, v45
	v_cvt_pk_bf16_f32 v45, v45, s0
	s_waitcnt vmcnt(3)
	v_lshlrev_b32_e32 v92, 16, v92
	v_fmamk_f32 v62, v92, 0x3fd744fd, v62
	v_cvt_pk_bf16_f32 v62, v62, s0
	s_waitcnt vmcnt(2)
	v_lshlrev_b32_e32 v93, 16, v93
	v_fmamk_f32 v46, v93, 0x3fd744fd, v46
	v_cvt_pk_bf16_f32 v46, v46, s0
	s_waitcnt vmcnt(1)
	v_lshlrev_b32_e32 v94, 16, v94
	v_fmamk_f32 v63, v94, 0x3fd744fd, v63
	v_cvt_pk_bf16_f32 v63, v63, s0
	s_waitcnt vmcnt(0)
	v_lshlrev_b32_e32 v95, 16, v95
	v_fmamk_f32 v47, v95, 0x3fd744fd, v47
	v_cvt_pk_bf16_f32 v47, v47, s0
	global_store_short v98, v48, s[96:97]
	global_store_short v98, v32, s[96:97] offset:64
	global_store_short v98, v49, s[96:97] offset:2048
	global_store_short v98, v33, s[96:97] offset:2112
	global_store_short v99, v50, s[96:97]
	global_store_short v99, v34, s[96:97] offset:64
	global_store_short v99, v51, s[96:97] offset:2048
	global_store_short v99, v35, s[96:97] offset:2112
	global_store_short v100, v52, s[96:97]
	global_store_short v100, v36, s[96:97] offset:64
	global_store_short v100, v53, s[96:97] offset:2048
	global_store_short v100, v37, s[96:97] offset:2112
	global_store_short v101, v54, s[96:97]
	global_store_short v101, v38, s[96:97] offset:64
	global_store_short v101, v55, s[96:97] offset:2048
	global_store_short v101, v39, s[96:97] offset:2112
	global_store_short v102, v56, s[96:97]
	global_store_short v102, v40, s[96:97] offset:64
	global_store_short v102, v57, s[96:97] offset:2048
	global_store_short v102, v41, s[96:97] offset:2112
	global_store_short v103, v58, s[96:97]
	global_store_short v103, v42, s[96:97] offset:64
	global_store_short v103, v59, s[96:97] offset:2048
	global_store_short v103, v43, s[96:97] offset:2112
	global_store_short v104, v60, s[96:97]
	global_store_short v104, v44, s[96:97] offset:64
	global_store_short v104, v61, s[96:97] offset:2048
	global_store_short v104, v45, s[96:97] offset:2112
	global_store_short v105, v62, s[96:97]
	global_store_short v105, v46, s[96:97] offset:64
	global_store_short v105, v63, s[96:97] offset:2048
	global_store_short v105, v47, s[96:97] offset:2112
	global_load_ushort v64, v106, s[94:95]
	global_load_ushort v65, v106, s[94:95] offset:64
	global_load_ushort v66, v106, s[94:95] offset:2048
	global_load_ushort v67, v106, s[94:95] offset:2112
	global_load_ushort v68, v107, s[94:95]
	global_load_ushort v69, v107, s[94:95] offset:64
	global_load_ushort v70, v107, s[94:95] offset:2048
	global_load_ushort v71, v107, s[94:95] offset:2112
	global_load_ushort v72, v108, s[94:95]
	global_load_ushort v73, v108, s[94:95] offset:64
	global_load_ushort v74, v108, s[94:95] offset:2048
	global_load_ushort v75, v108, s[94:95] offset:2112
	global_load_ushort v76, v109, s[94:95]
	global_load_ushort v77, v109, s[94:95] offset:64
	global_load_ushort v78, v109, s[94:95] offset:2048
	global_load_ushort v79, v109, s[94:95] offset:2112
	global_load_ushort v80, v110, s[94:95]
	global_load_ushort v81, v110, s[94:95] offset:64
	global_load_ushort v82, v110, s[94:95] offset:2048
	global_load_ushort v83, v110, s[94:95] offset:2112
	global_load_ushort v84, v111, s[94:95]
	global_load_ushort v85, v111, s[94:95] offset:64
	global_load_ushort v86, v111, s[94:95] offset:2048
	global_load_ushort v87, v111, s[94:95] offset:2112
	global_load_ushort v88, v112, s[94:95]
	global_load_ushort v89, v112, s[94:95] offset:64
	global_load_ushort v90, v112, s[94:95] offset:2048
	global_load_ushort v91, v112, s[94:95] offset:2112
	global_load_ushort v92, v113, s[94:95]
	global_load_ushort v93, v113, s[94:95] offset:64
	global_load_ushort v94, v113, s[94:95] offset:2048
	global_load_ushort v95, v113, s[94:95] offset:2112
	s_waitcnt vmcnt(31)
; #define PW(T, off) ((T*)(lndp(p.ws) + (off)))
; DEVI float bf2f(bf16 h) { return __uint_as_float(((unsigned)h) << 16); }
; DEVI int accrow(int r, int lane) { return (r & 3) + 8 * (r >> 2) + 4 * (lane >> 5); }
; template <int EPI>
; DEVI void gemm_epi(const Params& p, const GJob& jb, f32x16 (&acc)[2][2], int rbase, int cbase, int lane) {
;     ...
; #pragma unroll
;   for (int i = 0; i < 2; ++i) {
; #pragma unroll
;     for (int r = 0; r < 16; ++r) {
;       const int row = rbase + i * 32 + accrow(r, lane);
;       if (row < M) {
; #pragma unroll
;         for (int j = 0; j < 2; ++j) {
;           const int col = cbase + j * 32 + (lane & 31);
;           const float v = acc[i][j][r];
;           if (EPI == EPI_SSD_IN) {
;             if (col < 2048) ((bf16*)(ar + S_ZB))[(size_t)row * 2048 + col] = f2bf(v);
;             else if (col < 6144) ((bf16*)(ar + S_XBC))[(size_t)row * 4096 + col - 2048] = f2bf(v);
;             else if (col < 6176) ((float*)(ar + S_DTRAW))[(size_t)row * 32 + col - 6144] = v;
;           } else if (EPI == EPI_RESID) {
;             PW(bf16, W_Z)[(size_t)row * 1024 + col] = f2bf(ALPHA * bf2f(PW(bf16, W_Xb)[(size_t)row * 1024 + col]) + v);
	v_lshlrev_b32_e32 v64, 16, v64
	v_fmamk_f32 v16, v64, 0x3fd744fd, v16
	v_cvt_pk_bf16_f32 v16, v16, s0
	s_waitcnt vmcnt(30)
	v_lshlrev_b32_e32 v65, 16, v65
	v_fmamk_f32 v0, v65, 0x3fd744fd, v0
	v_cvt_pk_bf16_f32 v0, v0, s0
	s_waitcnt vmcnt(29)
	v_lshlrev_b32_e32 v66, 16, v66
	v_fmamk_f32 v17, v66, 0x3fd744fd, v17
	v_cvt_pk_bf16_f32 v17, v17, s0
	s_waitcnt vmcnt(28)
	v_lshlrev_b32_e32 v67, 16, v67
	v_fmamk_f32 v1, v67, 0x3fd744fd, v1
	v_cvt_pk_bf16_f32 v1, v1, s0
	s_waitcnt vmcnt(27)
	v_lshlrev_b32_e32 v68, 16, v68
	v_fmamk_f32 v18, v68, 0x3fd744fd, v18
	v_cvt_pk_bf16_f32 v18, v18, s0
	s_waitcnt vmcnt(26)
	v_lshlrev_b32_e32 v69, 16, v69
	v_fmamk_f32 v2, v69, 0x3fd744fd, v2
	v_cvt_pk_bf16_f32 v2, v2, s0
	s_waitcnt vmcnt(25)
	v_lshlrev_b32_e32 v70, 16, v70
	v_fmamk_f32 v19, v70, 0x3fd744fd, v19
	v_cvt_pk_bf16_f32 v19, v19, s0
	s_waitcnt vmcnt(24)
	v_lshlrev_b32_e32 v71, 16, v71
	v_fmamk_f32 v3, v71, 0x3fd744fd, v3
	v_cvt_pk_bf16_f32 v3, v3, s0
	s_waitcnt vmcnt(23)
	v_lshlrev_b32_e32 v72, 16, v72
	v_fmamk_f32 v20, v72, 0x3fd744fd, v20
	v_cvt_pk_bf16_f32 v20, v20, s0
	s_waitcnt vmcnt(22)
	v_lshlrev_b32_e32 v73, 16, v73
	v_fmamk_f32 v4, v73, 0x3fd744fd, v4
	v_cvt_pk_bf16_f32 v4, v4, s0
	s_waitcnt vmcnt(21)
	v_lshlrev_b32_e32 v74, 16, v74
	v_fmamk_f32 v21, v74, 0x3fd744fd, v21
	v_cvt_pk_bf16_f32 v21, v21, s0
	s_waitcnt vmcnt(20)
	v_lshlrev_b32_e32 v75, 16, v75
	v_fmamk_f32 v5, v75, 0x3fd744fd, v5
	v_cvt_pk_bf16_f32 v5, v5, s0
	s_waitcnt vmcnt(19)
	v_lshlrev_b32_e32 v76, 16, v76
	v_fmamk_f32 v22, v76, 0x3fd744fd, v22
	v_cvt_pk_bf16_f32 v22, v22, s0
	s_waitcnt vmcnt(18)
	v_lshlrev_b32_e32 v77, 16, v77
	v_fmamk_f32 v6, v77, 0x3fd744fd, v6
	v_cvt_pk_bf16_f32 v6, v6, s0
	s_waitcnt vmcnt(17)
	v_lshlrev_b32_e32 v78, 16, v78
	v_fmamk_f32 v23, v78, 0x3fd744fd, v23
	v_cvt_pk_bf16_f32 v23, v23, s0
	s_waitcnt vmcnt(16)
	v_lshlrev_b32_e32 v79, 16, v79
	v_fmamk_f32 v7, v79, 0x3fd744fd, v7
	v_cvt_pk_bf16_f32 v7, v7, s0
	s_waitcnt vmcnt(15)
	v_lshlrev_b32_e32 v80, 16, v80
	v_fmamk_f32 v24, v80, 0x3fd744fd, v24
	v_cvt_pk_bf16_f32 v24, v24, s0
	s_waitcnt vmcnt(14)
	v_lshlrev_b32_e32 v81, 16, v81
	v_fmamk_f32 v8, v81, 0x3fd744fd, v8
	v_cvt_pk_bf16_f32 v8, v8, s0
	s_waitcnt vmcnt(13)
	v_lshlrev_b32_e32 v82, 16, v82
	v_fmamk_f32 v25, v82, 0x3fd744fd, v25
	v_cvt_pk_bf16_f32 v25, v25, s0
	s_waitcnt vmcnt(12)
	v_lshlrev_b32_e32 v83, 16, v83
	v_fmamk_f32 v9, v83, 0x3fd744fd, v9
	v_cvt_pk_bf16_f32 v9, v9, s0
	s_waitcnt vmcnt(11)
	v_lshlrev_b32_e32 v84, 16, v84
	v_fmamk_f32 v26, v84, 0x3fd744fd, v26
	v_cvt_pk_bf16_f32 v26, v26, s0
	s_waitcnt vmcnt(10)
	v_lshlrev_b32_e32 v85, 16, v85
	v_fmamk_f32 v10, v85, 0x3fd744fd, v10
	v_cvt_pk_bf16_f32 v10, v10, s0
	s_waitcnt vmcnt(9)
	v_lshlrev_b32_e32 v86, 16, v86
	v_fmamk_f32 v27, v86, 0x3fd744fd, v27
	v_cvt_pk_bf16_f32 v27, v27, s0
	s_waitcnt vmcnt(8)
	v_lshlrev_b32_e32 v87, 16, v87
	v_fmamk_f32 v11, v87, 0x3fd744fd, v11
	v_cvt_pk_bf16_f32 v11, v11, s0
	s_waitcnt vmcnt(7)
	v_lshlrev_b32_e32 v88, 16, v88
	v_fmamk_f32 v28, v88, 0x3fd744fd, v28
	v_cvt_pk_bf16_f32 v28, v28, s0
	s_waitcnt vmcnt(6)
	v_lshlrev_b32_e32 v89, 16, v89
	v_fmamk_f32 v12, v89, 0x3fd744fd, v12
	v_cvt_pk_bf16_f32 v12, v12, s0
	s_waitcnt vmcnt(5)
	v_lshlrev_b32_e32 v90, 16, v90
	v_fmamk_f32 v29, v90, 0x3fd744fd, v29
	v_cvt_pk_bf16_f32 v29, v29, s0
	s_waitcnt vmcnt(4)
	v_lshlrev_b32_e32 v91, 16, v91
	v_fmamk_f32 v13, v91, 0x3fd744fd, v13
	v_cvt_pk_bf16_f32 v13, v13, s0
	s_waitcnt vmcnt(3)
	v_lshlrev_b32_e32 v92, 16, v92
	v_fmamk_f32 v30, v92, 0x3fd744fd, v30
	v_cvt_pk_bf16_f32 v30, v30, s0
	s_waitcnt vmcnt(2)
	v_lshlrev_b32_e32 v93, 16, v93
	v_fmamk_f32 v14, v93, 0x3fd744fd, v14
	v_cvt_pk_bf16_f32 v14, v14, s0
	s_waitcnt vmcnt(1)
	v_lshlrev_b32_e32 v94, 16, v94
	v_fmamk_f32 v31, v94, 0x3fd744fd, v31
	v_cvt_pk_bf16_f32 v31, v31, s0
	s_waitcnt vmcnt(0)
	v_lshlrev_b32_e32 v95, 16, v95
	v_fmamk_f32 v15, v95, 0x3fd744fd, v15
	v_cvt_pk_bf16_f32 v15, v15, s0
	global_store_short v106, v16, s[96:97]
	global_store_short v106, v0, s[96:97] offset:64
	global_store_short v106, v17, s[96:97] offset:2048
	global_store_short v106, v1, s[96:97] offset:2112
	global_store_short v107, v18, s[96:97]
	global_store_short v107, v2, s[96:97] offset:64
	global_store_short v107, v19, s[96:97] offset:2048
	global_store_short v107, v3, s[96:97] offset:2112
	global_store_short v108, v20, s[96:97]
	global_store_short v108, v4, s[96:97] offset:64
	global_store_short v108, v21, s[96:97] offset:2048
	global_store_short v108, v5, s[96:97] offset:2112
	global_store_short v109, v22, s[96:97]
	global_store_short v109, v6, s[96:97] offset:64
	global_store_short v109, v23, s[96:97] offset:2048
	global_store_short v109, v7, s[96:97] offset:2112
	global_store_short v110, v24, s[96:97]
	global_store_short v110, v8, s[96:97] offset:64
	global_store_short v110, v25, s[96:97] offset:2048
	global_store_short v110, v9, s[96:97] offset:2112
	global_store_short v111, v26, s[96:97]
	global_store_short v111, v10, s[96:97] offset:64
	global_store_short v111, v27, s[96:97] offset:2048
	global_store_short v111, v11, s[96:97] offset:2112
	global_store_short v112, v28, s[96:97]
	global_store_short v112, v12, s[96:97] offset:64
	global_store_short v112, v29, s[96:97] offset:2048
	global_store_short v112, v13, s[96:97] offset:2112
	global_store_short v113, v30, s[96:97]
	global_store_short v113, v14, s[96:97] offset:64
	global_store_short v113, v31, s[96:97] offset:2048
	global_store_short v113, v15, s[96:97] offset:2112
	s_mov_b64 s[2:3], exec
	s_branch .LBB0_19

; DEVI int TID() { int t = threadIdx.x; asm volatile("" : "+v"(t)); return t; }
;   bf16* As = (bf16*)smem;
;   bf16* Bs = As + 128 * 72;
;   const int tid = TID(), lane = tid & 63, wave = tid >> 6, wm = wave >> 1, wn = wave & 1;
;   f32x16 acc[2][2];
; #pragma unroll
;   for (int i = 0; i < 2; ++i)
; #pragma unroll
;     for (int j = 0; j < 2; ++j) acc[i][j] = zero16();
;   const int lrow = tid >> 3, lkc = (tid & 7) * 8;
;   const bf16* Ag = jb.A + (size_t)max(m0 + lrow, 0) * jb.lda + lkc;
;   const bf16* Ag1 = jb.A + (ptrdiff_t)(m0 + lrow) * jb.lda + lkc;
;   const bf16* Bg = jb.Bt + (size_t)(n0 + lrow) * jb.K + lkc;
;   const size_t astep = (size_t)32 * jb.lda, bstep = (size_t)32 * jb.K;
;   if (kt1 < 0) kt1 = jb.K >> 6;
;   const int nk = kt1 - kt0;
;   Ag += (size_t)kt0 * 64; Ag1 += (size_t)kt0 * 64; Bg += (size_t)kt0 * 64;
;   u32x4 ra0[4], rb0[4], ra1[4], rb1[4];
;     ...
;   bf16* As1 = As + 2 * 128 * 72;
;   bf16* Bs1 = As1 + 128 * 72;
;   G_LOAD(ra0, rb0, 0);
;   if (nk > 1) G_LOAD(ra1, rb1, 1);
;   G_STORE(ra0, rb0, As, Bs);
;   __syncthreads();
;   for (int kt = 0; kt < nk; kt += 2) {
;     if (kt + 2 < nk) G_LOAD(ra0, rb0, kt + 2);
;     if (kt + 1 < nk) G_STORE(ra1, rb1, As1, Bs1);
;     G_COMPUTE(As, Bs);
;     __syncthreads();
;     if (kt + 1 < nk) {
;       if (kt + 3 < nk) G_LOAD(ra1, rb1, kt + 3);
;       if (kt + 2 < nk) G_STORE(ra0, rb0, As, Bs);
;       G_COMPUTE(As1, Bs1);
;       __syncthreads();
;     }
;   }
.LBB0_1317:
	s_ashr_i32 s2, s4, 31
	s_lshr_b32 s2, s2, 25
	s_add_i32 s2, s4, s2
	s_and_b32 s3, s2, 0xffffff80
	s_sub_i32 s3, s4, s3
	s_ashr_i32 s5, s3, 31
	s_lshr_b32 s5, s5, 28
	s_add_i32 s5, s3, s5
	s_and_b32 s14, s5, 0x1fffff0
	s_sub_i32 s3, s3, s14
	s_lshl_b32 s2, s2, 4
	s_and_b32 s2, s2, 0xfffff800
	s_lshl_b32 s3, s3, 7
	s_waitcnt vmcnt(2)
	v_mov_b32_e32 v84, v208
	s_add_i32 s3, s3, s2
	s_lshl_b32 s2, s5, 3
	v_ashrrev_i32_e32 v82, 3, v84
	v_add_u32_e32 v0, s3, v82
	v_max_i32_e32 v96, 0, v0
	v_lshlrev_b32_e32 v1, 4, v84
	v_lshlrev_b64 v[2:3], 11, v[96:97]
	v_and_b32_e32 v96, 0x70, v1
	v_ashrrev_i32_e32 v1, 31, v0
	v_lshlrev_b64 v[0:1], 11, v[0:1]
	s_and_b32 s2, s2, 0xffffff80
	v_lshl_add_u64 v[0:1], s[8:9], 0, v[0:1]
	v_lshl_add_u64 v[28:29], v[0:1], 0, v[96:97]
	v_add_u32_e32 v0, s2, v82
	v_ashrrev_i32_e32 v1, 31, v0
	v_lshlrev_b64 v[0:1], 11, v[0:1]
	v_lshl_add_u64 v[0:1], s[12:13], 0, v[0:1]
	v_add_co_u32_e32 v70, vcc, s63, v28
	v_lshl_add_u64 v[68:69], v[0:1], 0, v[96:97]
	s_nop 0
	v_addc_co_u32_e32 v71, vcc, 0, v29, vcc
	v_add_co_u32_e32 v72, vcc, s63, v68
	v_lshl_add_u64 v[2:3], s[8:9], 0, v[2:3]
	s_nop 0
	v_addc_co_u32_e32 v73, vcc, 0, v69, vcc
	v_add_co_u32_e32 v74, vcc, s64, v28
	v_lshl_add_u64 v[66:67], v[2:3], 0, v[96:97]
	s_nop 0
	v_addc_co_u32_e32 v75, vcc, 0, v29, vcc
	v_add_co_u32_e32 v76, vcc, s64, v68
	global_load_dwordx4 v[0:3], v[66:67], off
	global_load_dwordx4 v[4:7], v[68:69], off
	v_addc_co_u32_e32 v77, vcc, 0, v69, vcc
	v_add_co_u32_e32 v78, vcc, s65, v68
	global_load_dwordx4 v[8:11], v[70:71], off
	s_nop 0
	v_addc_co_u32_e32 v79, vcc, 0, v69, vcc
	v_add_co_u32_e32 v80, vcc, s65, v28
	global_load_dwordx4 v[12:15], v[72:73], off
	s_nop 0
	v_addc_co_u32_e32 v81, vcc, 0, v29, vcc
	s_waitcnt lgkmcnt(0)
	global_load_dwordx4 v[16:19], v[74:75], off
	global_load_dwordx4 v[20:23], v[76:77], off
	global_load_dwordx4 v[24:27], v[78:79], off
	global_load_dwordx4 v[28:31], v[80:81], off
	global_load_dwordx4 v[32:35], v[66:67], off offset:128
	global_load_dwordx4 v[36:39], v[68:69], off offset:128
	global_load_dwordx4 v[40:43], v[70:71], off offset:128
	global_load_dwordx4 v[44:47], v[72:73], off offset:128
	global_load_dwordx4 v[48:51], v[74:75], off offset:128
	global_load_dwordx4 v[52:55], v[76:77], off offset:128
	global_load_dwordx4 v[56:59], v[80:81], off offset:128
	global_load_dwordx4 v[60:63], v[78:79], off offset:128
	v_ashrrev_i32_e32 v64, 1, v84
	v_lshrrev_b32_e32 v65, 1, v84
	v_and_b32_e32 v85, 0xffffffc0, v64
	s_waitcnt vmcnt(17)
	v_and_b32_e32 v88, 16, v65
	v_and_or_b32 v64, v84, 31, v85
	v_mad_u64_u32 v[82:83], s[14:15], v82, s91, v[96:97]
	v_mad_u64_u32 v[64:65], s[14:15], v64, s91, v[88:89]
	v_add_u32_e32 v86, 0xd800, v82
	v_and_b32_e32 v65, 0x5f, v84
	v_mad_u32_u24 v83, v65, s91, v88
	s_mov_b32 s14, 23
	s_waitcnt vmcnt(14)
	ds_write_b128 v82, v[4:7] offset:18432
	ds_write_b128 v82, v[0:3]
	s_waitcnt vmcnt(12)
	ds_write_b128 v82, v[12:15] offset:23040
	s_waitcnt vmcnt(10)
	ds_write_b128 v82, v[20:23] offset:27648
	s_waitcnt vmcnt(9)
	ds_write_b128 v82, v[24:27] offset:32256
	ds_write_b128 v82, v[8:11] offset:4608
	ds_write_b128 v82, v[16:19] offset:9216
	s_waitcnt vmcnt(8)
	ds_write_b128 v82, v[28:31] offset:13824
	s_waitcnt lgkmcnt(0)
	s_barrier
	s_waitcnt vmcnt(7)
	ds_write_b128 v82, v[32:35] offset:36864
	s_waitcnt vmcnt(6)
	ds_write_b128 v82, v[36:39] offset:55296
	s_waitcnt vmcnt(5)
	ds_write_b128 v82, v[40:43] offset:41472
	s_waitcnt vmcnt(4)
	ds_write_b128 v82, v[44:47] offset:59904
	s_waitcnt vmcnt(3)
	ds_write_b128 v82, v[48:51] offset:46080
	s_waitcnt vmcnt(2)
	ds_write_b128 v82, v[52:55] offset:64512
	s_waitcnt vmcnt(1)
	ds_write_b128 v82, v[56:59] offset:50688
	s_waitcnt vmcnt(0)
	ds_write_b128 v86, v[60:63] offset:13824
	ds_read_b128 v[0:3], v64
	ds_read_b128 v[4:7], v83 offset:18432
	ds_read_b128 v[88:91], v64 offset:32
	ds_read_b128 v[92:95], v83 offset:18464
	ds_read_b128 v[8:11], v83 offset:23040
	ds_read_b128 v[98:101], v83 offset:23072
	global_load_dwordx4 v[138:141], v[66:67], off offset:256
	global_load_dwordx4 v[142:145], v[68:69], off offset:256
	global_load_dwordx4 v[146:149], v[70:71], off offset:256
	global_load_dwordx4 v[150:153], v[72:73], off offset:256
	global_load_dwordx4 v[154:157], v[74:75], off offset:256
	global_load_dwordx4 v[158:161], v[76:77], off offset:256
	global_load_dwordx4 v[162:165], v[80:81], off offset:256
	global_load_dwordx4 v[166:169], v[78:79], off offset:256
	s_waitcnt lgkmcnt(4)
	v_mfma_f32_32x32x16_bf16 v[48:63], v[0:3], v[4:7], 0
	s_waitcnt lgkmcnt(1)
	v_mfma_f32_32x32x16_bf16 v[32:47], v[0:3], v[8:11], 0
	ds_read_b128 v[0:3], v64 offset:4608
	ds_read_b128 v[102:105], v64 offset:4640
	s_waitcnt lgkmcnt(1)
	v_mfma_f32_32x32x16_bf16 v[16:31], v[0:3], v[4:7], 0
	v_mfma_f32_32x32x16_bf16 v[0:15], v[0:3], v[8:11], 0
	v_mfma_f32_32x32x16_bf16 v[48:63], v[88:91], v[92:95], v[48:63]
	v_mfma_f32_32x32x16_bf16 v[32:47], v[88:91], v[98:101], v[32:47]
	s_waitcnt lgkmcnt(0)
	v_mfma_f32_32x32x16_bf16 v[16:31], v[102:105], v[92:95], v[16:31]
	v_mfma_f32_32x32x16_bf16 v[0:15], v[102:105], v[98:101], v[0:15]
	ds_read_b128 v[88:91], v64 offset:64
	ds_read_b128 v[92:95], v83 offset:18496
	ds_read_b128 v[98:101], v64 offset:96
	ds_read_b128 v[102:105], v83 offset:18528
	ds_read_b128 v[106:109], v83 offset:23104
	ds_read_b128 v[110:113], v83 offset:23136
	s_waitcnt lgkmcnt(4)
	v_mfma_f32_32x32x16_bf16 v[48:63], v[88:91], v[92:95], v[48:63]
	s_waitcnt lgkmcnt(1)
	v_mfma_f32_32x32x16_bf16 v[32:47], v[88:91], v[106:109], v[32:47]
	ds_read_b128 v[88:91], v64 offset:4672
	ds_read_b128 v[114:117], v64 offset:4704
	s_waitcnt lgkmcnt(1)
	v_mfma_f32_32x32x16_bf16 v[16:31], v[88:91], v[92:95], v[16:31]
	v_mfma_f32_32x32x16_bf16 v[0:15], v[88:91], v[106:109], v[0:15]
	v_mfma_f32_32x32x16_bf16 v[48:63], v[98:101], v[102:105], v[48:63]
	v_mfma_f32_32x32x16_bf16 v[32:47], v[98:101], v[110:113], v[32:47]
	s_waitcnt lgkmcnt(0)
	v_mfma_f32_32x32x16_bf16 v[16:31], v[114:117], v[102:105], v[16:31]
	s_barrier
;     ...
;   for (int kt = 0; kt < nk; kt += 2) {
;     if (kt + 2 < nk) G_LOAD(ra0, rb0, kt + 2);
;     if (kt + 1 < nk) G_STORE(ra1, rb1, As1, Bs1);
;     G_COMPUTE(As, Bs);
;     __syncthreads();
;     if (kt + 1 < nk) {
;       if (kt + 3 < nk) G_LOAD(ra1, rb1, kt + 3);
;       if (kt + 2 < nk) G_STORE(ra0, rb0, As, Bs);
;       G_COMPUTE(As1, Bs1);
;       __syncthreads();
;     }
;   }
	s_waitcnt vmcnt(7)
	ds_write_b128 v82, v[138:141]
	s_waitcnt vmcnt(6)
	ds_write_b128 v82, v[142:145] offset:18432
	s_waitcnt vmcnt(5)
	ds_write_b128 v82, v[146:149] offset:4608
	s_waitcnt vmcnt(4)
	ds_write_b128 v82, v[150:153] offset:23040
	s_waitcnt vmcnt(3)
	ds_write_b128 v82, v[154:157] offset:9216
	s_waitcnt vmcnt(2)
	ds_write_b128 v82, v[158:161] offset:27648
	s_waitcnt vmcnt(1)
	ds_write_b128 v82, v[162:165] offset:13824
	s_waitcnt vmcnt(0)
	ds_write_b128 v82, v[166:169] offset:32256
	v_mfma_f32_32x32x16_bf16 v[0:15], v[114:117], v[110:113], v[0:15]
	ds_read_b128 v[88:91], v64 offset:36864
	ds_read_b128 v[92:95], v83 offset:55296
	ds_read_b128 v[98:101], v64 offset:36896
	ds_read_b128 v[102:105], v83 offset:55328
	ds_read_b128 v[106:109], v83 offset:59904
	ds_read_b128 v[110:113], v83 offset:59936
	global_load_dwordx4 v[138:141], v[66:67], off offset:384
	global_load_dwordx4 v[142:145], v[68:69], off offset:384
	global_load_dwordx4 v[146:149], v[70:71], off offset:384
	global_load_dwordx4 v[150:153], v[72:73], off offset:384
	global_load_dwordx4 v[154:157], v[74:75], off offset:384
	global_load_dwordx4 v[158:161], v[76:77], off offset:384
	global_load_dwordx4 v[162:165], v[80:81], off offset:384
	global_load_dwordx4 v[166:169], v[78:79], off offset:384
	s_waitcnt lgkmcnt(4)
	v_mfma_f32_32x32x16_bf16 v[48:63], v[88:91], v[92:95], v[48:63]
	s_waitcnt lgkmcnt(1)
	v_mfma_f32_32x32x16_bf16 v[32:47], v[88:91], v[106:109], v[32:47]
	ds_read_b128 v[88:91], v64 offset:41472
	ds_read_b128 v[114:117], v64 offset:41504
	s_waitcnt lgkmcnt(1)
	v_mfma_f32_32x32x16_bf16 v[16:31], v[88:91], v[92:95], v[16:31]
	v_mfma_f32_32x32x16_bf16 v[0:15], v[88:91], v[106:109], v[0:15]
	v_mfma_f32_32x32x16_bf16 v[48:63], v[98:101], v[102:105], v[48:63]
	v_mfma_f32_32x32x16_bf16 v[32:47], v[98:101], v[110:113], v[32:47]
	s_waitcnt lgkmcnt(0)
	v_mfma_f32_32x32x16_bf16 v[16:31], v[114:117], v[102:105], v[16:31]
	ds_read_b128 v[88:91], v64 offset:36928
	ds_read_b128 v[92:95], v83 offset:55360
	ds_read_b128 v[98:101], v64 offset:36960
	ds_read_b128 v[102:105], v83 offset:55392
	v_mfma_f32_32x32x16_bf16 v[0:15], v[114:117], v[110:113], v[0:15]
	ds_read_b128 v[106:109], v83 offset:59968
	ds_read_b128 v[110:113], v83 offset:60000
	s_waitcnt lgkmcnt(4)
	v_mfma_f32_32x32x16_bf16 v[48:63], v[88:91], v[92:95], v[48:63]
	s_waitcnt lgkmcnt(1)
	v_mfma_f32_32x32x16_bf16 v[32:47], v[88:91], v[106:109], v[32:47]
	ds_read_b128 v[88:91], v64 offset:41536
	ds_read_b128 v[114:117], v64 offset:41568
	s_waitcnt lgkmcnt(1)
	v_mfma_f32_32x32x16_bf16 v[16:31], v[88:91], v[92:95], v[16:31]
	v_mfma_f32_32x32x16_bf16 v[0:15], v[88:91], v[106:109], v[0:15]
	v_mfma_f32_32x32x16_bf16 v[48:63], v[98:101], v[102:105], v[48:63]
	v_mfma_f32_32x32x16_bf16 v[32:47], v[98:101], v[110:113], v[32:47]
	s_waitcnt lgkmcnt(0)
	v_mfma_f32_32x32x16_bf16 v[16:31], v[114:117], v[102:105], v[16:31]
	s_barrier
	s_waitcnt vmcnt(7)
	ds_write_b128 v82, v[138:141] offset:36864
	s_waitcnt vmcnt(6)
	ds_write_b128 v82, v[142:145] offset:55296
	s_waitcnt vmcnt(5)
	ds_write_b128 v82, v[146:149] offset:41472
	s_waitcnt vmcnt(4)
	ds_write_b128 v82, v[150:153] offset:59904
	s_waitcnt vmcnt(3)
	ds_write_b128 v82, v[154:157] offset:46080
	s_waitcnt vmcnt(2)
	ds_write_b128 v82, v[158:161] offset:64512
	s_waitcnt vmcnt(1)
	ds_write_b128 v82, v[162:165] offset:50688
	s_waitcnt vmcnt(0)
	ds_write_b128 v86, v[166:169] offset:13824
	v_mfma_f32_32x32x16_bf16 v[0:15], v[114:117], v[110:113], v[0:15]
	ds_read_b128 v[88:91], v64
	ds_read_b128 v[92:95], v83 offset:18432
	ds_read_b128 v[98:101], v64 offset:32
	ds_read_b128 v[102:105], v83 offset:18464
	ds_read_b128 v[106:109], v83 offset:23040
	ds_read_b128 v[110:113], v83 offset:23072
	global_load_dwordx4 v[138:141], v[66:67], off offset:512
	global_load_dwordx4 v[142:145], v[68:69], off offset:512
	global_load_dwordx4 v[146:149], v[70:71], off offset:512
	global_load_dwordx4 v[150:153], v[72:73], off offset:512
	global_load_dwordx4 v[154:157], v[74:75], off offset:512
	global_load_dwordx4 v[158:161], v[76:77], off offset:512
	global_load_dwordx4 v[162:165], v[80:81], off offset:512
	global_load_dwordx4 v[166:169], v[78:79], off offset:512
	s_waitcnt lgkmcnt(4)
	v_mfma_f32_32x32x16_bf16 v[48:63], v[88:91], v[92:95], v[48:63]
	s_waitcnt lgkmcnt(1)
	v_mfma_f32_32x32x16_bf16 v[32:47], v[88:91], v[106:109], v[32:47]
	ds_read_b128 v[88:91], v64 offset:4608
	ds_read_b128 v[114:117], v64 offset:4640
	s_waitcnt lgkmcnt(1)
	v_mfma_f32_32x32x16_bf16 v[16:31], v[88:91], v[92:95], v[16:31]
	v_mfma_f32_32x32x16_bf16 v[0:15], v[88:91], v[106:109], v[0:15]
	v_mfma_f32_32x32x16_bf16 v[48:63], v[98:101], v[102:105], v[48:63]
	v_mfma_f32_32x32x16_bf16 v[32:47], v[98:101], v[110:113], v[32:47]
	s_waitcnt lgkmcnt(0)
	v_mfma_f32_32x32x16_bf16 v[16:31], v[114:117], v[102:105], v[16:31]
	ds_read_b128 v[88:91], v64 offset:64
	ds_read_b128 v[92:95], v83 offset:18496
	ds_read_b128 v[98:101], v64 offset:96
	ds_read_b128 v[102:105], v83 offset:18528
	v_mfma_f32_32x32x16_bf16 v[0:15], v[114:117], v[110:113], v[0:15]
	ds_read_b128 v[106:109], v83 offset:23104
	ds_read_b128 v[110:113], v83 offset:23136
	s_waitcnt lgkmcnt(4)
	v_mfma_f32_32x32x16_bf16 v[48:63], v[88:91], v[92:95], v[48:63]
	s_waitcnt lgkmcnt(1)
	v_mfma_f32_32x32x16_bf16 v[32:47], v[88:91], v[106:109], v[32:47]
	ds_read_b128 v[88:91], v64 offset:4672
	ds_read_b128 v[114:117], v64 offset:4704
	s_waitcnt lgkmcnt(1)
	v_mfma_f32_32x32x16_bf16 v[16:31], v[88:91], v[92:95], v[16:31]
	v_mfma_f32_32x32x16_bf16 v[0:15], v[88:91], v[106:109], v[0:15]
	v_mfma_f32_32x32x16_bf16 v[48:63], v[98:101], v[102:105], v[48:63]
	v_mfma_f32_32x32x16_bf16 v[32:47], v[98:101], v[110:113], v[32:47]
	s_waitcnt lgkmcnt(0)
	v_mfma_f32_32x32x16_bf16 v[16:31], v[114:117], v[102:105], v[16:31]
	s_barrier
;     ...
;   for (int kt = 0; kt < nk; kt += 2) {
;     if (kt + 2 < nk) G_LOAD(ra0, rb0, kt + 2);
;     if (kt + 1 < nk) G_STORE(ra1, rb1, As1, Bs1);
;     G_COMPUTE(As, Bs);
;     __syncthreads();
;     if (kt + 1 < nk) {
;       if (kt + 3 < nk) G_LOAD(ra1, rb1, kt + 3);
;       if (kt + 2 < nk) G_STORE(ra0, rb0, As, Bs);
;       G_COMPUTE(As1, Bs1);
;       __syncthreads();
;     }
;   }
	s_waitcnt vmcnt(7)
	ds_write_b128 v82, v[138:141]
	s_waitcnt vmcnt(6)
	ds_write_b128 v82, v[142:145] offset:18432
	s_waitcnt vmcnt(5)
	ds_write_b128 v82, v[146:149] offset:4608
	s_waitcnt vmcnt(4)
	ds_write_b128 v82, v[150:153] offset:23040
	s_waitcnt vmcnt(3)
	ds_write_b128 v82, v[154:157] offset:9216
	s_waitcnt vmcnt(2)
	ds_write_b128 v82, v[158:161] offset:27648
	s_waitcnt vmcnt(1)
	ds_write_b128 v82, v[162:165] offset:13824
	s_waitcnt vmcnt(0)
	ds_write_b128 v82, v[166:169] offset:32256
	v_mfma_f32_32x32x16_bf16 v[0:15], v[114:117], v[110:113], v[0:15]
	ds_read_b128 v[88:91], v64 offset:36864
	ds_read_b128 v[92:95], v83 offset:55296
	ds_read_b128 v[98:101], v64 offset:36896
	ds_read_b128 v[102:105], v83 offset:55328
	ds_read_b128 v[106:109], v83 offset:59904
	ds_read_b128 v[110:113], v83 offset:59936
	global_load_dwordx4 v[138:141], v[66:67], off offset:640
	global_load_dwordx4 v[142:145], v[68:69], off offset:640
	global_load_dwordx4 v[146:149], v[70:71], off offset:640
	global_load_dwordx4 v[150:153], v[72:73], off offset:640
	global_load_dwordx4 v[154:157], v[74:75], off offset:640
	global_load_dwordx4 v[158:161], v[76:77], off offset:640
	global_load_dwordx4 v[162:165], v[80:81], off offset:640
	global_load_dwordx4 v[166:169], v[78:79], off offset:640
	s_waitcnt lgkmcnt(4)
	v_mfma_f32_32x32x16_bf16 v[48:63], v[88:91], v[92:95], v[48:63]
	s_waitcnt lgkmcnt(1)
	v_mfma_f32_32x32x16_bf16 v[32:47], v[88:91], v[106:109], v[32:47]
	ds_read_b128 v[88:91], v64 offset:41472
	ds_read_b128 v[114:117], v64 offset:41504
	s_waitcnt lgkmcnt(1)
	v_mfma_f32_32x32x16_bf16 v[16:31], v[88:91], v[92:95], v[16:31]
	v_mfma_f32_32x32x16_bf16 v[0:15], v[88:91], v[106:109], v[0:15]
	v_mfma_f32_32x32x16_bf16 v[48:63], v[98:101], v[102:105], v[48:63]
	v_mfma_f32_32x32x16_bf16 v[32:47], v[98:101], v[110:113], v[32:47]
	s_waitcnt lgkmcnt(0)
	v_mfma_f32_32x32x16_bf16 v[16:31], v[114:117], v[102:105], v[16:31]
	ds_read_b128 v[88:91], v64 offset:36928
	ds_read_b128 v[92:95], v83 offset:55360
	ds_read_b128 v[98:101], v64 offset:36960
	ds_read_b128 v[102:105], v83 offset:55392
	v_mfma_f32_32x32x16_bf16 v[0:15], v[114:117], v[110:113], v[0:15]
	ds_read_b128 v[106:109], v83 offset:59968
	ds_read_b128 v[110:113], v83 offset:60000
	s_waitcnt lgkmcnt(4)
	v_mfma_f32_32x32x16_bf16 v[48:63], v[88:91], v[92:95], v[48:63]
	s_waitcnt lgkmcnt(1)
	v_mfma_f32_32x32x16_bf16 v[32:47], v[88:91], v[106:109], v[32:47]
	ds_read_b128 v[88:91], v64 offset:41536
	ds_read_b128 v[114:117], v64 offset:41568
	s_waitcnt lgkmcnt(1)
	v_mfma_f32_32x32x16_bf16 v[16:31], v[88:91], v[92:95], v[16:31]
	v_mfma_f32_32x32x16_bf16 v[0:15], v[88:91], v[106:109], v[0:15]
	v_mfma_f32_32x32x16_bf16 v[48:63], v[98:101], v[102:105], v[48:63]
	v_mfma_f32_32x32x16_bf16 v[32:47], v[98:101], v[110:113], v[32:47]
	s_waitcnt lgkmcnt(0)
	v_mfma_f32_32x32x16_bf16 v[16:31], v[114:117], v[102:105], v[16:31]
	s_barrier
	s_waitcnt vmcnt(7)
	ds_write_b128 v82, v[138:141] offset:36864
	s_waitcnt vmcnt(6)
	ds_write_b128 v82, v[142:145] offset:55296
	s_waitcnt vmcnt(5)
	ds_write_b128 v82, v[146:149] offset:41472
	s_waitcnt vmcnt(4)
	ds_write_b128 v82, v[150:153] offset:59904
	s_waitcnt vmcnt(3)
	ds_write_b128 v82, v[154:157] offset:46080
	s_waitcnt vmcnt(2)
	ds_write_b128 v82, v[158:161] offset:64512
	s_waitcnt vmcnt(1)
	ds_write_b128 v82, v[162:165] offset:50688
	s_waitcnt vmcnt(0)
	ds_write_b128 v86, v[166:169] offset:13824
	v_mfma_f32_32x32x16_bf16 v[0:15], v[114:117], v[110:113], v[0:15]
	ds_read_b128 v[88:91], v64
	ds_read_b128 v[92:95], v83 offset:18432
	ds_read_b128 v[98:101], v64 offset:32
	ds_read_b128 v[102:105], v83 offset:18464
	ds_read_b128 v[106:109], v83 offset:23040
	ds_read_b128 v[110:113], v83 offset:23072
	global_load_dwordx4 v[138:141], v[66:67], off offset:768
	global_load_dwordx4 v[142:145], v[68:69], off offset:768
	global_load_dwordx4 v[146:149], v[70:71], off offset:768
	global_load_dwordx4 v[150:153], v[72:73], off offset:768
	global_load_dwordx4 v[154:157], v[74:75], off offset:768
	global_load_dwordx4 v[158:161], v[76:77], off offset:768
	global_load_dwordx4 v[162:165], v[80:81], off offset:768
	global_load_dwordx4 v[166:169], v[78:79], off offset:768
	s_waitcnt lgkmcnt(4)
	v_mfma_f32_32x32x16_bf16 v[48:63], v[88:91], v[92:95], v[48:63]
	s_waitcnt lgkmcnt(1)
	v_mfma_f32_32x32x16_bf16 v[32:47], v[88:91], v[106:109], v[32:47]
	ds_read_b128 v[88:91], v64 offset:4608
	ds_read_b128 v[114:117], v64 offset:4640
	s_waitcnt lgkmcnt(1)
	v_mfma_f32_32x32x16_bf16 v[16:31], v[88:91], v[92:95], v[16:31]
	v_mfma_f32_32x32x16_bf16 v[0:15], v[88:91], v[106:109], v[0:15]
	v_mfma_f32_32x32x16_bf16 v[48:63], v[98:101], v[102:105], v[48:63]
	v_mfma_f32_32x32x16_bf16 v[32:47], v[98:101], v[110:113], v[32:47]
	s_waitcnt lgkmcnt(0)
	v_mfma_f32_32x32x16_bf16 v[16:31], v[114:117], v[102:105], v[16:31]
	ds_read_b128 v[88:91], v64 offset:64
	ds_read_b128 v[92:95], v83 offset:18496
	ds_read_b128 v[98:101], v64 offset:96
	ds_read_b128 v[102:105], v83 offset:18528
	v_mfma_f32_32x32x16_bf16 v[0:15], v[114:117], v[110:113], v[0:15]
	ds_read_b128 v[106:109], v83 offset:23104
	ds_read_b128 v[110:113], v83 offset:23136
	s_waitcnt lgkmcnt(4)
	v_mfma_f32_32x32x16_bf16 v[48:63], v[88:91], v[92:95], v[48:63]
	s_waitcnt lgkmcnt(1)
	v_mfma_f32_32x32x16_bf16 v[32:47], v[88:91], v[106:109], v[32:47]
	ds_read_b128 v[88:91], v64 offset:4672
	ds_read_b128 v[114:117], v64 offset:4704
	s_waitcnt lgkmcnt(1)
	v_mfma_f32_32x32x16_bf16 v[16:31], v[88:91], v[92:95], v[16:31]
	v_mfma_f32_32x32x16_bf16 v[0:15], v[88:91], v[106:109], v[0:15]
	v_mfma_f32_32x32x16_bf16 v[48:63], v[98:101], v[102:105], v[48:63]
	v_mfma_f32_32x32x16_bf16 v[32:47], v[98:101], v[110:113], v[32:47]
	s_waitcnt lgkmcnt(0)
	v_mfma_f32_32x32x16_bf16 v[16:31], v[114:117], v[102:105], v[16:31]
	s_barrier
;     ...
;   bf16* As1 = As + 2 * 128 * 72;
;   bf16* Bs1 = As1 + 128 * 72;
;   G_LOAD(ra0, rb0, 0);
;   if (nk > 1) G_LOAD(ra1, rb1, 1);
;   G_STORE(ra0, rb0, As, Bs);
;   __syncthreads();
;   for (int kt = 0; kt < nk; kt += 2) {
;     if (kt + 2 < nk) G_LOAD(ra0, rb0, kt + 2);
;     if (kt + 1 < nk) G_STORE(ra1, rb1, As1, Bs1);
;     G_COMPUTE(As, Bs);
;     __syncthreads();
;     if (kt + 1 < nk) {
;       if (kt + 3 < nk) G_LOAD(ra1, rb1, kt + 3);
;       if (kt + 2 < nk) G_STORE(ra0, rb0, As, Bs);
;       G_COMPUTE(As1, Bs1);
;       __syncthreads();
;     }
;   }
	s_waitcnt vmcnt(7)
	ds_write_b128 v82, v[138:141]
	s_waitcnt vmcnt(6)
	ds_write_b128 v82, v[142:145] offset:18432
	s_waitcnt vmcnt(5)
	ds_write_b128 v82, v[146:149] offset:4608
	s_waitcnt vmcnt(4)
	ds_write_b128 v82, v[150:153] offset:23040
	s_waitcnt vmcnt(3)
	ds_write_b128 v82, v[154:157] offset:9216
	s_waitcnt vmcnt(2)
	ds_write_b128 v82, v[158:161] offset:27648
	s_waitcnt vmcnt(1)
	ds_write_b128 v82, v[162:165] offset:13824
	s_waitcnt vmcnt(0)
	ds_write_b128 v82, v[166:169] offset:32256
	v_mfma_f32_32x32x16_bf16 v[0:15], v[114:117], v[110:113], v[0:15]
	ds_read_b128 v[88:91], v64 offset:36864
	ds_read_b128 v[92:95], v83 offset:55296
	ds_read_b128 v[98:101], v64 offset:36896
	ds_read_b128 v[102:105], v83 offset:55328
	ds_read_b128 v[106:109], v83 offset:59904
	ds_read_b128 v[110:113], v83 offset:59936
	global_load_dwordx4 v[138:141], v[66:67], off offset:896
	global_load_dwordx4 v[142:145], v[68:69], off offset:896
	global_load_dwordx4 v[146:149], v[70:71], off offset:896
	global_load_dwordx4 v[150:153], v[72:73], off offset:896
	global_load_dwordx4 v[154:157], v[74:75], off offset:896
	global_load_dwordx4 v[158:161], v[76:77], off offset:896
	global_load_dwordx4 v[162:165], v[80:81], off offset:896
	global_load_dwordx4 v[166:169], v[78:79], off offset:896
	s_waitcnt lgkmcnt(4)
	v_mfma_f32_32x32x16_bf16 v[48:63], v[88:91], v[92:95], v[48:63]
	s_waitcnt lgkmcnt(1)
	v_mfma_f32_32x32x16_bf16 v[32:47], v[88:91], v[106:109], v[32:47]
	ds_read_b128 v[88:91], v64 offset:41472
	ds_read_b128 v[114:117], v64 offset:41504
	s_waitcnt lgkmcnt(1)
	v_mfma_f32_32x32x16_bf16 v[16:31], v[88:91], v[92:95], v[16:31]
	v_mfma_f32_32x32x16_bf16 v[0:15], v[88:91], v[106:109], v[0:15]
	v_mfma_f32_32x32x16_bf16 v[48:63], v[98:101], v[102:105], v[48:63]
	v_mfma_f32_32x32x16_bf16 v[32:47], v[98:101], v[110:113], v[32:47]
	s_waitcnt lgkmcnt(0)
	v_mfma_f32_32x32x16_bf16 v[16:31], v[114:117], v[102:105], v[16:31]
	ds_read_b128 v[88:91], v64 offset:36928
	ds_read_b128 v[92:95], v83 offset:55360
	ds_read_b128 v[98:101], v64 offset:36960
	ds_read_b128 v[102:105], v83 offset:55392
	v_mfma_f32_32x32x16_bf16 v[0:15], v[114:117], v[110:113], v[0:15]
	ds_read_b128 v[106:109], v83 offset:59968
	ds_read_b128 v[110:113], v83 offset:60000
	s_waitcnt lgkmcnt(4)
	v_mfma_f32_32x32x16_bf16 v[48:63], v[88:91], v[92:95], v[48:63]
	s_waitcnt lgkmcnt(1)
	v_mfma_f32_32x32x16_bf16 v[32:47], v[88:91], v[106:109], v[32:47]
	ds_read_b128 v[88:91], v64 offset:41536
	ds_read_b128 v[114:117], v64 offset:41568
	s_waitcnt lgkmcnt(1)
	v_mfma_f32_32x32x16_bf16 v[16:31], v[88:91], v[92:95], v[16:31]
	v_mfma_f32_32x32x16_bf16 v[0:15], v[88:91], v[106:109], v[0:15]
	v_mfma_f32_32x32x16_bf16 v[48:63], v[98:101], v[102:105], v[48:63]
	v_mfma_f32_32x32x16_bf16 v[32:47], v[98:101], v[110:113], v[32:47]
	s_waitcnt lgkmcnt(0)
	v_mfma_f32_32x32x16_bf16 v[16:31], v[114:117], v[102:105], v[16:31]
	s_barrier
	s_waitcnt vmcnt(7)
	ds_write_b128 v82, v[138:141] offset:36864
	s_waitcnt vmcnt(6)
	ds_write_b128 v82, v[142:145] offset:55296
	s_waitcnt vmcnt(5)
	ds_write_b128 v82, v[146:149] offset:41472
	s_waitcnt vmcnt(4)
	ds_write_b128 v82, v[150:153] offset:59904
	s_waitcnt vmcnt(3)
	ds_write_b128 v82, v[154:157] offset:46080
	s_waitcnt vmcnt(2)
	ds_write_b128 v82, v[158:161] offset:64512
	s_waitcnt vmcnt(1)
	ds_write_b128 v82, v[162:165] offset:50688
	s_waitcnt vmcnt(0)
	ds_write_b128 v86, v[166:169] offset:13824
	v_mfma_f32_32x32x16_bf16 v[0:15], v[114:117], v[110:113], v[0:15]
	ds_read_b128 v[88:91], v64
	ds_read_b128 v[92:95], v83 offset:18432
	ds_read_b128 v[98:101], v64 offset:32
	ds_read_b128 v[102:105], v83 offset:18464
	ds_read_b128 v[106:109], v83 offset:23040
	ds_read_b128 v[110:113], v83 offset:23072
	global_load_dwordx4 v[138:141], v[66:67], off offset:1024
	global_load_dwordx4 v[142:145], v[68:69], off offset:1024
	global_load_dwordx4 v[146:149], v[70:71], off offset:1024
	global_load_dwordx4 v[150:153], v[72:73], off offset:1024
	global_load_dwordx4 v[154:157], v[74:75], off offset:1024
	global_load_dwordx4 v[158:161], v[76:77], off offset:1024
	global_load_dwordx4 v[162:165], v[80:81], off offset:1024
	global_load_dwordx4 v[166:169], v[78:79], off offset:1024
	s_waitcnt lgkmcnt(4)
	v_mfma_f32_32x32x16_bf16 v[48:63], v[88:91], v[92:95], v[48:63]
	s_waitcnt lgkmcnt(1)
	v_mfma_f32_32x32x16_bf16 v[32:47], v[88:91], v[106:109], v[32:47]
	ds_read_b128 v[88:91], v64 offset:4608
	ds_read_b128 v[114:117], v64 offset:4640
	s_waitcnt lgkmcnt(1)
	v_mfma_f32_32x32x16_bf16 v[16:31], v[88:91], v[92:95], v[16:31]
	v_mfma_f32_32x32x16_bf16 v[0:15], v[88:91], v[106:109], v[0:15]
	v_mfma_f32_32x32x16_bf16 v[48:63], v[98:101], v[102:105], v[48:63]
	v_mfma_f32_32x32x16_bf16 v[32:47], v[98:101], v[110:113], v[32:47]
	s_waitcnt lgkmcnt(0)
	v_mfma_f32_32x32x16_bf16 v[16:31], v[114:117], v[102:105], v[16:31]
	ds_read_b128 v[88:91], v64 offset:64
	ds_read_b128 v[92:95], v83 offset:18496
	ds_read_b128 v[98:101], v64 offset:96
	ds_read_b128 v[102:105], v83 offset:18528
	v_mfma_f32_32x32x16_bf16 v[0:15], v[114:117], v[110:113], v[0:15]
	ds_read_b128 v[106:109], v83 offset:23104
	ds_read_b128 v[110:113], v83 offset:23136
	s_waitcnt lgkmcnt(4)
	v_mfma_f32_32x32x16_bf16 v[48:63], v[88:91], v[92:95], v[48:63]
	s_waitcnt lgkmcnt(1)
	v_mfma_f32_32x32x16_bf16 v[32:47], v[88:91], v[106:109], v[32:47]
	ds_read_b128 v[88:91], v64 offset:4672
	ds_read_b128 v[114:117], v64 offset:4704
	s_waitcnt lgkmcnt(1)
	v_mfma_f32_32x32x16_bf16 v[16:31], v[88:91], v[92:95], v[16:31]
	v_mfma_f32_32x32x16_bf16 v[0:15], v[88:91], v[106:109], v[0:15]
	v_mfma_f32_32x32x16_bf16 v[48:63], v[98:101], v[102:105], v[48:63]
	v_mfma_f32_32x32x16_bf16 v[32:47], v[98:101], v[110:113], v[32:47]
	s_waitcnt lgkmcnt(0)
	v_mfma_f32_32x32x16_bf16 v[16:31], v[114:117], v[102:105], v[16:31]
	s_barrier
;     ...
;   bf16* As1 = As + 2 * 128 * 72;
;   bf16* Bs1 = As1 + 128 * 72;
;   G_LOAD(ra0, rb0, 0);
;   if (nk > 1) G_LOAD(ra1, rb1, 1);
;   G_STORE(ra0, rb0, As, Bs);
;   __syncthreads();
;   for (int kt = 0; kt < nk; kt += 2) {
;     if (kt + 2 < nk) G_LOAD(ra0, rb0, kt + 2);
;     if (kt + 1 < nk) G_STORE(ra1, rb1, As1, Bs1);
;     G_COMPUTE(As, Bs);
;     __syncthreads();
;     if (kt + 1 < nk) {
;       if (kt + 3 < nk) G_LOAD(ra1, rb1, kt + 3);
;       if (kt + 2 < nk) G_STORE(ra0, rb0, As, Bs);
;       G_COMPUTE(As1, Bs1);
;       __syncthreads();
;     }
;   }
	s_waitcnt vmcnt(7)
	ds_write_b128 v82, v[138:141]
	s_waitcnt vmcnt(6)
	ds_write_b128 v82, v[142:145] offset:18432
	s_waitcnt vmcnt(5)
	ds_write_b128 v82, v[146:149] offset:4608
	s_waitcnt vmcnt(4)
	ds_write_b128 v82, v[150:153] offset:23040
	s_waitcnt vmcnt(3)
	ds_write_b128 v82, v[154:157] offset:9216
	s_waitcnt vmcnt(2)
	ds_write_b128 v82, v[158:161] offset:27648
	s_waitcnt vmcnt(1)
	ds_write_b128 v82, v[162:165] offset:13824
	s_waitcnt vmcnt(0)
	ds_write_b128 v82, v[166:169] offset:32256
	v_mfma_f32_32x32x16_bf16 v[0:15], v[114:117], v[110:113], v[0:15]
	ds_read_b128 v[88:91], v64 offset:36864
	ds_read_b128 v[92:95], v83 offset:55296
	ds_read_b128 v[98:101], v64 offset:36896
	ds_read_b128 v[102:105], v83 offset:55328
	ds_read_b128 v[106:109], v83 offset:59904
	ds_read_b128 v[110:113], v83 offset:59936
	global_load_dwordx4 v[138:141], v[66:67], off offset:1152
	global_load_dwordx4 v[142:145], v[68:69], off offset:1152
	global_load_dwordx4 v[146:149], v[70:71], off offset:1152
	global_load_dwordx4 v[150:153], v[72:73], off offset:1152
	global_load_dwordx4 v[154:157], v[74:75], off offset:1152
	global_load_dwordx4 v[158:161], v[76:77], off offset:1152
	global_load_dwordx4 v[162:165], v[80:81], off offset:1152
	global_load_dwordx4 v[166:169], v[78:79], off offset:1152
	s_waitcnt lgkmcnt(4)
	v_mfma_f32_32x32x16_bf16 v[48:63], v[88:91], v[92:95], v[48:63]
	s_waitcnt lgkmcnt(1)
	v_mfma_f32_32x32x16_bf16 v[32:47], v[88:91], v[106:109], v[32:47]
	ds_read_b128 v[88:91], v64 offset:41472
	ds_read_b128 v[114:117], v64 offset:41504
	s_waitcnt lgkmcnt(1)
	v_mfma_f32_32x32x16_bf16 v[16:31], v[88:91], v[92:95], v[16:31]
	v_mfma_f32_32x32x16_bf16 v[0:15], v[88:91], v[106:109], v[0:15]
	v_mfma_f32_32x32x16_bf16 v[48:63], v[98:101], v[102:105], v[48:63]
	v_mfma_f32_32x32x16_bf16 v[32:47], v[98:101], v[110:113], v[32:47]
	s_waitcnt lgkmcnt(0)
	v_mfma_f32_32x32x16_bf16 v[16:31], v[114:117], v[102:105], v[16:31]
	ds_read_b128 v[88:91], v64 offset:36928
	ds_read_b128 v[92:95], v83 offset:55360
	ds_read_b128 v[98:101], v64 offset:36960
	ds_read_b128 v[102:105], v83 offset:55392
	v_mfma_f32_32x32x16_bf16 v[0:15], v[114:117], v[110:113], v[0:15]
	ds_read_b128 v[106:109], v83 offset:59968
	ds_read_b128 v[110:113], v83 offset:60000
	s_waitcnt lgkmcnt(4)
	v_mfma_f32_32x32x16_bf16 v[48:63], v[88:91], v[92:95], v[48:63]
	s_waitcnt lgkmcnt(1)
	v_mfma_f32_32x32x16_bf16 v[32:47], v[88:91], v[106:109], v[32:47]
	ds_read_b128 v[88:91], v64 offset:41536
	ds_read_b128 v[114:117], v64 offset:41568
	s_waitcnt lgkmcnt(1)
	v_mfma_f32_32x32x16_bf16 v[16:31], v[88:91], v[92:95], v[16:31]
	v_mfma_f32_32x32x16_bf16 v[0:15], v[88:91], v[106:109], v[0:15]
	v_mfma_f32_32x32x16_bf16 v[48:63], v[98:101], v[102:105], v[48:63]
	v_mfma_f32_32x32x16_bf16 v[32:47], v[98:101], v[110:113], v[32:47]
	s_waitcnt lgkmcnt(0)
	v_mfma_f32_32x32x16_bf16 v[16:31], v[114:117], v[102:105], v[16:31]
	s_barrier
	s_waitcnt vmcnt(7)
	ds_write_b128 v82, v[138:141] offset:36864
	s_waitcnt vmcnt(6)
	ds_write_b128 v82, v[142:145] offset:55296
	s_waitcnt vmcnt(5)
	ds_write_b128 v82, v[146:149] offset:41472
	s_waitcnt vmcnt(4)
	ds_write_b128 v82, v[150:153] offset:59904
	s_waitcnt vmcnt(3)
	ds_write_b128 v82, v[154:157] offset:46080
	s_waitcnt vmcnt(2)
	ds_write_b128 v82, v[158:161] offset:64512
	s_waitcnt vmcnt(1)
	ds_write_b128 v82, v[162:165] offset:50688
	s_waitcnt vmcnt(0)
	ds_write_b128 v86, v[166:169] offset:13824
	v_mfma_f32_32x32x16_bf16 v[0:15], v[114:117], v[110:113], v[0:15]
	ds_read_b128 v[88:91], v64
	ds_read_b128 v[92:95], v83 offset:18432
	ds_read_b128 v[98:101], v64 offset:32
	ds_read_b128 v[102:105], v83 offset:18464
	ds_read_b128 v[106:109], v83 offset:23040
	ds_read_b128 v[110:113], v83 offset:23072
	global_load_dwordx4 v[138:141], v[66:67], off offset:1280
	global_load_dwordx4 v[142:145], v[68:69], off offset:1280
	global_load_dwordx4 v[146:149], v[70:71], off offset:1280
	global_load_dwordx4 v[150:153], v[72:73], off offset:1280
	global_load_dwordx4 v[154:157], v[74:75], off offset:1280
	global_load_dwordx4 v[158:161], v[76:77], off offset:1280
	global_load_dwordx4 v[162:165], v[80:81], off offset:1280
	global_load_dwordx4 v[166:169], v[78:79], off offset:1280
	s_waitcnt lgkmcnt(4)
	v_mfma_f32_32x32x16_bf16 v[48:63], v[88:91], v[92:95], v[48:63]
	s_waitcnt lgkmcnt(1)
	v_mfma_f32_32x32x16_bf16 v[32:47], v[88:91], v[106:109], v[32:47]
	ds_read_b128 v[88:91], v64 offset:4608
	ds_read_b128 v[114:117], v64 offset:4640
	s_waitcnt lgkmcnt(1)
	v_mfma_f32_32x32x16_bf16 v[16:31], v[88:91], v[92:95], v[16:31]
	v_mfma_f32_32x32x16_bf16 v[0:15], v[88:91], v[106:109], v[0:15]
	v_mfma_f32_32x32x16_bf16 v[48:63], v[98:101], v[102:105], v[48:63]
	v_mfma_f32_32x32x16_bf16 v[32:47], v[98:101], v[110:113], v[32:47]
	s_waitcnt lgkmcnt(0)
	v_mfma_f32_32x32x16_bf16 v[16:31], v[114:117], v[102:105], v[16:31]
	ds_read_b128 v[88:91], v64 offset:64
	ds_read_b128 v[92:95], v83 offset:18496
	ds_read_b128 v[98:101], v64 offset:96
	ds_read_b128 v[102:105], v83 offset:18528
	v_mfma_f32_32x32x16_bf16 v[0:15], v[114:117], v[110:113], v[0:15]
	ds_read_b128 v[106:109], v83 offset:23104
	ds_read_b128 v[110:113], v83 offset:23136
	s_waitcnt lgkmcnt(4)
	v_mfma_f32_32x32x16_bf16 v[48:63], v[88:91], v[92:95], v[48:63]
	s_waitcnt lgkmcnt(1)
	v_mfma_f32_32x32x16_bf16 v[32:47], v[88:91], v[106:109], v[32:47]
	ds_read_b128 v[88:91], v64 offset:4672
	ds_read_b128 v[114:117], v64 offset:4704
	s_waitcnt lgkmcnt(1)
	v_mfma_f32_32x32x16_bf16 v[16:31], v[88:91], v[92:95], v[16:31]
	v_mfma_f32_32x32x16_bf16 v[0:15], v[88:91], v[106:109], v[0:15]
	v_mfma_f32_32x32x16_bf16 v[48:63], v[98:101], v[102:105], v[48:63]
	v_mfma_f32_32x32x16_bf16 v[32:47], v[98:101], v[110:113], v[32:47]
	s_waitcnt lgkmcnt(0)
	v_mfma_f32_32x32x16_bf16 v[16:31], v[114:117], v[102:105], v[16:31]
	s_barrier
;     ...
;   bf16* As1 = As + 2 * 128 * 72;
;   bf16* Bs1 = As1 + 128 * 72;
;   G_LOAD(ra0, rb0, 0);
;   if (nk > 1) G_LOAD(ra1, rb1, 1);
;   G_STORE(ra0, rb0, As, Bs);
;   __syncthreads();
;   for (int kt = 0; kt < nk; kt += 2) {
;     if (kt + 2 < nk) G_LOAD(ra0, rb0, kt + 2);
;     if (kt + 1 < nk) G_STORE(ra1, rb1, As1, Bs1);
;     G_COMPUTE(As, Bs);
;     __syncthreads();
;     if (kt + 1 < nk) {
;       if (kt + 3 < nk) G_LOAD(ra1, rb1, kt + 3);
;       if (kt + 2 < nk) G_STORE(ra0, rb0, As, Bs);
;       G_COMPUTE(As1, Bs1);
;       __syncthreads();
;     }
;   }
	s_waitcnt vmcnt(7)
	ds_write_b128 v82, v[138:141]
	s_waitcnt vmcnt(6)
	ds_write_b128 v82, v[142:145] offset:18432
	s_waitcnt vmcnt(5)
	ds_write_b128 v82, v[146:149] offset:4608
	s_waitcnt vmcnt(4)
	ds_write_b128 v82, v[150:153] offset:23040
	s_waitcnt vmcnt(3)
	ds_write_b128 v82, v[154:157] offset:9216
	s_waitcnt vmcnt(2)
	ds_write_b128 v82, v[158:161] offset:27648
	s_waitcnt vmcnt(1)
	ds_write_b128 v82, v[162:165] offset:13824
	s_waitcnt vmcnt(0)
	ds_write_b128 v82, v[166:169] offset:32256
	v_mfma_f32_32x32x16_bf16 v[0:15], v[114:117], v[110:113], v[0:15]
	ds_read_b128 v[88:91], v64 offset:36864
	ds_read_b128 v[92:95], v83 offset:55296
	ds_read_b128 v[98:101], v64 offset:36896
	ds_read_b128 v[102:105], v83 offset:55328
	ds_read_b128 v[106:109], v83 offset:59904
	ds_read_b128 v[110:113], v83 offset:59936
	global_load_dwordx4 v[138:141], v[66:67], off offset:1408
	global_load_dwordx4 v[142:145], v[68:69], off offset:1408
	global_load_dwordx4 v[146:149], v[70:71], off offset:1408
	global_load_dwordx4 v[150:153], v[72:73], off offset:1408
	global_load_dwordx4 v[154:157], v[74:75], off offset:1408
	global_load_dwordx4 v[158:161], v[76:77], off offset:1408
	global_load_dwordx4 v[162:165], v[80:81], off offset:1408
	global_load_dwordx4 v[166:169], v[78:79], off offset:1408
	s_waitcnt lgkmcnt(4)
	v_mfma_f32_32x32x16_bf16 v[48:63], v[88:91], v[92:95], v[48:63]
	s_waitcnt lgkmcnt(1)
	v_mfma_f32_32x32x16_bf16 v[32:47], v[88:91], v[106:109], v[32:47]
	ds_read_b128 v[88:91], v64 offset:41472
	ds_read_b128 v[114:117], v64 offset:41504
	s_waitcnt lgkmcnt(1)
	v_mfma_f32_32x32x16_bf16 v[16:31], v[88:91], v[92:95], v[16:31]
	v_mfma_f32_32x32x16_bf16 v[0:15], v[88:91], v[106:109], v[0:15]
	v_mfma_f32_32x32x16_bf16 v[48:63], v[98:101], v[102:105], v[48:63]
	v_mfma_f32_32x32x16_bf16 v[32:47], v[98:101], v[110:113], v[32:47]
	s_waitcnt lgkmcnt(0)
	v_mfma_f32_32x32x16_bf16 v[16:31], v[114:117], v[102:105], v[16:31]
	ds_read_b128 v[88:91], v64 offset:36928
	ds_read_b128 v[92:95], v83 offset:55360
	ds_read_b128 v[98:101], v64 offset:36960
	ds_read_b128 v[102:105], v83 offset:55392
	v_mfma_f32_32x32x16_bf16 v[0:15], v[114:117], v[110:113], v[0:15]
	ds_read_b128 v[106:109], v83 offset:59968
	ds_read_b128 v[110:113], v83 offset:60000
	s_waitcnt lgkmcnt(4)
	v_mfma_f32_32x32x16_bf16 v[48:63], v[88:91], v[92:95], v[48:63]
	s_waitcnt lgkmcnt(1)
	v_mfma_f32_32x32x16_bf16 v[32:47], v[88:91], v[106:109], v[32:47]
	ds_read_b128 v[88:91], v64 offset:41536
	ds_read_b128 v[114:117], v64 offset:41568
	s_waitcnt lgkmcnt(1)
	v_mfma_f32_32x32x16_bf16 v[16:31], v[88:91], v[92:95], v[16:31]
	v_mfma_f32_32x32x16_bf16 v[0:15], v[88:91], v[106:109], v[0:15]
	v_mfma_f32_32x32x16_bf16 v[48:63], v[98:101], v[102:105], v[48:63]
	v_mfma_f32_32x32x16_bf16 v[32:47], v[98:101], v[110:113], v[32:47]
	s_waitcnt lgkmcnt(0)
	v_mfma_f32_32x32x16_bf16 v[16:31], v[114:117], v[102:105], v[16:31]
	s_barrier
	s_waitcnt vmcnt(7)
	ds_write_b128 v82, v[138:141] offset:36864
	s_waitcnt vmcnt(6)
	ds_write_b128 v82, v[142:145] offset:55296
	s_waitcnt vmcnt(5)
	ds_write_b128 v82, v[146:149] offset:41472
	s_waitcnt vmcnt(4)
	ds_write_b128 v82, v[150:153] offset:59904
	s_waitcnt vmcnt(3)
	ds_write_b128 v82, v[154:157] offset:46080
	s_waitcnt vmcnt(2)
	ds_write_b128 v82, v[158:161] offset:64512
	s_waitcnt vmcnt(1)
	ds_write_b128 v82, v[162:165] offset:50688
	s_waitcnt vmcnt(0)
	ds_write_b128 v86, v[166:169] offset:13824
	v_mfma_f32_32x32x16_bf16 v[0:15], v[114:117], v[110:113], v[0:15]
	ds_read_b128 v[88:91], v64
	ds_read_b128 v[92:95], v83 offset:18432
	ds_read_b128 v[98:101], v64 offset:32
	ds_read_b128 v[102:105], v83 offset:18464
	ds_read_b128 v[106:109], v83 offset:23040
	ds_read_b128 v[110:113], v83 offset:23072
	global_load_dwordx4 v[138:141], v[66:67], off offset:1536
	global_load_dwordx4 v[142:145], v[68:69], off offset:1536
	global_load_dwordx4 v[146:149], v[70:71], off offset:1536
	global_load_dwordx4 v[150:153], v[72:73], off offset:1536
	global_load_dwordx4 v[154:157], v[74:75], off offset:1536
	global_load_dwordx4 v[158:161], v[76:77], off offset:1536
	global_load_dwordx4 v[162:165], v[80:81], off offset:1536
	global_load_dwordx4 v[166:169], v[78:79], off offset:1536
	s_waitcnt lgkmcnt(4)
	v_mfma_f32_32x32x16_bf16 v[48:63], v[88:91], v[92:95], v[48:63]
	s_waitcnt lgkmcnt(1)
	v_mfma_f32_32x32x16_bf16 v[32:47], v[88:91], v[106:109], v[32:47]
	ds_read_b128 v[88:91], v64 offset:4608
	ds_read_b128 v[114:117], v64 offset:4640
	s_waitcnt lgkmcnt(1)
	v_mfma_f32_32x32x16_bf16 v[16:31], v[88:91], v[92:95], v[16:31]
	v_mfma_f32_32x32x16_bf16 v[0:15], v[88:91], v[106:109], v[0:15]
	v_mfma_f32_32x32x16_bf16 v[48:63], v[98:101], v[102:105], v[48:63]
	v_mfma_f32_32x32x16_bf16 v[32:47], v[98:101], v[110:113], v[32:47]
	s_waitcnt lgkmcnt(0)
	v_mfma_f32_32x32x16_bf16 v[16:31], v[114:117], v[102:105], v[16:31]
	ds_read_b128 v[88:91], v64 offset:64
	ds_read_b128 v[92:95], v83 offset:18496
	ds_read_b128 v[98:101], v64 offset:96
	ds_read_b128 v[102:105], v83 offset:18528
	v_mfma_f32_32x32x16_bf16 v[0:15], v[114:117], v[110:113], v[0:15]
	ds_read_b128 v[106:109], v83 offset:23104
	ds_read_b128 v[110:113], v83 offset:23136
	s_waitcnt lgkmcnt(4)
	v_mfma_f32_32x32x16_bf16 v[48:63], v[88:91], v[92:95], v[48:63]
	s_waitcnt lgkmcnt(1)
	v_mfma_f32_32x32x16_bf16 v[32:47], v[88:91], v[106:109], v[32:47]
	ds_read_b128 v[88:91], v64 offset:4672
	ds_read_b128 v[114:117], v64 offset:4704
	s_waitcnt lgkmcnt(1)
	v_mfma_f32_32x32x16_bf16 v[16:31], v[88:91], v[92:95], v[16:31]
	v_mfma_f32_32x32x16_bf16 v[0:15], v[88:91], v[106:109], v[0:15]
	v_mfma_f32_32x32x16_bf16 v[48:63], v[98:101], v[102:105], v[48:63]
	v_mfma_f32_32x32x16_bf16 v[32:47], v[98:101], v[110:113], v[32:47]
	s_waitcnt lgkmcnt(0)
	v_mfma_f32_32x32x16_bf16 v[16:31], v[114:117], v[102:105], v[16:31]
	s_barrier
;     ...
;   bf16* As1 = As + 2 * 128 * 72;
;   bf16* Bs1 = As1 + 128 * 72;
;   G_LOAD(ra0, rb0, 0);
;   if (nk > 1) G_LOAD(ra1, rb1, 1);
;   G_STORE(ra0, rb0, As, Bs);
;   __syncthreads();
;   for (int kt = 0; kt < nk; kt += 2) {
;     if (kt + 2 < nk) G_LOAD(ra0, rb0, kt + 2);
;     if (kt + 1 < nk) G_STORE(ra1, rb1, As1, Bs1);
;     G_COMPUTE(As, Bs);
;     __syncthreads();
;     if (kt + 1 < nk) {
;       if (kt + 3 < nk) G_LOAD(ra1, rb1, kt + 3);
;       if (kt + 2 < nk) G_STORE(ra0, rb0, As, Bs);
;       G_COMPUTE(As1, Bs1);
;       __syncthreads();
;     }
;   }
	s_waitcnt vmcnt(7)
	ds_write_b128 v82, v[138:141]
	s_waitcnt vmcnt(6)
	ds_write_b128 v82, v[142:145] offset:18432
	s_waitcnt vmcnt(5)
	ds_write_b128 v82, v[146:149] offset:4608
	s_waitcnt vmcnt(4)
	ds_write_b128 v82, v[150:153] offset:23040
	s_waitcnt vmcnt(3)
	ds_write_b128 v82, v[154:157] offset:9216
	s_waitcnt vmcnt(2)
	ds_write_b128 v82, v[158:161] offset:27648
	s_waitcnt vmcnt(1)
	ds_write_b128 v82, v[162:165] offset:13824
	s_waitcnt vmcnt(0)
	ds_write_b128 v82, v[166:169] offset:32256
	v_mfma_f32_32x32x16_bf16 v[0:15], v[114:117], v[110:113], v[0:15]
	ds_read_b128 v[88:91], v64 offset:36864
	ds_read_b128 v[92:95], v83 offset:55296
	ds_read_b128 v[98:101], v64 offset:36896
	ds_read_b128 v[102:105], v83 offset:55328
	ds_read_b128 v[106:109], v83 offset:59904
	ds_read_b128 v[110:113], v83 offset:59936
	global_load_dwordx4 v[138:141], v[66:67], off offset:1664
	global_load_dwordx4 v[142:145], v[68:69], off offset:1664
	global_load_dwordx4 v[146:149], v[70:71], off offset:1664
	global_load_dwordx4 v[150:153], v[72:73], off offset:1664
	global_load_dwordx4 v[154:157], v[74:75], off offset:1664
	global_load_dwordx4 v[158:161], v[76:77], off offset:1664
	global_load_dwordx4 v[162:165], v[80:81], off offset:1664
	global_load_dwordx4 v[166:169], v[78:79], off offset:1664
	s_waitcnt lgkmcnt(4)
	v_mfma_f32_32x32x16_bf16 v[48:63], v[88:91], v[92:95], v[48:63]
	s_waitcnt lgkmcnt(1)
	v_mfma_f32_32x32x16_bf16 v[32:47], v[88:91], v[106:109], v[32:47]
	ds_read_b128 v[88:91], v64 offset:41472
	ds_read_b128 v[114:117], v64 offset:41504
	s_waitcnt lgkmcnt(1)
	v_mfma_f32_32x32x16_bf16 v[16:31], v[88:91], v[92:95], v[16:31]
	v_mfma_f32_32x32x16_bf16 v[0:15], v[88:91], v[106:109], v[0:15]
	v_mfma_f32_32x32x16_bf16 v[48:63], v[98:101], v[102:105], v[48:63]
	v_mfma_f32_32x32x16_bf16 v[32:47], v[98:101], v[110:113], v[32:47]
	s_waitcnt lgkmcnt(0)
	v_mfma_f32_32x32x16_bf16 v[16:31], v[114:117], v[102:105], v[16:31]
	ds_read_b128 v[88:91], v64 offset:36928
	ds_read_b128 v[92:95], v83 offset:55360
	ds_read_b128 v[98:101], v64 offset:36960
	ds_read_b128 v[102:105], v83 offset:55392
	v_mfma_f32_32x32x16_bf16 v[0:15], v[114:117], v[110:113], v[0:15]
	ds_read_b128 v[106:109], v83 offset:59968
	ds_read_b128 v[110:113], v83 offset:60000
	s_waitcnt lgkmcnt(4)
	v_mfma_f32_32x32x16_bf16 v[48:63], v[88:91], v[92:95], v[48:63]
	s_waitcnt lgkmcnt(1)
	v_mfma_f32_32x32x16_bf16 v[32:47], v[88:91], v[106:109], v[32:47]
	ds_read_b128 v[88:91], v64 offset:41536
	ds_read_b128 v[114:117], v64 offset:41568
	s_waitcnt lgkmcnt(1)
	v_mfma_f32_32x32x16_bf16 v[16:31], v[88:91], v[92:95], v[16:31]
	v_mfma_f32_32x32x16_bf16 v[0:15], v[88:91], v[106:109], v[0:15]
	v_mfma_f32_32x32x16_bf16 v[48:63], v[98:101], v[102:105], v[48:63]
	v_mfma_f32_32x32x16_bf16 v[32:47], v[98:101], v[110:113], v[32:47]
	s_waitcnt lgkmcnt(0)
	v_mfma_f32_32x32x16_bf16 v[16:31], v[114:117], v[102:105], v[16:31]
	s_barrier
	s_waitcnt vmcnt(7)
	ds_write_b128 v82, v[138:141] offset:36864
	s_waitcnt vmcnt(6)
	ds_write_b128 v82, v[142:145] offset:55296
	s_waitcnt vmcnt(5)
	ds_write_b128 v82, v[146:149] offset:41472
	s_waitcnt vmcnt(4)
	ds_write_b128 v82, v[150:153] offset:59904
	s_waitcnt vmcnt(3)
	ds_write_b128 v82, v[154:157] offset:46080
	s_waitcnt vmcnt(2)
	ds_write_b128 v82, v[158:161] offset:64512
	s_waitcnt vmcnt(1)
	ds_write_b128 v82, v[162:165] offset:50688
	s_waitcnt vmcnt(0)
	ds_write_b128 v86, v[166:169] offset:13824
	v_mfma_f32_32x32x16_bf16 v[0:15], v[114:117], v[110:113], v[0:15]
	ds_read_b128 v[88:91], v64
	ds_read_b128 v[92:95], v83 offset:18432
	ds_read_b128 v[98:101], v64 offset:32
	ds_read_b128 v[102:105], v83 offset:18464
	ds_read_b128 v[106:109], v83 offset:23040
	ds_read_b128 v[110:113], v83 offset:23072
	global_load_dwordx4 v[138:141], v[66:67], off offset:1792
	global_load_dwordx4 v[142:145], v[68:69], off offset:1792
	global_load_dwordx4 v[146:149], v[70:71], off offset:1792
	global_load_dwordx4 v[150:153], v[72:73], off offset:1792
	global_load_dwordx4 v[154:157], v[74:75], off offset:1792
	global_load_dwordx4 v[158:161], v[76:77], off offset:1792
	global_load_dwordx4 v[162:165], v[80:81], off offset:1792
	global_load_dwordx4 v[166:169], v[78:79], off offset:1792
	s_waitcnt lgkmcnt(4)
	v_mfma_f32_32x32x16_bf16 v[48:63], v[88:91], v[92:95], v[48:63]
	s_waitcnt lgkmcnt(1)
	v_mfma_f32_32x32x16_bf16 v[32:47], v[88:91], v[106:109], v[32:47]
	ds_read_b128 v[88:91], v64 offset:4608
	ds_read_b128 v[114:117], v64 offset:4640
	s_waitcnt lgkmcnt(1)
	v_mfma_f32_32x32x16_bf16 v[16:31], v[88:91], v[92:95], v[16:31]
	v_mfma_f32_32x32x16_bf16 v[0:15], v[88:91], v[106:109], v[0:15]
	v_mfma_f32_32x32x16_bf16 v[48:63], v[98:101], v[102:105], v[48:63]
	v_mfma_f32_32x32x16_bf16 v[32:47], v[98:101], v[110:113], v[32:47]
	s_waitcnt lgkmcnt(0)
	v_mfma_f32_32x32x16_bf16 v[16:31], v[114:117], v[102:105], v[16:31]
	ds_read_b128 v[88:91], v64 offset:64
	ds_read_b128 v[92:95], v83 offset:18496
	ds_read_b128 v[98:101], v64 offset:96
	ds_read_b128 v[102:105], v83 offset:18528
	v_mfma_f32_32x32x16_bf16 v[0:15], v[114:117], v[110:113], v[0:15]
	ds_read_b128 v[106:109], v83 offset:23104
	ds_read_b128 v[110:113], v83 offset:23136
	s_waitcnt lgkmcnt(4)
	v_mfma_f32_32x32x16_bf16 v[48:63], v[88:91], v[92:95], v[48:63]
	s_waitcnt lgkmcnt(1)
	v_mfma_f32_32x32x16_bf16 v[32:47], v[88:91], v[106:109], v[32:47]
	ds_read_b128 v[88:91], v64 offset:4672
	ds_read_b128 v[114:117], v64 offset:4704
	s_waitcnt lgkmcnt(1)
	v_mfma_f32_32x32x16_bf16 v[16:31], v[88:91], v[92:95], v[16:31]
	v_mfma_f32_32x32x16_bf16 v[0:15], v[88:91], v[106:109], v[0:15]
	v_mfma_f32_32x32x16_bf16 v[48:63], v[98:101], v[102:105], v[48:63]
	v_mfma_f32_32x32x16_bf16 v[32:47], v[98:101], v[110:113], v[32:47]
	s_waitcnt lgkmcnt(0)
	v_mfma_f32_32x32x16_bf16 v[16:31], v[114:117], v[102:105], v[16:31]
	s_barrier
;     ...
;   bf16* As1 = As + 2 * 128 * 72;
;   bf16* Bs1 = As1 + 128 * 72;
;   G_LOAD(ra0, rb0, 0);
;   if (nk > 1) G_LOAD(ra1, rb1, 1);
;   G_STORE(ra0, rb0, As, Bs);
;   __syncthreads();
;   for (int kt = 0; kt < nk; kt += 2) {
;     if (kt + 2 < nk) G_LOAD(ra0, rb0, kt + 2);
;     if (kt + 1 < nk) G_STORE(ra1, rb1, As1, Bs1);
;     G_COMPUTE(As, Bs);
;     __syncthreads();
;     if (kt + 1 < nk) {
;       if (kt + 3 < nk) G_LOAD(ra1, rb1, kt + 3);
;       if (kt + 2 < nk) G_STORE(ra0, rb0, As, Bs);
;       G_COMPUTE(As1, Bs1);
;       __syncthreads();
;     }
;   }
	s_waitcnt vmcnt(7)
	ds_write_b128 v82, v[138:141]
	s_waitcnt vmcnt(6)
	ds_write_b128 v82, v[142:145] offset:18432
	s_waitcnt vmcnt(5)
	ds_write_b128 v82, v[146:149] offset:4608
	s_waitcnt vmcnt(4)
	ds_write_b128 v82, v[150:153] offset:23040
	s_waitcnt vmcnt(3)
	ds_write_b128 v82, v[154:157] offset:9216
	s_waitcnt vmcnt(2)
	ds_write_b128 v82, v[158:161] offset:27648
	s_waitcnt vmcnt(1)
	ds_write_b128 v82, v[162:165] offset:13824
	s_waitcnt vmcnt(0)
	ds_write_b128 v82, v[166:169] offset:32256
	v_mfma_f32_32x32x16_bf16 v[0:15], v[114:117], v[110:113], v[0:15]
	ds_read_b128 v[88:91], v64 offset:36864
	ds_read_b128 v[92:95], v83 offset:55296
	ds_read_b128 v[98:101], v64 offset:36896
	ds_read_b128 v[102:105], v83 offset:55328
	ds_read_b128 v[106:109], v83 offset:59904
	ds_read_b128 v[110:113], v83 offset:59936
	global_load_dwordx4 v[138:141], v[66:67], off offset:1920
	global_load_dwordx4 v[142:145], v[68:69], off offset:1920
	global_load_dwordx4 v[146:149], v[70:71], off offset:1920
	global_load_dwordx4 v[150:153], v[72:73], off offset:1920
	global_load_dwordx4 v[154:157], v[74:75], off offset:1920
	global_load_dwordx4 v[158:161], v[76:77], off offset:1920
	global_load_dwordx4 v[162:165], v[80:81], off offset:1920
	global_load_dwordx4 v[166:169], v[78:79], off offset:1920
	s_waitcnt lgkmcnt(4)
	v_mfma_f32_32x32x16_bf16 v[48:63], v[88:91], v[92:95], v[48:63]
	s_waitcnt lgkmcnt(1)
	v_mfma_f32_32x32x16_bf16 v[32:47], v[88:91], v[106:109], v[32:47]
	ds_read_b128 v[88:91], v64 offset:41472
	ds_read_b128 v[114:117], v64 offset:41504
	s_waitcnt lgkmcnt(1)
	v_mfma_f32_32x32x16_bf16 v[16:31], v[88:91], v[92:95], v[16:31]
	v_mfma_f32_32x32x16_bf16 v[0:15], v[88:91], v[106:109], v[0:15]
	v_mfma_f32_32x32x16_bf16 v[48:63], v[98:101], v[102:105], v[48:63]
	v_mfma_f32_32x32x16_bf16 v[32:47], v[98:101], v[110:113], v[32:47]
	s_waitcnt lgkmcnt(0)
	v_mfma_f32_32x32x16_bf16 v[16:31], v[114:117], v[102:105], v[16:31]
	ds_read_b128 v[88:91], v64 offset:36928
	ds_read_b128 v[92:95], v83 offset:55360
	ds_read_b128 v[98:101], v64 offset:36960
	ds_read_b128 v[102:105], v83 offset:55392
	v_mfma_f32_32x32x16_bf16 v[0:15], v[114:117], v[110:113], v[0:15]
	ds_read_b128 v[106:109], v83 offset:59968
	ds_read_b128 v[110:113], v83 offset:60000
	s_waitcnt lgkmcnt(4)
	v_mfma_f32_32x32x16_bf16 v[48:63], v[88:91], v[92:95], v[48:63]
	s_waitcnt lgkmcnt(1)
	v_mfma_f32_32x32x16_bf16 v[32:47], v[88:91], v[106:109], v[32:47]
	ds_read_b128 v[88:91], v64 offset:41536
	ds_read_b128 v[114:117], v64 offset:41568
	s_waitcnt lgkmcnt(1)
	v_mfma_f32_32x32x16_bf16 v[16:31], v[88:91], v[92:95], v[16:31]
	v_mfma_f32_32x32x16_bf16 v[0:15], v[88:91], v[106:109], v[0:15]
	v_mfma_f32_32x32x16_bf16 v[48:63], v[98:101], v[102:105], v[48:63]
	v_mfma_f32_32x32x16_bf16 v[32:47], v[98:101], v[110:113], v[32:47]
	s_nop 0
	s_nop 0
	s_nop 0
	s_nop 0
	s_nop 0
	s_nop 0
	s_nop 0
	s_waitcnt lgkmcnt(0)
	s_barrier
	s_waitcnt vmcnt(7)
	ds_write_b128 v82, v[138:141] offset:36864
	s_waitcnt vmcnt(6)
	ds_write_b128 v82, v[142:145] offset:55296
	s_waitcnt vmcnt(5)
	ds_write_b128 v82, v[146:149] offset:41472
	s_waitcnt vmcnt(4)
	ds_write_b128 v82, v[150:153] offset:59904
	s_waitcnt vmcnt(3)
	ds_write_b128 v82, v[154:157] offset:46080
	s_waitcnt vmcnt(2)
	ds_write_b128 v82, v[158:161] offset:64512
	s_waitcnt vmcnt(1)
	ds_write_b128 v82, v[162:165] offset:50688
	s_waitcnt vmcnt(0)
	ds_write_b128 v86, v[166:169] offset:13824
	v_mfma_f32_32x32x16_bf16 v[16:31], v[114:117], v[102:105], v[16:31]
	ds_read_b128 v[66:69], v64
	ds_read_b128 v[70:73], v83 offset:18432
	ds_read_b128 v[74:77], v64 offset:32
	ds_read_b128 v[78:81], v83 offset:18464
	ds_read_b128 v[86:89], v83 offset:23040
	ds_read_b128 v[90:93], v83 offset:23072
	v_mfma_f32_32x32x16_bf16 v[0:15], v[114:117], v[110:113], v[0:15]
	s_waitcnt lgkmcnt(4)
	v_mfma_f32_32x32x16_bf16 v[48:63], v[66:69], v[70:73], v[48:63]
	s_waitcnt lgkmcnt(1)
	v_mfma_f32_32x32x16_bf16 v[32:47], v[66:69], v[86:89], v[32:47]
	ds_read_b128 v[66:69], v64 offset:4608
	ds_read_b128 v[98:101], v64 offset:4640
	s_waitcnt lgkmcnt(1)
	v_mfma_f32_32x32x16_bf16 v[16:31], v[66:69], v[70:73], v[16:31]
	v_mfma_f32_32x32x16_bf16 v[0:15], v[66:69], v[86:89], v[0:15]
	v_mfma_f32_32x32x16_bf16 v[48:63], v[74:77], v[78:81], v[48:63]
	v_mfma_f32_32x32x16_bf16 v[32:47], v[74:77], v[90:93], v[32:47]
	s_waitcnt lgkmcnt(0)
	v_mfma_f32_32x32x16_bf16 v[16:31], v[98:101], v[78:81], v[16:31]
	ds_read_b128 v[66:69], v64 offset:64
	ds_read_b128 v[70:73], v83 offset:18496
	ds_read_b128 v[74:77], v64 offset:96
	ds_read_b128 v[78:81], v83 offset:18528
	v_mfma_f32_32x32x16_bf16 v[0:15], v[98:101], v[90:93], v[0:15]
	ds_read_b128 v[86:89], v83 offset:23104
	ds_read_b128 v[90:93], v83 offset:23136
	s_waitcnt lgkmcnt(4)
	v_mfma_f32_32x32x16_bf16 v[48:63], v[66:69], v[70:73], v[48:63]
	s_waitcnt lgkmcnt(1)
	v_mfma_f32_32x32x16_bf16 v[32:47], v[66:69], v[86:89], v[32:47]
	ds_read_b128 v[66:69], v64 offset:4672
	ds_read_b128 v[98:101], v64 offset:4704
	s_waitcnt lgkmcnt(0)
	s_barrier
; #define PW(T, off) ((T*)(lndp(p.ws) + (off)))
; DEVI float bf2f(bf16 h) { return __uint_as_float(((unsigned)h) << 16); }
; DEVI int accrow(int r, int lane) { return (r & 3) + 8 * (r >> 2) + 4 * (lane >> 5); }
; template <int EPI>
; DEVI void gemm_epi(const Params& p, const GJob& jb, f32x16 (&acc)[2][2], int rbase, int cbase, int lane) {
;     ...
; #pragma unroll
;   for (int i = 0; i < 2; ++i) {
; #pragma unroll
;     for (int r = 0; r < 16; ++r) {
;       const int row = rbase + i * 32 + accrow(r, lane);
;       if (row < M) {
; #pragma unroll
;         for (int j = 0; j < 2; ++j) {
;           const int col = cbase + j * 32 + (lane & 31);
;           const float v = acc[i][j][r];
;           if (EPI == EPI_SSD_IN) {
;             if (col < 2048) ((bf16*)(ar + S_ZB))[(size_t)row * 2048 + col] = f2bf(v);
;             else if (col < 6144) ((bf16*)(ar + S_XBC))[(size_t)row * 4096 + col - 2048] = f2bf(v);
;             else if (col < 6176) ((float*)(ar + S_DTRAW))[(size_t)row * 32 + col - 6144] = v;
;           } else if (EPI == EPI_RESID) {
;             PW(bf16, W_Z)[(size_t)row * 1024 + col] = f2bf(ALPHA * bf2f(PW(bf16, W_Xb)[(size_t)row * 1024 + col]) + v);
;     ...
;   for (int kt = 0; kt < nk; kt += 2) {
;     if (kt + 2 < nk) G_LOAD(ra0, rb0, kt + 2);
;     if (kt + 1 < nk) G_STORE(ra1, rb1, As1, Bs1);
;     G_COMPUTE(As, Bs);
;     __syncthreads();
;     if (kt + 1 < nk) {
;       if (kt + 3 < nk) G_LOAD(ra1, rb1, kt + 3);
;       if (kt + 2 < nk) G_STORE(ra0, rb0, As, Bs);
;       G_COMPUTE(As1, Bs1);
;       __syncthreads();
;     }
;   }
	v_mfma_f32_32x32x16_bf16 v[16:31], v[66:69], v[70:73], v[16:31]
	v_mfma_f32_32x32x16_bf16 v[48:63], v[74:77], v[78:81], v[48:63]
	v_mfma_f32_32x32x16_bf16 v[32:47], v[74:77], v[90:93], v[32:47]
	v_mfma_f32_32x32x16_bf16 v[0:15], v[66:69], v[86:89], v[0:15]
	v_mfma_f32_32x32x16_bf16 v[16:31], v[98:101], v[78:81], v[16:31]
	ds_read_b128 v[66:69], v64 offset:36864
	ds_read_b128 v[70:73], v83 offset:55296
	ds_read_b128 v[74:77], v83 offset:55328
	ds_read_b128 v[78:81], v64 offset:36896
	ds_read_b128 v[86:89], v83 offset:59904
	s_waitcnt lgkmcnt(3)
	v_mfma_f32_32x32x16_bf16 v[48:63], v[66:69], v[70:73], v[48:63]
	s_waitcnt lgkmcnt(0)
	v_mfma_f32_32x32x16_bf16 v[32:47], v[66:69], v[86:89], v[32:47]
	ds_read_b128 v[66:69], v64 offset:41472
	v_mfma_f32_32x32x16_bf16 v[0:15], v[98:101], v[90:93], v[0:15]
	s_waitcnt lgkmcnt(0)
	v_mfma_f32_32x32x16_bf16 v[16:31], v[66:69], v[70:73], v[16:31]
	ds_read_b128 v[70:73], v64 offset:41504
	v_mfma_f32_32x32x16_bf16 v[0:15], v[66:69], v[86:89], v[0:15]
	ds_read_b128 v[66:69], v83 offset:59936
	v_mfma_f32_32x32x16_bf16 v[48:63], v[78:81], v[74:77], v[48:63]
	s_waitcnt lgkmcnt(0)
	v_mfma_f32_32x32x16_bf16 v[32:47], v[78:81], v[66:69], v[32:47]
	v_mfma_f32_32x32x16_bf16 v[16:31], v[70:73], v[74:77], v[16:31]
	v_mfma_f32_32x32x16_bf16 v[0:15], v[70:73], v[66:69], v[0:15]
	ds_read_b128 v[66:69], v64 offset:36928
	ds_read_b128 v[70:73], v83 offset:55360
	ds_read_b128 v[74:77], v83 offset:59968
	s_waitcnt lgkmcnt(1)
	v_mfma_f32_32x32x16_bf16 v[48:63], v[66:69], v[70:73], v[48:63]
	s_waitcnt lgkmcnt(0)
	v_mfma_f32_32x32x16_bf16 v[32:47], v[66:69], v[74:77], v[32:47]
	ds_read_b128 v[66:69], v64 offset:41536
	s_waitcnt lgkmcnt(0)
	v_mfma_f32_32x32x16_bf16 v[16:31], v[66:69], v[70:73], v[16:31]
	ds_read_b128 v[78:81], v83 offset:60000
	ds_read_b128 v[86:89], v83 offset:55392
	ds_read_b128 v[90:93], v64 offset:41568
	ds_read_b128 v[70:73], v64 offset:36960
	s_waitcnt lgkmcnt(0)
	s_barrier
	s_ashr_i32 s15, s14, 31
	s_lshl_b64 s[14:15], s[14:15], 3
	v_mfma_f32_32x32x16_bf16 v[0:15], v[66:69], v[74:77], v[0:15]
	s_add_u32 s14, s0, s14
	s_addc_u32 s15, s1, s15
	s_load_dwordx2 s[14:15], s[14:15], 0x0
	s_waitcnt lgkmcnt(0)
	s_mov_b32 s14, 26
	s_ashr_i32 s15, s14, 31
	v_mfma_f32_32x32x16_bf16 v[48:63], v[70:73], v[86:89], v[48:63]
	s_lshl_b64 s[14:15], s[14:15], 3
	s_add_u32 s14, s0, s14
	s_addc_u32 s15, s1, s15
	s_load_dwordx2 s[14:15], s[14:15], 0x0
	v_or_b32_e32 v66, s2, v65
	s_waitcnt lgkmcnt(0)
	v_or_b32_e32 v64, 32, v66
	v_mfma_f32_32x32x16_bf16 v[32:47], v[70:73], v[78:81], v[32:47]
	v_lshrrev_b32_e32 v72, 3, v84
	v_add_u32_e32 v70, s3, v85
	v_and_b32_e32 v71, 4, v72
	v_or_b32_e32 v68, v70, v71
	s_mov_b64 s[14:15], s[74:75]
	v_cmp_gt_i32_e32 vcc, s90, v68
	v_ashrrev_i32_e32 v67, 31, v66
	v_mfma_f32_32x32x16_bf16 v[16:31], v[90:93], v[86:89], v[16:31]
	v_ashrrev_i32_e32 v65, 31, v64
	v_mfma_f32_32x32x16_bf16 v[0:15], v[90:93], v[78:81], v[0:15]
	s_add_u32 s94, s74, 0xf724000
	s_addc_u32 s95, s75, 0
	s_add_u32 s96, s74, 0xb5a4000
	s_addc_u32 s97, s75, 0
	v_lshlrev_b32_e32 v115, 1, v66
	v_lshl_add_u32 v116, v68, 11, v115
	v_mov_b32_e32 v98, v116
	v_add_u32_e32 v99, 0x1000, v116
	v_add_u32_e32 v100, 0x4000, v116
	v_add_u32_e32 v101, 0x5000, v116
	v_add_u32_e32 v102, 0x8000, v116
	v_add_u32_e32 v103, 0x9000, v116
	v_add_u32_e32 v104, 0xc000, v116
	v_add_u32_e32 v105, 0xd000, v116
	v_add_u32_e32 v106, 0x10000, v116
	v_add_u32_e32 v107, 0x11000, v116
	v_add_u32_e32 v108, 0x14000, v116
	v_add_u32_e32 v109, 0x15000, v116
	v_add_u32_e32 v110, 0x18000, v116
	v_add_u32_e32 v111, 0x19000, v116
	v_add_u32_e32 v112, 0x1c000, v116
	v_add_u32_e32 v113, 0x1d000, v116
	global_load_ushort v64, v98, s[94:95]
	global_load_ushort v65, v98, s[94:95] offset:64
	global_load_ushort v66, v98, s[94:95] offset:2048
	global_load_ushort v67, v98, s[94:95] offset:2112
	global_load_ushort v68, v99, s[94:95]
	global_load_ushort v69, v99, s[94:95] offset:64
	global_load_ushort v70, v99, s[94:95] offset:2048
	global_load_ushort v71, v99, s[94:95] offset:2112
	global_load_ushort v72, v100, s[94:95]
	global_load_ushort v73, v100, s[94:95] offset:64
	global_load_ushort v74, v100, s[94:95] offset:2048
	global_load_ushort v75, v100, s[94:95] offset:2112
	global_load_ushort v76, v101, s[94:95]
	global_load_ushort v77, v101, s[94:95] offset:64
	global_load_ushort v78, v101, s[94:95] offset:2048
	global_load_ushort v79, v101, s[94:95] offset:2112
	global_load_ushort v80, v102, s[94:95]
	global_load_ushort v81, v102, s[94:95] offset:64
	global_load_ushort v82, v102, s[94:95] offset:2048
	global_load_ushort v83, v102, s[94:95] offset:2112
	global_load_ushort v84, v103, s[94:95]
	global_load_ushort v85, v103, s[94:95] offset:64
	global_load_ushort v86, v103, s[94:95] offset:2048
	global_load_ushort v87, v103, s[94:95] offset:2112
	global_load_ushort v88, v104, s[94:95]
	global_load_ushort v89, v104, s[94:95] offset:64
	global_load_ushort v90, v104, s[94:95] offset:2048
	global_load_ushort v91, v104, s[94:95] offset:2112
	global_load_ushort v92, v105, s[94:95]
	global_load_ushort v93, v105, s[94:95] offset:64
	global_load_ushort v94, v105, s[94:95] offset:2048
	global_load_ushort v95, v105, s[94:95] offset:2112
	s_waitcnt vmcnt(31)
	v_lshlrev_b32_e32 v64, 16, v64
	v_fmamk_f32 v48, v64, 0x3fd744fd, v48
	v_cvt_pk_bf16_f32 v48, v48, s0
	s_waitcnt vmcnt(30)
	v_lshlrev_b32_e32 v65, 16, v65
	v_fmamk_f32 v32, v65, 0x3fd744fd, v32
	v_cvt_pk_bf16_f32 v32, v32, s0
	s_waitcnt vmcnt(29)
	v_lshlrev_b32_e32 v66, 16, v66
	v_fmamk_f32 v49, v66, 0x3fd744fd, v49
	v_cvt_pk_bf16_f32 v49, v49, s0
	s_waitcnt vmcnt(28)
	v_lshlrev_b32_e32 v67, 16, v67
	v_fmamk_f32 v33, v67, 0x3fd744fd, v33
	v_cvt_pk_bf16_f32 v33, v33, s0
	s_waitcnt vmcnt(27)
; #define PW(T, off) ((T*)(lndp(p.ws) + (off)))
; DEVI float bf2f(bf16 h) { return __uint_as_float(((unsigned)h) << 16); }
; DEVI int accrow(int r, int lane) { return (r & 3) + 8 * (r >> 2) + 4 * (lane >> 5); }
; template <int EPI>
; DEVI void gemm_epi(const Params& p, const GJob& jb, f32x16 (&acc)[2][2], int rbase, int cbase, int lane) {
;     ...
; #pragma unroll
;   for (int i = 0; i < 2; ++i) {
; #pragma unroll
;     for (int r = 0; r < 16; ++r) {
;       const int row = rbase + i * 32 + accrow(r, lane);
;       if (row < M) {
; #pragma unroll
;         for (int j = 0; j < 2; ++j) {
;           const int col = cbase + j * 32 + (lane & 31);
;           const float v = acc[i][j][r];
;           if (EPI == EPI_SSD_IN) {
;             if (col < 2048) ((bf16*)(ar + S_ZB))[(size_t)row * 2048 + col] = f2bf(v);
;             else if (col < 6144) ((bf16*)(ar + S_XBC))[(size_t)row * 4096 + col - 2048] = f2bf(v);
;             else if (col < 6176) ((float*)(ar + S_DTRAW))[(size_t)row * 32 + col - 6144] = v;
;           } else if (EPI == EPI_RESID) {
;             PW(bf16, W_Z)[(size_t)row * 1024 + col] = f2bf(ALPHA * bf2f(PW(bf16, W_Xb)[(size_t)row * 1024 + col]) + v);
	v_lshlrev_b32_e32 v68, 16, v68
	v_fmamk_f32 v50, v68, 0x3fd744fd, v50
	v_cvt_pk_bf16_f32 v50, v50, s0
	s_waitcnt vmcnt(26)
	v_lshlrev_b32_e32 v69, 16, v69
	v_fmamk_f32 v34, v69, 0x3fd744fd, v34
	v_cvt_pk_bf16_f32 v34, v34, s0
	s_waitcnt vmcnt(25)
	v_lshlrev_b32_e32 v70, 16, v70
	v_fmamk_f32 v51, v70, 0x3fd744fd, v51
	v_cvt_pk_bf16_f32 v51, v51, s0
	s_waitcnt vmcnt(24)
	v_lshlrev_b32_e32 v71, 16, v71
	v_fmamk_f32 v35, v71, 0x3fd744fd, v35
	v_cvt_pk_bf16_f32 v35, v35, s0
	s_waitcnt vmcnt(23)
	v_lshlrev_b32_e32 v72, 16, v72
	v_fmamk_f32 v52, v72, 0x3fd744fd, v52
	v_cvt_pk_bf16_f32 v52, v52, s0
	s_waitcnt vmcnt(22)
	v_lshlrev_b32_e32 v73, 16, v73
	v_fmamk_f32 v36, v73, 0x3fd744fd, v36
	v_cvt_pk_bf16_f32 v36, v36, s0
	s_waitcnt vmcnt(21)
	v_lshlrev_b32_e32 v74, 16, v74
	v_fmamk_f32 v53, v74, 0x3fd744fd, v53
	v_cvt_pk_bf16_f32 v53, v53, s0
	s_waitcnt vmcnt(20)
	v_lshlrev_b32_e32 v75, 16, v75
	v_fmamk_f32 v37, v75, 0x3fd744fd, v37
	v_cvt_pk_bf16_f32 v37, v37, s0
	s_waitcnt vmcnt(19)
	v_lshlrev_b32_e32 v76, 16, v76
	v_fmamk_f32 v54, v76, 0x3fd744fd, v54
	v_cvt_pk_bf16_f32 v54, v54, s0
	s_waitcnt vmcnt(18)
	v_lshlrev_b32_e32 v77, 16, v77
	v_fmamk_f32 v38, v77, 0x3fd744fd, v38
	v_cvt_pk_bf16_f32 v38, v38, s0
	s_waitcnt vmcnt(17)
	v_lshlrev_b32_e32 v78, 16, v78
	v_fmamk_f32 v55, v78, 0x3fd744fd, v55
	v_cvt_pk_bf16_f32 v55, v55, s0
	s_waitcnt vmcnt(16)
	v_lshlrev_b32_e32 v79, 16, v79
	v_fmamk_f32 v39, v79, 0x3fd744fd, v39
	v_cvt_pk_bf16_f32 v39, v39, s0
	s_waitcnt vmcnt(15)
	v_lshlrev_b32_e32 v80, 16, v80
	v_fmamk_f32 v56, v80, 0x3fd744fd, v56
	v_cvt_pk_bf16_f32 v56, v56, s0
	s_waitcnt vmcnt(14)
	v_lshlrev_b32_e32 v81, 16, v81
	v_fmamk_f32 v40, v81, 0x3fd744fd, v40
	v_cvt_pk_bf16_f32 v40, v40, s0
	s_waitcnt vmcnt(13)
	v_lshlrev_b32_e32 v82, 16, v82
	v_fmamk_f32 v57, v82, 0x3fd744fd, v57
	v_cvt_pk_bf16_f32 v57, v57, s0
	s_waitcnt vmcnt(12)
	v_lshlrev_b32_e32 v83, 16, v83
	v_fmamk_f32 v41, v83, 0x3fd744fd, v41
	v_cvt_pk_bf16_f32 v41, v41, s0
	s_waitcnt vmcnt(11)
	v_lshlrev_b32_e32 v84, 16, v84
	v_fmamk_f32 v58, v84, 0x3fd744fd, v58
	v_cvt_pk_bf16_f32 v58, v58, s0
	s_waitcnt vmcnt(10)
	v_lshlrev_b32_e32 v85, 16, v85
	v_fmamk_f32 v42, v85, 0x3fd744fd, v42
	v_cvt_pk_bf16_f32 v42, v42, s0
	s_waitcnt vmcnt(9)
	v_lshlrev_b32_e32 v86, 16, v86
	v_fmamk_f32 v59, v86, 0x3fd744fd, v59
	v_cvt_pk_bf16_f32 v59, v59, s0
	s_waitcnt vmcnt(8)
	v_lshlrev_b32_e32 v87, 16, v87
	v_fmamk_f32 v43, v87, 0x3fd744fd, v43
	v_cvt_pk_bf16_f32 v43, v43, s0
	s_waitcnt vmcnt(7)
	v_lshlrev_b32_e32 v88, 16, v88
	v_fmamk_f32 v60, v88, 0x3fd744fd, v60
	v_cvt_pk_bf16_f32 v60, v60, s0
	s_waitcnt vmcnt(6)
	v_lshlrev_b32_e32 v89, 16, v89
	v_fmamk_f32 v44, v89, 0x3fd744fd, v44
	v_cvt_pk_bf16_f32 v44, v44, s0
	s_waitcnt vmcnt(5)
	v_lshlrev_b32_e32 v90, 16, v90
	v_fmamk_f32 v61, v90, 0x3fd744fd, v61
	v_cvt_pk_bf16_f32 v61, v61, s0
	s_waitcnt vmcnt(4)
	v_lshlrev_b32_e32 v91, 16, v91
	v_fmamk_f32 v45, v91, 0x3fd744fd, v45
	v_cvt_pk_bf16_f32 v45, v45, s0
	s_waitcnt vmcnt(3)
	v_lshlrev_b32_e32 v92, 16, v92
	v_fmamk_f32 v62, v92, 0x3fd744fd, v62
	v_cvt_pk_bf16_f32 v62, v62, s0
	s_waitcnt vmcnt(2)
	v_lshlrev_b32_e32 v93, 16, v93
	v_fmamk_f32 v46, v93, 0x3fd744fd, v46
	v_cvt_pk_bf16_f32 v46, v46, s0
	s_waitcnt vmcnt(1)
	v_lshlrev_b32_e32 v94, 16, v94
	v_fmamk_f32 v63, v94, 0x3fd744fd, v63
	v_cvt_pk_bf16_f32 v63, v63, s0
	s_waitcnt vmcnt(0)
	v_lshlrev_b32_e32 v95, 16, v95
	v_fmamk_f32 v47, v95, 0x3fd744fd, v47
	v_cvt_pk_bf16_f32 v47, v47, s0
	global_store_short v98, v48, s[96:97]
	global_store_short v98, v32, s[96:97] offset:64
	global_store_short v98, v49, s[96:97] offset:2048
	global_store_short v98, v33, s[96:97] offset:2112
	global_store_short v99, v50, s[96:97]
	global_store_short v99, v34, s[96:97] offset:64
	global_store_short v99, v51, s[96:97] offset:2048
	global_store_short v99, v35, s[96:97] offset:2112
	global_store_short v100, v52, s[96:97]
	global_store_short v100, v36, s[96:97] offset:64
	global_store_short v100, v53, s[96:97] offset:2048
	global_store_short v100, v37, s[96:97] offset:2112
	global_store_short v101, v54, s[96:97]
	global_store_short v101, v38, s[96:97] offset:64
	global_store_short v101, v55, s[96:97] offset:2048
	global_store_short v101, v39, s[96:97] offset:2112
	global_store_short v102, v56, s[96:97]
	global_store_short v102, v40, s[96:97] offset:64
	global_store_short v102, v57, s[96:97] offset:2048
	global_store_short v102, v41, s[96:97] offset:2112
	global_store_short v103, v58, s[96:97]
	global_store_short v103, v42, s[96:97] offset:64
	global_store_short v103, v59, s[96:97] offset:2048
	global_store_short v103, v43, s[96:97] offset:2112
	global_store_short v104, v60, s[96:97]
	global_store_short v104, v44, s[96:97] offset:64
	global_store_short v104, v61, s[96:97] offset:2048
	global_store_short v104, v45, s[96:97] offset:2112
	global_store_short v105, v62, s[96:97]
	global_store_short v105, v46, s[96:97] offset:64
	global_store_short v105, v63, s[96:97] offset:2048
	global_store_short v105, v47, s[96:97] offset:2112
	global_load_ushort v64, v106, s[94:95]
	global_load_ushort v65, v106, s[94:95] offset:64
	global_load_ushort v66, v106, s[94:95] offset:2048
	global_load_ushort v67, v106, s[94:95] offset:2112
	global_load_ushort v68, v107, s[94:95]
	global_load_ushort v69, v107, s[94:95] offset:64
	global_load_ushort v70, v107, s[94:95] offset:2048
	global_load_ushort v71, v107, s[94:95] offset:2112
	global_load_ushort v72, v108, s[94:95]
	global_load_ushort v73, v108, s[94:95] offset:64
	global_load_ushort v74, v108, s[94:95] offset:2048
	global_load_ushort v75, v108, s[94:95] offset:2112
	global_load_ushort v76, v109, s[94:95]
	global_load_ushort v77, v109, s[94:95] offset:64
	global_load_ushort v78, v109, s[94:95] offset:2048
	global_load_ushort v79, v109, s[94:95] offset:2112
	global_load_ushort v80, v110, s[94:95]
	global_load_ushort v81, v110, s[94:95] offset:64
	global_load_ushort v82, v110, s[94:95] offset:2048
	global_load_ushort v83, v110, s[94:95] offset:2112
	global_load_ushort v84, v111, s[94:95]
	global_load_ushort v85, v111, s[94:95] offset:64
	global_load_ushort v86, v111, s[94:95] offset:2048
	global_load_ushort v87, v111, s[94:95] offset:2112
	global_load_ushort v88, v112, s[94:95]
	global_load_ushort v89, v112, s[94:95] offset:64
	global_load_ushort v90, v112, s[94:95] offset:2048
	global_load_ushort v91, v112, s[94:95] offset:2112
	global_load_ushort v92, v113, s[94:95]
	global_load_ushort v93, v113, s[94:95] offset:64
	global_load_ushort v94, v113, s[94:95] offset:2048
	global_load_ushort v95, v113, s[94:95] offset:2112
	s_waitcnt vmcnt(31)
; #define PW(T, off) ((T*)(lndp(p.ws) + (off)))
; DEVI float bf2f(bf16 h) { return __uint_as_float(((unsigned)h) << 16); }
; DEVI int accrow(int r, int lane) { return (r & 3) + 8 * (r >> 2) + 4 * (lane >> 5); }
; template <int EPI>
; DEVI void gemm_epi(const Params& p, const GJob& jb, f32x16 (&acc)[2][2], int rbase, int cbase, int lane) {
;     ...
; #pragma unroll
;   for (int i = 0; i < 2; ++i) {
; #pragma unroll
;     for (int r = 0; r < 16; ++r) {
;       const int row = rbase + i * 32 + accrow(r, lane);
;       if (row < M) {
; #pragma unroll
;         for (int j = 0; j < 2; ++j) {
;           const int col = cbase + j * 32 + (lane & 31);
;           const float v = acc[i][j][r];
;           if (EPI == EPI_SSD_IN) {
;             if (col < 2048) ((bf16*)(ar + S_ZB))[(size_t)row * 2048 + col] = f2bf(v);
;             else if (col < 6144) ((bf16*)(ar + S_XBC))[(size_t)row * 4096 + col - 2048] = f2bf(v);
;             else if (col < 6176) ((float*)(ar + S_DTRAW))[(size_t)row * 32 + col - 6144] = v;
;           } else if (EPI == EPI_RESID) {
;             PW(bf16, W_Z)[(size_t)row * 1024 + col] = f2bf(ALPHA * bf2f(PW(bf16, W_Xb)[(size_t)row * 1024 + col]) + v);
	v_lshlrev_b32_e32 v64, 16, v64
	v_fmamk_f32 v16, v64, 0x3fd744fd, v16
	v_cvt_pk_bf16_f32 v16, v16, s0
	s_waitcnt vmcnt(30)
	v_lshlrev_b32_e32 v65, 16, v65
	v_fmamk_f32 v0, v65, 0x3fd744fd, v0
	v_cvt_pk_bf16_f32 v0, v0, s0
	s_waitcnt vmcnt(29)
	v_lshlrev_b32_e32 v66, 16, v66
	v_fmamk_f32 v17, v66, 0x3fd744fd, v17
	v_cvt_pk_bf16_f32 v17, v17, s0
	s_waitcnt vmcnt(28)
	v_lshlrev_b32_e32 v67, 16, v67
	v_fmamk_f32 v1, v67, 0x3fd744fd, v1
	v_cvt_pk_bf16_f32 v1, v1, s0
	s_waitcnt vmcnt(27)
	v_lshlrev_b32_e32 v68, 16, v68
	v_fmamk_f32 v18, v68, 0x3fd744fd, v18
	v_cvt_pk_bf16_f32 v18, v18, s0
	s_waitcnt vmcnt(26)
	v_lshlrev_b32_e32 v69, 16, v69
	v_fmamk_f32 v2, v69, 0x3fd744fd, v2
	v_cvt_pk_bf16_f32 v2, v2, s0
	s_waitcnt vmcnt(25)
	v_lshlrev_b32_e32 v70, 16, v70
	v_fmamk_f32 v19, v70, 0x3fd744fd, v19
	v_cvt_pk_bf16_f32 v19, v19, s0
	s_waitcnt vmcnt(24)
	v_lshlrev_b32_e32 v71, 16, v71
	v_fmamk_f32 v3, v71, 0x3fd744fd, v3
	v_cvt_pk_bf16_f32 v3, v3, s0
	s_waitcnt vmcnt(23)
	v_lshlrev_b32_e32 v72, 16, v72
	v_fmamk_f32 v20, v72, 0x3fd744fd, v20
	v_cvt_pk_bf16_f32 v20, v20, s0
	s_waitcnt vmcnt(22)
	v_lshlrev_b32_e32 v73, 16, v73
	v_fmamk_f32 v4, v73, 0x3fd744fd, v4
	v_cvt_pk_bf16_f32 v4, v4, s0
	s_waitcnt vmcnt(21)
	v_lshlrev_b32_e32 v74, 16, v74
	v_fmamk_f32 v21, v74, 0x3fd744fd, v21
	v_cvt_pk_bf16_f32 v21, v21, s0
	s_waitcnt vmcnt(20)
	v_lshlrev_b32_e32 v75, 16, v75
	v_fmamk_f32 v5, v75, 0x3fd744fd, v5
	v_cvt_pk_bf16_f32 v5, v5, s0
	s_waitcnt vmcnt(19)
	v_lshlrev_b32_e32 v76, 16, v76
	v_fmamk_f32 v22, v76, 0x3fd744fd, v22
	v_cvt_pk_bf16_f32 v22, v22, s0
	s_waitcnt vmcnt(18)
	v_lshlrev_b32_e32 v77, 16, v77
	v_fmamk_f32 v6, v77, 0x3fd744fd, v6
	v_cvt_pk_bf16_f32 v6, v6, s0
	s_waitcnt vmcnt(17)
	v_lshlrev_b32_e32 v78, 16, v78
	v_fmamk_f32 v23, v78, 0x3fd744fd, v23
	v_cvt_pk_bf16_f32 v23, v23, s0
	s_waitcnt vmcnt(16)
	v_lshlrev_b32_e32 v79, 16, v79
	v_fmamk_f32 v7, v79, 0x3fd744fd, v7
	v_cvt_pk_bf16_f32 v7, v7, s0
	s_waitcnt vmcnt(15)
	v_lshlrev_b32_e32 v80, 16, v80
	v_fmamk_f32 v24, v80, 0x3fd744fd, v24
	v_cvt_pk_bf16_f32 v24, v24, s0
	s_waitcnt vmcnt(14)
	v_lshlrev_b32_e32 v81, 16, v81
	v_fmamk_f32 v8, v81, 0x3fd744fd, v8
	v_cvt_pk_bf16_f32 v8, v8, s0
	s_waitcnt vmcnt(13)
	v_lshlrev_b32_e32 v82, 16, v82
	v_fmamk_f32 v25, v82, 0x3fd744fd, v25
	v_cvt_pk_bf16_f32 v25, v25, s0
	s_waitcnt vmcnt(12)
	v_lshlrev_b32_e32 v83, 16, v83
	v_fmamk_f32 v9, v83, 0x3fd744fd, v9
	v_cvt_pk_bf16_f32 v9, v9, s0
	s_waitcnt vmcnt(11)
	v_lshlrev_b32_e32 v84, 16, v84
	v_fmamk_f32 v26, v84, 0x3fd744fd, v26
	v_cvt_pk_bf16_f32 v26, v26, s0
	s_waitcnt vmcnt(10)
	v_lshlrev_b32_e32 v85, 16, v85
	v_fmamk_f32 v10, v85, 0x3fd744fd, v10
	v_cvt_pk_bf16_f32 v10, v10, s0
	s_waitcnt vmcnt(9)
	v_lshlrev_b32_e32 v86, 16, v86
	v_fmamk_f32 v27, v86, 0x3fd744fd, v27
	v_cvt_pk_bf16_f32 v27, v27, s0
	s_waitcnt vmcnt(8)
	v_lshlrev_b32_e32 v87, 16, v87
	v_fmamk_f32 v11, v87, 0x3fd744fd, v11
	v_cvt_pk_bf16_f32 v11, v11, s0
	s_waitcnt vmcnt(7)
	v_lshlrev_b32_e32 v88, 16, v88
	v_fmamk_f32 v28, v88, 0x3fd744fd, v28
	v_cvt_pk_bf16_f32 v28, v28, s0
	s_waitcnt vmcnt(6)
	v_lshlrev_b32_e32 v89, 16, v89
	v_fmamk_f32 v12, v89, 0x3fd744fd, v12
	v_cvt_pk_bf16_f32 v12, v12, s0
	s_waitcnt vmcnt(5)
	v_lshlrev_b32_e32 v90, 16, v90
	v_fmamk_f32 v29, v90, 0x3fd744fd, v29
	v_cvt_pk_bf16_f32 v29, v29, s0
	s_waitcnt vmcnt(4)
	v_lshlrev_b32_e32 v91, 16, v91
	v_fmamk_f32 v13, v91, 0x3fd744fd, v13
	v_cvt_pk_bf16_f32 v13, v13, s0
	s_waitcnt vmcnt(3)
	v_lshlrev_b32_e32 v92, 16, v92
	v_fmamk_f32 v30, v92, 0x3fd744fd, v30
	v_cvt_pk_bf16_f32 v30, v30, s0
	s_waitcnt vmcnt(2)
	v_lshlrev_b32_e32 v93, 16, v93
	v_fmamk_f32 v14, v93, 0x3fd744fd, v14
	v_cvt_pk_bf16_f32 v14, v14, s0
	s_waitcnt vmcnt(1)
	v_lshlrev_b32_e32 v94, 16, v94
	v_fmamk_f32 v31, v94, 0x3fd744fd, v31
	v_cvt_pk_bf16_f32 v31, v31, s0
	s_waitcnt vmcnt(0)
	v_lshlrev_b32_e32 v95, 16, v95
	v_fmamk_f32 v15, v95, 0x3fd744fd, v15
	v_cvt_pk_bf16_f32 v15, v15, s0
	global_store_short v106, v16, s[96:97]
	global_store_short v106, v0, s[96:97] offset:64
	global_store_short v106, v17, s[96:97] offset:2048
	global_store_short v106, v1, s[96:97] offset:2112
	global_store_short v107, v18, s[96:97]
	global_store_short v107, v2, s[96:97] offset:64
	global_store_short v107, v19, s[96:97] offset:2048
	global_store_short v107, v3, s[96:97] offset:2112
	global_store_short v108, v20, s[96:97]
	global_store_short v108, v4, s[96:97] offset:64
	global_store_short v108, v21, s[96:97] offset:2048
	global_store_short v108, v5, s[96:97] offset:2112
	global_store_short v109, v22, s[96:97]
	global_store_short v109, v6, s[96:97] offset:64
	global_store_short v109, v23, s[96:97] offset:2048
	global_store_short v109, v7, s[96:97] offset:2112
	global_store_short v110, v24, s[96:97]
	global_store_short v110, v8, s[96:97] offset:64
	global_store_short v110, v25, s[96:97] offset:2048
	global_store_short v110, v9, s[96:97] offset:2112
	global_store_short v111, v26, s[96:97]
	global_store_short v111, v10, s[96:97] offset:64
	global_store_short v111, v27, s[96:97] offset:2048
	global_store_short v111, v11, s[96:97] offset:2112
	global_store_short v112, v28, s[96:97]
	global_store_short v112, v12, s[96:97] offset:64
	global_store_short v112, v29, s[96:97] offset:2048
	global_store_short v112, v13, s[96:97] offset:2112
	global_store_short v113, v30, s[96:97]
	global_store_short v113, v14, s[96:97] offset:64
	global_store_short v113, v31, s[96:97] offset:2048
	global_store_short v113, v15, s[96:97] offset:2112
	s_mov_b64 s[2:3], exec
	s_branch .LBB0_1316

; #define PW(T, off) ((T*)(lndp(p.ws) + (off)))
; DEVI float bf2f(bf16 h) { return __uint_as_float(((unsigned)h) << 16); }
; DEVI int accrow(int r, int lane) { return (r & 3) + 8 * (r >> 2) + 4 * (lane >> 5); }
; template <int EPI>
; DEVI void gemm_epi(const Params& p, const GJob& jb, f32x16 (&acc)[2][2], int rbase, int cbase, int lane) {
;     ...
; #pragma unroll
;   for (int i = 0; i < 2; ++i) {
; #pragma unroll
;     for (int r = 0; r < 16; ++r) {
;       const int row = rbase + i * 32 + accrow(r, lane);
;       if (row < M) {
; #pragma unroll
;         for (int j = 0; j < 2; ++j) {
;           const int col = cbase + j * 32 + (lane & 31);
;           const float v = acc[i][j][r];
;           if (EPI == EPI_SSD_IN) {
;             if (col < 2048) ((bf16*)(ar + S_ZB))[(size_t)row * 2048 + col] = f2bf(v);
;             else if (col < 6144) ((bf16*)(ar + S_XBC))[(size_t)row * 4096 + col - 2048] = f2bf(v);
;             else if (col < 6176) ((float*)(ar + S_DTRAW))[(size_t)row * 32 + col - 6144] = v;
;           } else if (EPI == EPI_RESID) {
;             PW(bf16, W_Z)[(size_t)row * 1024 + col] = f2bf(ALPHA * bf2f(PW(bf16, W_Xb)[(size_t)row * 1024 + col]) + v);
.LBB0_2648:
	s_add_u32 s94, s74, 0xf724000
	s_addc_u32 s95, s75, 0
	s_add_u32 s96, s74, 0xb5a4000
	s_addc_u32 s97, s75, 0
	v_lshrrev_b32_e32 v114, 3, v133
	v_and_b32_e32 v114, 4, v114
	v_add3_u32 v114, s14, v151, v114
	v_or_b32_e32 v115, s13, v150
	v_lshlrev_b32_e32 v115, 1, v115
	v_lshl_add_u32 v116, v114, 11, v115
	v_mov_b32_e32 v98, v116
	v_add_u32_e32 v99, 0x1000, v116
	v_add_u32_e32 v100, 0x4000, v116
	v_add_u32_e32 v101, 0x5000, v116
	v_add_u32_e32 v102, 0x8000, v116
	v_add_u32_e32 v103, 0x9000, v116
	v_add_u32_e32 v104, 0xc000, v116
	v_add_u32_e32 v105, 0xd000, v116
	v_add_u32_e32 v106, 0x10000, v116
	v_add_u32_e32 v107, 0x11000, v116
	v_add_u32_e32 v108, 0x14000, v116
	v_add_u32_e32 v109, 0x15000, v116
	v_add_u32_e32 v110, 0x18000, v116
	v_add_u32_e32 v111, 0x19000, v116
	v_add_u32_e32 v112, 0x1c000, v116
	v_add_u32_e32 v113, 0x1d000, v116
	global_load_ushort v64, v98, s[94:95]
	global_load_ushort v65, v98, s[94:95] offset:64
	global_load_ushort v66, v98, s[94:95] offset:2048
	global_load_ushort v67, v98, s[94:95] offset:2112
	global_load_ushort v68, v99, s[94:95]
	global_load_ushort v69, v99, s[94:95] offset:64
	global_load_ushort v70, v99, s[94:95] offset:2048
	global_load_ushort v71, v99, s[94:95] offset:2112
	global_load_ushort v72, v100, s[94:95]
	global_load_ushort v73, v100, s[94:95] offset:64
	global_load_ushort v74, v100, s[94:95] offset:2048
	global_load_ushort v75, v100, s[94:95] offset:2112
	global_load_ushort v76, v101, s[94:95]
	global_load_ushort v77, v101, s[94:95] offset:64
	global_load_ushort v78, v101, s[94:95] offset:2048
	global_load_ushort v79, v101, s[94:95] offset:2112
	global_load_ushort v80, v102, s[94:95]
	global_load_ushort v81, v102, s[94:95] offset:64
	global_load_ushort v82, v102, s[94:95] offset:2048
	global_load_ushort v83, v102, s[94:95] offset:2112
	global_load_ushort v84, v103, s[94:95]
	global_load_ushort v85, v103, s[94:95] offset:64
	global_load_ushort v86, v103, s[94:95] offset:2048
	global_load_ushort v87, v103, s[94:95] offset:2112
	global_load_ushort v88, v104, s[94:95]
	global_load_ushort v89, v104, s[94:95] offset:64
	global_load_ushort v90, v104, s[94:95] offset:2048
	global_load_ushort v91, v104, s[94:95] offset:2112
	global_load_ushort v92, v105, s[94:95]
	global_load_ushort v93, v105, s[94:95] offset:64
	global_load_ushort v94, v105, s[94:95] offset:2048
	global_load_ushort v95, v105, s[94:95] offset:2112
	s_waitcnt vmcnt(31)
	v_lshlrev_b32_e32 v64, 16, v64
	v_fmamk_f32 v48, v64, 0x3fd744fd, v48
	v_cvt_pk_bf16_f32 v48, v48, s0
	s_waitcnt vmcnt(30)
	v_lshlrev_b32_e32 v65, 16, v65
	v_fmamk_f32 v32, v65, 0x3fd744fd, v32
	v_cvt_pk_bf16_f32 v32, v32, s0
	s_waitcnt vmcnt(29)
	v_lshlrev_b32_e32 v66, 16, v66
	v_fmamk_f32 v49, v66, 0x3fd744fd, v49
	v_cvt_pk_bf16_f32 v49, v49, s0
	s_waitcnt vmcnt(28)
	v_lshlrev_b32_e32 v67, 16, v67
	v_fmamk_f32 v33, v67, 0x3fd744fd, v33
	v_cvt_pk_bf16_f32 v33, v33, s0
	s_waitcnt vmcnt(27)
	v_lshlrev_b32_e32 v68, 16, v68
	v_fmamk_f32 v50, v68, 0x3fd744fd, v50
	v_cvt_pk_bf16_f32 v50, v50, s0
	s_waitcnt vmcnt(26)
	v_lshlrev_b32_e32 v69, 16, v69
	v_fmamk_f32 v34, v69, 0x3fd744fd, v34
	v_cvt_pk_bf16_f32 v34, v34, s0
	s_waitcnt vmcnt(25)
	v_lshlrev_b32_e32 v70, 16, v70
	v_fmamk_f32 v51, v70, 0x3fd744fd, v51
	v_cvt_pk_bf16_f32 v51, v51, s0
	s_waitcnt vmcnt(24)
	v_lshlrev_b32_e32 v71, 16, v71
	v_fmamk_f32 v35, v71, 0x3fd744fd, v35
	v_cvt_pk_bf16_f32 v35, v35, s0
	s_waitcnt vmcnt(23)
	v_lshlrev_b32_e32 v72, 16, v72
	v_fmamk_f32 v52, v72, 0x3fd744fd, v52
	v_cvt_pk_bf16_f32 v52, v52, s0
	s_waitcnt vmcnt(22)
	v_lshlrev_b32_e32 v73, 16, v73
	v_fmamk_f32 v36, v73, 0x3fd744fd, v36
	v_cvt_pk_bf16_f32 v36, v36, s0
	s_waitcnt vmcnt(21)
	v_lshlrev_b32_e32 v74, 16, v74
	v_fmamk_f32 v53, v74, 0x3fd744fd, v53
	v_cvt_pk_bf16_f32 v53, v53, s0
	s_waitcnt vmcnt(20)
	v_lshlrev_b32_e32 v75, 16, v75
	v_fmamk_f32 v37, v75, 0x3fd744fd, v37
	v_cvt_pk_bf16_f32 v37, v37, s0
	s_waitcnt vmcnt(19)
	v_lshlrev_b32_e32 v76, 16, v76
	v_fmamk_f32 v54, v76, 0x3fd744fd, v54
	v_cvt_pk_bf16_f32 v54, v54, s0
	s_waitcnt vmcnt(18)
	v_lshlrev_b32_e32 v77, 16, v77
	v_fmamk_f32 v38, v77, 0x3fd744fd, v38
	v_cvt_pk_bf16_f32 v38, v38, s0
	s_waitcnt vmcnt(17)
	v_lshlrev_b32_e32 v78, 16, v78
	v_fmamk_f32 v55, v78, 0x3fd744fd, v55
	v_cvt_pk_bf16_f32 v55, v55, s0
	s_waitcnt vmcnt(16)
	v_lshlrev_b32_e32 v79, 16, v79
	v_fmamk_f32 v39, v79, 0x3fd744fd, v39
	v_cvt_pk_bf16_f32 v39, v39, s0
	s_waitcnt vmcnt(15)
	v_lshlrev_b32_e32 v80, 16, v80
	v_fmamk_f32 v56, v80, 0x3fd744fd, v56
	v_cvt_pk_bf16_f32 v56, v56, s0
	s_waitcnt vmcnt(14)
	v_lshlrev_b32_e32 v81, 16, v81
	v_fmamk_f32 v40, v81, 0x3fd744fd, v40
	v_cvt_pk_bf16_f32 v40, v40, s0
	s_waitcnt vmcnt(13)
	v_lshlrev_b32_e32 v82, 16, v82
	v_fmamk_f32 v57, v82, 0x3fd744fd, v57
	v_cvt_pk_bf16_f32 v57, v57, s0
	s_waitcnt vmcnt(12)
	v_lshlrev_b32_e32 v83, 16, v83
	v_fmamk_f32 v41, v83, 0x3fd744fd, v41
	v_cvt_pk_bf16_f32 v41, v41, s0
	s_waitcnt vmcnt(11)
	v_lshlrev_b32_e32 v84, 16, v84
	v_fmamk_f32 v58, v84, 0x3fd744fd, v58
	v_cvt_pk_bf16_f32 v58, v58, s0
	s_waitcnt vmcnt(10)
	v_lshlrev_b32_e32 v85, 16, v85
	v_fmamk_f32 v42, v85, 0x3fd744fd, v42
	v_cvt_pk_bf16_f32 v42, v42, s0
	s_waitcnt vmcnt(9)
	v_lshlrev_b32_e32 v86, 16, v86
	v_fmamk_f32 v59, v86, 0x3fd744fd, v59
	v_cvt_pk_bf16_f32 v59, v59, s0
	s_waitcnt vmcnt(8)
	v_lshlrev_b32_e32 v87, 16, v87
	v_fmamk_f32 v43, v87, 0x3fd744fd, v43
	v_cvt_pk_bf16_f32 v43, v43, s0
	s_waitcnt vmcnt(7)
	v_lshlrev_b32_e32 v88, 16, v88
	v_fmamk_f32 v60, v88, 0x3fd744fd, v60
	v_cvt_pk_bf16_f32 v60, v60, s0
	s_waitcnt vmcnt(6)
	v_lshlrev_b32_e32 v89, 16, v89
	v_fmamk_f32 v44, v89, 0x3fd744fd, v44
	v_cvt_pk_bf16_f32 v44, v44, s0
	s_waitcnt vmcnt(5)
; #define PW(T, off) ((T*)(lndp(p.ws) + (off)))
; DEVI float bf2f(bf16 h) { return __uint_as_float(((unsigned)h) << 16); }
; DEVI int accrow(int r, int lane) { return (r & 3) + 8 * (r >> 2) + 4 * (lane >> 5); }
; template <int EPI>
; DEVI void gemm_epi(const Params& p, const GJob& jb, f32x16 (&acc)[2][2], int rbase, int cbase, int lane) {
;     ...
; #pragma unroll
;   for (int i = 0; i < 2; ++i) {
; #pragma unroll
;     for (int r = 0; r < 16; ++r) {
;       const int row = rbase + i * 32 + accrow(r, lane);
;       if (row < M) {
; #pragma unroll
;         for (int j = 0; j < 2; ++j) {
;           const int col = cbase + j * 32 + (lane & 31);
;           const float v = acc[i][j][r];
;           if (EPI == EPI_SSD_IN) {
;             if (col < 2048) ((bf16*)(ar + S_ZB))[(size_t)row * 2048 + col] = f2bf(v);
;             else if (col < 6144) ((bf16*)(ar + S_XBC))[(size_t)row * 4096 + col - 2048] = f2bf(v);
;             else if (col < 6176) ((float*)(ar + S_DTRAW))[(size_t)row * 32 + col - 6144] = v;
;           } else if (EPI == EPI_RESID) {
;             PW(bf16, W_Z)[(size_t)row * 1024 + col] = f2bf(ALPHA * bf2f(PW(bf16, W_Xb)[(size_t)row * 1024 + col]) + v);
	v_lshlrev_b32_e32 v90, 16, v90
	v_fmamk_f32 v61, v90, 0x3fd744fd, v61
	v_cvt_pk_bf16_f32 v61, v61, s0
	s_waitcnt vmcnt(4)
	v_lshlrev_b32_e32 v91, 16, v91
	v_fmamk_f32 v45, v91, 0x3fd744fd, v45
	v_cvt_pk_bf16_f32 v45, v45, s0
	s_waitcnt vmcnt(3)
	v_lshlrev_b32_e32 v92, 16, v92
	v_fmamk_f32 v62, v92, 0x3fd744fd, v62
	v_cvt_pk_bf16_f32 v62, v62, s0
	s_waitcnt vmcnt(2)
	v_lshlrev_b32_e32 v93, 16, v93
	v_fmamk_f32 v46, v93, 0x3fd744fd, v46
	v_cvt_pk_bf16_f32 v46, v46, s0
	s_waitcnt vmcnt(1)
	v_lshlrev_b32_e32 v94, 16, v94
	v_fmamk_f32 v63, v94, 0x3fd744fd, v63
	v_cvt_pk_bf16_f32 v63, v63, s0
	s_waitcnt vmcnt(0)
	v_lshlrev_b32_e32 v95, 16, v95
	v_fmamk_f32 v47, v95, 0x3fd744fd, v47
	v_cvt_pk_bf16_f32 v47, v47, s0
	global_store_short v98, v48, s[96:97]
	global_store_short v98, v32, s[96:97] offset:64
	global_store_short v98, v49, s[96:97] offset:2048
	global_store_short v98, v33, s[96:97] offset:2112
	global_store_short v99, v50, s[96:97]
	global_store_short v99, v34, s[96:97] offset:64
	global_store_short v99, v51, s[96:97] offset:2048
	global_store_short v99, v35, s[96:97] offset:2112
	global_store_short v100, v52, s[96:97]
	global_store_short v100, v36, s[96:97] offset:64
	global_store_short v100, v53, s[96:97] offset:2048
	global_store_short v100, v37, s[96:97] offset:2112
	global_store_short v101, v54, s[96:97]
	global_store_short v101, v38, s[96:97] offset:64
	global_store_short v101, v55, s[96:97] offset:2048
	global_store_short v101, v39, s[96:97] offset:2112
	global_store_short v102, v56, s[96:97]
	global_store_short v102, v40, s[96:97] offset:64
	global_store_short v102, v57, s[96:97] offset:2048
	global_store_short v102, v41, s[96:97] offset:2112
	global_store_short v103, v58, s[96:97]
	global_store_short v103, v42, s[96:97] offset:64
	global_store_short v103, v59, s[96:97] offset:2048
	global_store_short v103, v43, s[96:97] offset:2112
	global_store_short v104, v60, s[96:97]
	global_store_short v104, v44, s[96:97] offset:64
	global_store_short v104, v61, s[96:97] offset:2048
	global_store_short v104, v45, s[96:97] offset:2112
	global_store_short v105, v62, s[96:97]
	global_store_short v105, v46, s[96:97] offset:64
	global_store_short v105, v63, s[96:97] offset:2048
	global_store_short v105, v47, s[96:97] offset:2112
	global_load_ushort v64, v106, s[94:95]
	global_load_ushort v65, v106, s[94:95] offset:64
	global_load_ushort v66, v106, s[94:95] offset:2048
	global_load_ushort v67, v106, s[94:95] offset:2112
	global_load_ushort v68, v107, s[94:95]
	global_load_ushort v69, v107, s[94:95] offset:64
	global_load_ushort v70, v107, s[94:95] offset:2048
	global_load_ushort v71, v107, s[94:95] offset:2112
	global_load_ushort v72, v108, s[94:95]
	global_load_ushort v73, v108, s[94:95] offset:64
	global_load_ushort v74, v108, s[94:95] offset:2048
	global_load_ushort v75, v108, s[94:95] offset:2112
	global_load_ushort v76, v109, s[94:95]
	global_load_ushort v77, v109, s[94:95] offset:64
	global_load_ushort v78, v109, s[94:95] offset:2048
	global_load_ushort v79, v109, s[94:95] offset:2112
	global_load_ushort v80, v110, s[94:95]
	global_load_ushort v81, v110, s[94:95] offset:64
	global_load_ushort v82, v110, s[94:95] offset:2048
	global_load_ushort v83, v110, s[94:95] offset:2112
	global_load_ushort v84, v111, s[94:95]
	global_load_ushort v85, v111, s[94:95] offset:64
	global_load_ushort v86, v111, s[94:95] offset:2048
	global_load_ushort v87, v111, s[94:95] offset:2112
	global_load_ushort v88, v112, s[94:95]
	global_load_ushort v89, v112, s[94:95] offset:64
	global_load_ushort v90, v112, s[94:95] offset:2048
	global_load_ushort v91, v112, s[94:95] offset:2112
	global_load_ushort v92, v113, s[94:95]
	global_load_ushort v93, v113, s[94:95] offset:64
	global_load_ushort v94, v113, s[94:95] offset:2048
	global_load_ushort v95, v113, s[94:95] offset:2112
	s_waitcnt vmcnt(31)
	v_lshlrev_b32_e32 v64, 16, v64
	v_fmamk_f32 v16, v64, 0x3fd744fd, v16
	v_cvt_pk_bf16_f32 v16, v16, s0
	s_waitcnt vmcnt(30)
	v_lshlrev_b32_e32 v65, 16, v65
	v_fmamk_f32 v0, v65, 0x3fd744fd, v0
	v_cvt_pk_bf16_f32 v0, v0, s0
	s_waitcnt vmcnt(29)
	v_lshlrev_b32_e32 v66, 16, v66
	v_fmamk_f32 v17, v66, 0x3fd744fd, v17
	v_cvt_pk_bf16_f32 v17, v17, s0
	s_waitcnt vmcnt(28)
	v_lshlrev_b32_e32 v67, 16, v67
	v_fmamk_f32 v1, v67, 0x3fd744fd, v1
	v_cvt_pk_bf16_f32 v1, v1, s0
	s_waitcnt vmcnt(27)
	v_lshlrev_b32_e32 v68, 16, v68
	v_fmamk_f32 v18, v68, 0x3fd744fd, v18
	v_cvt_pk_bf16_f32 v18, v18, s0
	s_waitcnt vmcnt(26)
	v_lshlrev_b32_e32 v69, 16, v69
	v_fmamk_f32 v2, v69, 0x3fd744fd, v2
	v_cvt_pk_bf16_f32 v2, v2, s0
	s_waitcnt vmcnt(25)
	v_lshlrev_b32_e32 v70, 16, v70
	v_fmamk_f32 v19, v70, 0x3fd744fd, v19
	v_cvt_pk_bf16_f32 v19, v19, s0
	s_waitcnt vmcnt(24)
; #define PW(T, off) ((T*)(lndp(p.ws) + (off)))
; DEVI float bf2f(bf16 h) { return __uint_as_float(((unsigned)h) << 16); }
; DEVI int accrow(int r, int lane) { return (r & 3) + 8 * (r >> 2) + 4 * (lane >> 5); }
; template <int EPI>
; DEVI void gemm_epi(const Params& p, const GJob& jb, f32x16 (&acc)[2][2], int rbase, int cbase, int lane) {
;     ...
; #pragma unroll
;   for (int i = 0; i < 2; ++i) {
; #pragma unroll
;     for (int r = 0; r < 16; ++r) {
;       const int row = rbase + i * 32 + accrow(r, lane);
;       if (row < M) {
; #pragma unroll
;         for (int j = 0; j < 2; ++j) {
;           const int col = cbase + j * 32 + (lane & 31);
;           const float v = acc[i][j][r];
;           if (EPI == EPI_SSD_IN) {
;             if (col < 2048) ((bf16*)(ar + S_ZB))[(size_t)row * 2048 + col] = f2bf(v);
;             else if (col < 6144) ((bf16*)(ar + S_XBC))[(size_t)row * 4096 + col - 2048] = f2bf(v);
;             else if (col < 6176) ((float*)(ar + S_DTRAW))[(size_t)row * 32 + col - 6144] = v;
;           } else if (EPI == EPI_RESID) {
;             PW(bf16, W_Z)[(size_t)row * 1024 + col] = f2bf(ALPHA * bf2f(PW(bf16, W_Xb)[(size_t)row * 1024 + col]) + v);
	v_lshlrev_b32_e32 v71, 16, v71
	v_fmamk_f32 v3, v71, 0x3fd744fd, v3
	v_cvt_pk_bf16_f32 v3, v3, s0
	s_waitcnt vmcnt(23)
	v_lshlrev_b32_e32 v72, 16, v72
	v_fmamk_f32 v20, v72, 0x3fd744fd, v20
	v_cvt_pk_bf16_f32 v20, v20, s0
	s_waitcnt vmcnt(22)
	v_lshlrev_b32_e32 v73, 16, v73
	v_fmamk_f32 v4, v73, 0x3fd744fd, v4
	v_cvt_pk_bf16_f32 v4, v4, s0
	s_waitcnt vmcnt(21)
	v_lshlrev_b32_e32 v74, 16, v74
	v_fmamk_f32 v21, v74, 0x3fd744fd, v21
	v_cvt_pk_bf16_f32 v21, v21, s0
	s_waitcnt vmcnt(20)
	v_lshlrev_b32_e32 v75, 16, v75
	v_fmamk_f32 v5, v75, 0x3fd744fd, v5
	v_cvt_pk_bf16_f32 v5, v5, s0
	s_waitcnt vmcnt(19)
	v_lshlrev_b32_e32 v76, 16, v76
	v_fmamk_f32 v22, v76, 0x3fd744fd, v22
	v_cvt_pk_bf16_f32 v22, v22, s0
	s_waitcnt vmcnt(18)
	v_lshlrev_b32_e32 v77, 16, v77
	v_fmamk_f32 v6, v77, 0x3fd744fd, v6
	v_cvt_pk_bf16_f32 v6, v6, s0
	s_waitcnt vmcnt(17)
	v_lshlrev_b32_e32 v78, 16, v78
	v_fmamk_f32 v23, v78, 0x3fd744fd, v23
	v_cvt_pk_bf16_f32 v23, v23, s0
	s_waitcnt vmcnt(16)
	v_lshlrev_b32_e32 v79, 16, v79
	v_fmamk_f32 v7, v79, 0x3fd744fd, v7
	v_cvt_pk_bf16_f32 v7, v7, s0
	s_waitcnt vmcnt(15)
	v_lshlrev_b32_e32 v80, 16, v80
	v_fmamk_f32 v24, v80, 0x3fd744fd, v24
	v_cvt_pk_bf16_f32 v24, v24, s0
	s_waitcnt vmcnt(14)
	v_lshlrev_b32_e32 v81, 16, v81
	v_fmamk_f32 v8, v81, 0x3fd744fd, v8
	v_cvt_pk_bf16_f32 v8, v8, s0
	s_waitcnt vmcnt(13)
	v_lshlrev_b32_e32 v82, 16, v82
	v_fmamk_f32 v25, v82, 0x3fd744fd, v25
	v_cvt_pk_bf16_f32 v25, v25, s0
	s_waitcnt vmcnt(12)
	v_lshlrev_b32_e32 v83, 16, v83
	v_fmamk_f32 v9, v83, 0x3fd744fd, v9
	v_cvt_pk_bf16_f32 v9, v9, s0
	s_waitcnt vmcnt(11)
	v_lshlrev_b32_e32 v84, 16, v84
	v_fmamk_f32 v26, v84, 0x3fd744fd, v26
	v_cvt_pk_bf16_f32 v26, v26, s0
	s_waitcnt vmcnt(10)
	v_lshlrev_b32_e32 v85, 16, v85
	v_fmamk_f32 v10, v85, 0x3fd744fd, v10
	v_cvt_pk_bf16_f32 v10, v10, s0
	s_waitcnt vmcnt(9)
	v_lshlrev_b32_e32 v86, 16, v86
	v_fmamk_f32 v27, v86, 0x3fd744fd, v27
	v_cvt_pk_bf16_f32 v27, v27, s0
	s_waitcnt vmcnt(8)
	v_lshlrev_b32_e32 v87, 16, v87
	v_fmamk_f32 v11, v87, 0x3fd744fd, v11
	v_cvt_pk_bf16_f32 v11, v11, s0
	s_waitcnt vmcnt(7)
	v_lshlrev_b32_e32 v88, 16, v88
	v_fmamk_f32 v28, v88, 0x3fd744fd, v28
	v_cvt_pk_bf16_f32 v28, v28, s0
	s_waitcnt vmcnt(6)
	v_lshlrev_b32_e32 v89, 16, v89
	v_fmamk_f32 v12, v89, 0x3fd744fd, v12
	v_cvt_pk_bf16_f32 v12, v12, s0
	s_waitcnt vmcnt(5)
	v_lshlrev_b32_e32 v90, 16, v90
	v_fmamk_f32 v29, v90, 0x3fd744fd, v29
	v_cvt_pk_bf16_f32 v29, v29, s0
	s_waitcnt vmcnt(4)
	v_lshlrev_b32_e32 v91, 16, v91
	v_fmamk_f32 v13, v91, 0x3fd744fd, v13
	v_cvt_pk_bf16_f32 v13, v13, s0
	s_waitcnt vmcnt(3)
	v_lshlrev_b32_e32 v92, 16, v92
	v_fmamk_f32 v30, v92, 0x3fd744fd, v30
	v_cvt_pk_bf16_f32 v30, v30, s0
	s_waitcnt vmcnt(2)
	v_lshlrev_b32_e32 v93, 16, v93
	v_fmamk_f32 v14, v93, 0x3fd744fd, v14
	v_cvt_pk_bf16_f32 v14, v14, s0
	s_waitcnt vmcnt(1)
	v_lshlrev_b32_e32 v94, 16, v94
	v_fmamk_f32 v31, v94, 0x3fd744fd, v31
	v_cvt_pk_bf16_f32 v31, v31, s0
	s_waitcnt vmcnt(0)
	v_lshlrev_b32_e32 v95, 16, v95
	v_fmamk_f32 v15, v95, 0x3fd744fd, v15
	v_cvt_pk_bf16_f32 v15, v15, s0
	global_store_short v106, v16, s[96:97]
	global_store_short v106, v0, s[96:97] offset:64
	global_store_short v106, v17, s[96:97] offset:2048
	global_store_short v106, v1, s[96:97] offset:2112
	global_store_short v107, v18, s[96:97]
	global_store_short v107, v2, s[96:97] offset:64
	global_store_short v107, v19, s[96:97] offset:2048
	global_store_short v107, v3, s[96:97] offset:2112
	global_store_short v108, v20, s[96:97]
	global_store_short v108, v4, s[96:97] offset:64
	global_store_short v108, v21, s[96:97] offset:2048
	global_store_short v108, v5, s[96:97] offset:2112
	global_store_short v109, v22, s[96:97]
	global_store_short v109, v6, s[96:97] offset:64
	global_store_short v109, v23, s[96:97] offset:2048
	global_store_short v109, v7, s[96:97] offset:2112
	global_store_short v110, v24, s[96:97]
	global_store_short v110, v8, s[96:97] offset:64
	global_store_short v110, v25, s[96:97] offset:2048
	global_store_short v110, v9, s[96:97] offset:2112
	global_store_short v111, v26, s[96:97]
	global_store_short v111, v10, s[96:97] offset:64
	global_store_short v111, v27, s[96:97] offset:2048
	global_store_short v111, v11, s[96:97] offset:2112
	global_store_short v112, v28, s[96:97]
	global_store_short v112, v12, s[96:97] offset:64
	global_store_short v112, v29, s[96:97] offset:2048
	global_store_short v112, v13, s[96:97] offset:2112
	global_store_short v113, v30, s[96:97]
	global_store_short v113, v14, s[96:97] offset:64
	global_store_short v113, v31, s[96:97] offset:2048
	global_store_short v113, v15, s[96:97] offset:2112
	s_mov_b64 s[2:3], exec
	s_branch .LBB0_2639
